# stack: GEMM snake MFMA order + saddr-form DMAs + permlane-swap QKV reductions + attention prologue fixes (all bit-identical)
# speedup vs baseline: 1.0023x; 1.0023x over previous
; #define PG8_STAGE(bufoff, gbase, voff) do { _Pragma("unroll") for (int _i = 0; _i < 2; ++_i) \
;         __builtin_amdgcn_global_load_lds((const unsigned*)((const char*)(gbase) + (voff)[_i]), (PG8_LAS unsigned*)(lds + (bufoff) + ldsw + _i * 8192), 16, 0, 0); } while (0)
; #define PG8_LDA(dst, b, h) do { _Pragma("unroll") for (int m = 0; m < 4; ++m) _Pragma("unroll") for (int k = 0; k < 2; ++k) dst[m][k] = *(const PG8_LAS bf16x8*)(lds + PG8_SA(b, h) + aoff + m * 2048 + k * 1024); } while (0)
; #define PG8_LDB(dst, b, h) do { _Pragma("unroll") for (int n = 0; n < 2; ++n) _Pragma("unroll") for (int k = 0; k < 2; ++k) dst[n][k] = *(const PG8_LAS bf16x8*)(lds + PG8_SB(b, h) + boff + n * 2048 + k * 1024); } while (0)
; #define PG8_MMA(ai, bj, At, Bt) do { __builtin_amdgcn_s_setprio(1); _Pragma("unroll") for (int m = 0; m < 4; ++m) _Pragma("unroll") for (int n = 0; n < 2; ++n) _Pragma("unroll") for (int k = 0; k < 2; ++k) \
;         acc[ai][bj][m][n] = __builtin_amdgcn_mfma_f32_16x16x32_bf16(Bt[n][k], At[m][k], acc[ai][bj][m][n], 0, 0, 0); __builtin_amdgcn_s_setprio(0); } while (0)
; #define PG8_WAIT_V(n) asm volatile("s_waitcnt vmcnt(" #n ")" ::: "memory")
; #define PG8_BAR __builtin_amdgcn_s_barrier()
; template <class Epi, class Sched, bool ALIGN_EPI = false, bool SP2 = false>
; __device__ __forceinline__ void gemm_phase(PG8_LAS unsigned char* lds, const Gemm g, const Sched& S, const Epi& E) {
;     ...
;             const bool last = (t == nt - 2);
;             const char* a1 = cA + (size_t)(t + 1) * kstep;
;             const char* a2 = last ? nA : cA + (size_t)(t + 2) * kstep; const char* b2 = last ? nB : cB + (size_t)(t + 2) * kstep;
;             const char* a3 = a2 + kstep; const char* b3 = b2 + kstep;
;             if (last && has_next) S.a_ready(nxt);
;             if (last) E.prefetch(lds + 139264, cur, wid, lane);
;             if constexpr (SP2) {
;             PG8_LDB(B0, 0, 0); PG8_LDB(B1, 0, 1); PG8_SCHED; PG8_LDA(At, 0, 0); PG8_STAGE(PG8_SA(1, 1), a1 + hstep, voffA);
;             PG8_WAIT_V(8); PG8_WAIT_L(0); PG8_BAR; PG8_MMA(0, 0, At, B0); PG8_MMA(0, 1, At, B1); PG8_BAR; PG8_SCHED;
;             PG8_LDA(At, 0, 1); PG8_STAGE(PG8_SB(0, 0), b2, voffB); PG8_STAGE(PG8_SB(0, 1), b2 + hstep, voffB); PG8_STAGE(PG8_SA(0, 0), a2, voffA);
;             PG8_WAIT_V(8); PG8_WAIT_L(0); PG8_BAR; PG8_MMA(1, 0, At, B0); PG8_MMA(1, 1, At, B1); PG8_BAR; PG8_SCHED;
.LBB0_510:
	ds_read_b128 v[128:131], v184
	ds_read_b128 v[148:151], v184 offset:1024
	ds_read_b128 v[152:155], v184 offset:2048
	ds_read_b128 v[158:161], v184 offset:3072
	ds_read_b128 v[190:193], v185
	ds_read_b128 v[194:197], v185 offset:1024
	ds_read_b128 v[198:201], v185 offset:2048
	ds_read_b128 v[202:205], v185 offset:3072
	s_add_u32 s34, s10, 0xfffc0080
	s_addc_u32 s35, s11, -1
	s_cmp_eq_u32 vcc_lo, 12
	s_cselect_b32 s69, s57, s35
	s_cselect_b32 s68, s63, s34
	s_cselect_b32 s67, s55, s97
	s_cselect_b32 s66, s95, s96
	s_add_i32 m0, s65, 0xc000
	ds_read_b128 v[206:209], v186
	ds_read_b128 v[210:213], v186 offset:1024
	ds_read_b128 v[214:217], v186 offset:2048
	ds_read_b128 v[218:221], v186 offset:3072
	ds_read_b128 v[222:225], v186 offset:4096
	ds_read_b128 v[226:229], v186 offset:5120
	ds_read_b128 v[230:233], v186 offset:6144
	ds_read_b128 v[234:237], v186 offset:7168
	global_load_lds_dwordx4 v142, s[10:11]
	s_add_i32 m0, s65, 0xe000
	s_nop 0
	global_load_lds_dwordx4 v140, s[10:11]
	s_waitcnt vmcnt(8)
	s_waitcnt lgkmcnt(0)
	s_barrier
	s_setprio 1
	s_waitcnt lgkmcnt(0)
	v_mfma_f32_16x16x32_bf16 v[124:127], v[128:131], v[206:209], v[124:127]
	v_mfma_f32_16x16x32_bf16 v[120:123], v[152:155], v[206:209], v[120:123]
	v_mfma_f32_16x16x32_bf16 v[104:107], v[152:155], v[214:217], v[104:107]
	v_mfma_f32_16x16x32_bf16 v[108:111], v[128:131], v[214:217], v[108:111]
	v_mfma_f32_16x16x32_bf16 v[92:95], v[128:131], v[222:225], v[92:95]
	v_mfma_f32_16x16x32_bf16 v[88:91], v[152:155], v[222:225], v[88:91]
	v_mfma_f32_16x16x32_bf16 v[72:75], v[152:155], v[230:233], v[72:75]
	v_mfma_f32_16x16x32_bf16 v[76:79], v[128:131], v[230:233], v[76:79]
	v_mfma_f32_16x16x32_bf16 v[124:127], v[148:151], v[210:213], v[124:127]
	v_mfma_f32_16x16x32_bf16 v[120:123], v[158:161], v[210:213], v[120:123]
	v_mfma_f32_16x16x32_bf16 v[104:107], v[158:161], v[218:221], v[104:107]
	v_mfma_f32_16x16x32_bf16 v[108:111], v[148:151], v[218:221], v[108:111]
	v_mfma_f32_16x16x32_bf16 v[92:95], v[148:151], v[226:229], v[92:95]
	v_mfma_f32_16x16x32_bf16 v[88:91], v[158:161], v[226:229], v[88:91]
	v_mfma_f32_16x16x32_bf16 v[72:75], v[158:161], v[234:237], v[72:75]
	v_mfma_f32_16x16x32_bf16 v[76:79], v[148:151], v[234:237], v[76:79]
	s_setprio 0
	s_setprio 1
	v_mfma_f32_16x16x32_bf16 v[116:119], v[190:193], v[206:209], v[116:119]
	v_mfma_f32_16x16x32_bf16 v[112:115], v[198:201], v[206:209], v[112:115]
	v_mfma_f32_16x16x32_bf16 v[96:99], v[198:201], v[214:217], v[96:99]
	v_mfma_f32_16x16x32_bf16 v[100:103], v[190:193], v[214:217], v[100:103]
	v_mfma_f32_16x16x32_bf16 v[84:87], v[190:193], v[222:225], v[84:87]
	v_mfma_f32_16x16x32_bf16 v[80:83], v[198:201], v[222:225], v[80:83]
	v_mfma_f32_16x16x32_bf16 v[64:67], v[198:201], v[230:233], v[64:67]
	v_mfma_f32_16x16x32_bf16 v[68:71], v[190:193], v[230:233], v[68:71]
	v_mfma_f32_16x16x32_bf16 v[116:119], v[194:197], v[210:213], v[116:119]
	v_mfma_f32_16x16x32_bf16 v[112:115], v[202:205], v[210:213], v[112:115]
	v_mfma_f32_16x16x32_bf16 v[96:99], v[202:205], v[218:221], v[96:99]
	v_mfma_f32_16x16x32_bf16 v[100:103], v[194:197], v[218:221], v[100:103]
	v_mfma_f32_16x16x32_bf16 v[84:87], v[194:197], v[226:229], v[84:87]
	v_mfma_f32_16x16x32_bf16 v[80:83], v[202:205], v[226:229], v[80:83]
	v_mfma_f32_16x16x32_bf16 v[64:67], v[202:205], v[234:237], v[64:67]
	v_mfma_f32_16x16x32_bf16 v[68:71], v[194:197], v[234:237], v[68:71]
	s_setprio 0
	s_barrier
	s_add_i32 s34, s84, s71
	s_mov_b32 m0, s34
	ds_read_b128 v[206:209], v186 offset:16384
	ds_read_b128 v[210:213], v186 offset:17408
	ds_read_b128 v[214:217], v186 offset:18432
	ds_read_b128 v[218:221], v186 offset:19456
	ds_read_b128 v[222:225], v186 offset:20480
	ds_read_b128 v[226:229], v186 offset:21504
	ds_read_b128 v[230:233], v186 offset:22528
	ds_read_b128 v[234:237], v186 offset:23552
	global_load_lds_dwordx4 v134, s[66:67]
	s_add_i32 m0, s34, 0x2000
	s_add_u32 s34, s66, 0x40000
	s_addc_u32 s35, s67, 0
	s_add_i32 vcc_hi, s85, s71
	global_load_lds_dwordx4 v138, s[66:67]
	s_mov_b32 m0, vcc_hi
	s_nop 0
	global_load_lds_dwordx4 v134, s[34:35]
	s_add_i32 m0, vcc_hi, 0x2000
	s_nop 0
	global_load_lds_dwordx4 v138, s[34:35]
	s_mov_b32 m0, s65
	s_nop 0
	global_load_lds_dwordx4 v132, s[68:69]
	s_mov_b32 m0, s73
	s_nop 0
	global_load_lds_dwordx4 v136, s[68:69]
	s_waitcnt vmcnt(8)
	s_waitcnt lgkmcnt(0)
	s_barrier
	s_setprio 1
	s_waitcnt lgkmcnt(0)
	v_mfma_f32_16x16x32_bf16 v[60:63], v[128:131], v[206:209], v[60:63]
	v_mfma_f32_16x16x32_bf16 v[56:59], v[152:155], v[206:209], v[56:59]
	v_mfma_f32_16x16x32_bf16 v[40:43], v[152:155], v[214:217], v[40:43]
	v_mfma_f32_16x16x32_bf16 v[44:47], v[128:131], v[214:217], v[44:47]
	v_mfma_f32_16x16x32_bf16 v[28:31], v[128:131], v[222:225], v[28:31]
	v_mfma_f32_16x16x32_bf16 v[24:27], v[152:155], v[222:225], v[24:27]
	v_mfma_f32_16x16x32_bf16 v[8:11], v[152:155], v[230:233], v[8:11]
	v_mfma_f32_16x16x32_bf16 v[12:15], v[128:131], v[230:233], v[12:15]
	v_mfma_f32_16x16x32_bf16 v[60:63], v[148:151], v[210:213], v[60:63]
	v_mfma_f32_16x16x32_bf16 v[56:59], v[158:161], v[210:213], v[56:59]
	v_mfma_f32_16x16x32_bf16 v[40:43], v[158:161], v[218:221], v[40:43]
	v_mfma_f32_16x16x32_bf16 v[44:47], v[148:151], v[218:221], v[44:47]
	v_mfma_f32_16x16x32_bf16 v[28:31], v[148:151], v[226:229], v[28:31]
	v_mfma_f32_16x16x32_bf16 v[24:27], v[158:161], v[226:229], v[24:27]
	v_mfma_f32_16x16x32_bf16 v[8:11], v[158:161], v[234:237], v[8:11]
	v_mfma_f32_16x16x32_bf16 v[12:15], v[148:151], v[234:237], v[12:15]
	s_setprio 0
	s_setprio 1
	v_mfma_f32_16x16x32_bf16 v[52:55], v[190:193], v[206:209], v[52:55]
	v_mfma_f32_16x16x32_bf16 v[48:51], v[198:201], v[206:209], v[48:51]
	v_mfma_f32_16x16x32_bf16 v[32:35], v[198:201], v[214:217], v[32:35]
	v_mfma_f32_16x16x32_bf16 v[36:39], v[190:193], v[214:217], v[36:39]
	v_mfma_f32_16x16x32_bf16 v[20:23], v[190:193], v[222:225], v[20:23]
	v_mfma_f32_16x16x32_bf16 v[16:19], v[198:201], v[222:225], v[16:19]
	v_mfma_f32_16x16x32_bf16 v[0:3], v[198:201], v[230:233], v[0:3]
	v_mfma_f32_16x16x32_bf16 v[4:7], v[190:193], v[230:233], v[4:7]
	v_mfma_f32_16x16x32_bf16 v[52:55], v[194:197], v[210:213], v[52:55]
	v_mfma_f32_16x16x32_bf16 v[48:51], v[202:205], v[210:213], v[48:51]
	v_mfma_f32_16x16x32_bf16 v[32:35], v[202:205], v[218:221], v[32:35]
	v_mfma_f32_16x16x32_bf16 v[36:39], v[194:197], v[218:221], v[36:39]
	v_mfma_f32_16x16x32_bf16 v[20:23], v[194:197], v[226:229], v[20:23]
	v_mfma_f32_16x16x32_bf16 v[16:19], v[202:205], v[226:229], v[16:19]
	v_mfma_f32_16x16x32_bf16 v[0:3], v[202:205], v[234:237], v[0:3]
	v_mfma_f32_16x16x32_bf16 v[4:7], v[194:197], v[234:237], v[4:7]
	s_setprio 0
	s_barrier
; #define PG8_STAGE(bufoff, gbase, voff) do { _Pragma("unroll") for (int _i = 0; _i < 2; ++_i) \
;         __builtin_amdgcn_global_load_lds((const unsigned*)((const char*)(gbase) + (voff)[_i]), (PG8_LAS unsigned*)(lds + (bufoff) + ldsw + _i * 8192), 16, 0, 0); } while (0)
; #define PG8_LDA(dst, b, h) do { _Pragma("unroll") for (int m = 0; m < 4; ++m) _Pragma("unroll") for (int k = 0; k < 2; ++k) dst[m][k] = *(const PG8_LAS bf16x8*)(lds + PG8_SA(b, h) + aoff + m * 2048 + k * 1024); } while (0)
; #define PG8_WAIT_V(n) asm volatile("s_waitcnt vmcnt(" #n ")" ::: "memory")
; template <class Epi, class Sched, bool ALIGN_EPI = false, bool SP2 = false>
; __device__ __forceinline__ void gemm_phase(PG8_LAS unsigned char* lds, const Gemm g, const Sched& S, const Epi& E) {
;     ...
;         for (int t = 0; t < nt; t += 2) {
;             const bool last = (t == nt - 2);
;             const char* a1 = cA + (size_t)(t + 1) * kstep;
;             const char* a2 = last ? nA : cA + (size_t)(t + 2) * kstep; const char* b2 = last ? nB : cB + (size_t)(t + 2) * kstep;
;             const char* a3 = a2 + kstep; const char* b3 = b2 + kstep;
;             if (last && has_next) S.a_ready(nxt);
;             if (last) E.prefetch(lds + 139264, cur, wid, lane);
;             if constexpr (SP2) {
;             PG8_LDB(B0, 0, 0); PG8_LDB(B1, 0, 1); PG8_SCHED; PG8_LDA(At, 0, 0); PG8_STAGE(PG8_SA(1, 1), a1 + hstep, voffA);
;             PG8_WAIT_V(8); PG8_WAIT_L(0); PG8_BAR; PG8_MMA(0, 0, At, B0); PG8_MMA(0, 1, At, B1); PG8_BAR; PG8_SCHED;
;             PG8_LDA(At, 0, 1); PG8_STAGE(PG8_SB(0, 0), b2, voffB); PG8_STAGE(PG8_SB(0, 1), b2 + hstep, voffB); PG8_STAGE(PG8_SA(0, 0), a2, voffA);
;             PG8_WAIT_V(8); PG8_WAIT_L(0); PG8_BAR; PG8_MMA(1, 0, At, B0); PG8_MMA(1, 1, At, B1); PG8_BAR; PG8_SCHED;
;             PG8_LDB(B0, 1, 0); PG8_LDB(B1, 1, 1); PG8_SCHED; PG8_LDA(At, 1, 0); PG8_STAGE(PG8_SA(0, 1), a2 + hstep, voffA);
;             PG8_WAIT_V(8); PG8_WAIT_L(0); PG8_BAR; PG8_MMA(0, 0, At, B0); PG8_MMA(0, 1, At, B1); PG8_BAR; PG8_SCHED;
;             PG8_LDA(At, 1, 1); PG8_STAGE(PG8_SB(1, 0), b3, voffB); PG8_STAGE(PG8_SB(1, 1), b3 + hstep, voffB); PG8_STAGE(PG8_SA(1, 0), a3, voffA);
;             PG8_WAIT_V(8); PG8_WAIT_L(0); PG8_BAR; PG8_MMA(1, 0, At, B0); PG8_MMA(1, 1, At, B1); PG8_BAR; PG8_SCHED;
;     ...
;         if constexpr (ALIGN_EPI) { if (wr == 0) PG8_BAR; }
	s_add_i32 vcc_hi, 0, 0x18000
	s_add_i32 s14, 0, 0x1c000
	v_add_u32_e32 v158, vcc_hi, v163
	v_add_u32_e32 v202, s14, v163
	ds_read_b128 v[128:131], v158
	ds_read_b128 v[148:151], v158 offset:1024
	ds_read_b128 v[152:155], v158 offset:2048
	ds_read_b128 v[158:161], v158 offset:3072
	ds_read_b128 v[190:193], v202
	ds_read_b128 v[194:197], v202 offset:1024
	ds_read_b128 v[198:201], v202 offset:2048
	ds_read_b128 v[202:205], v202 offset:3072
	s_add_u32 s34, s68, 0x40000
	s_addc_u32 s35, s69, 0
	s_mov_b32 m0, s74
	ds_read_b128 v[206:209], v186 offset:32768
	ds_read_b128 v[210:213], v186 offset:33792
	ds_read_b128 v[214:217], v186 offset:34816
	ds_read_b128 v[218:221], v186 offset:35840
	ds_read_b128 v[222:225], v186 offset:36864
	ds_read_b128 v[226:229], v186 offset:37888
	ds_read_b128 v[230:233], v186 offset:38912
	ds_read_b128 v[234:237], v186 offset:39936
	global_load_lds_dwordx4 v132, s[34:35]
	s_mov_b32 m0, s75
	s_nop 0
	global_load_lds_dwordx4 v136, s[34:35]
	s_waitcnt vmcnt(8)
	s_waitcnt lgkmcnt(0)
	s_barrier
	s_setprio 1
	s_waitcnt lgkmcnt(0)
	v_mfma_f32_16x16x32_bf16 v[124:127], v[128:131], v[206:209], v[124:127]
	v_mfma_f32_16x16x32_bf16 v[120:123], v[152:155], v[206:209], v[120:123]
	v_mfma_f32_16x16x32_bf16 v[104:107], v[152:155], v[214:217], v[104:107]
	v_mfma_f32_16x16x32_bf16 v[108:111], v[128:131], v[214:217], v[108:111]
	v_mfma_f32_16x16x32_bf16 v[92:95], v[128:131], v[222:225], v[92:95]
	v_mfma_f32_16x16x32_bf16 v[88:91], v[152:155], v[222:225], v[88:91]
	v_mfma_f32_16x16x32_bf16 v[72:75], v[152:155], v[230:233], v[72:75]
	v_mfma_f32_16x16x32_bf16 v[76:79], v[128:131], v[230:233], v[76:79]
	v_mfma_f32_16x16x32_bf16 v[124:127], v[148:151], v[210:213], v[124:127]
	v_mfma_f32_16x16x32_bf16 v[120:123], v[158:161], v[210:213], v[120:123]
	v_mfma_f32_16x16x32_bf16 v[104:107], v[158:161], v[218:221], v[104:107]
	v_mfma_f32_16x16x32_bf16 v[108:111], v[148:151], v[218:221], v[108:111]
	v_mfma_f32_16x16x32_bf16 v[92:95], v[148:151], v[226:229], v[92:95]
	v_mfma_f32_16x16x32_bf16 v[88:91], v[158:161], v[226:229], v[88:91]
	v_mfma_f32_16x16x32_bf16 v[72:75], v[158:161], v[234:237], v[72:75]
	v_mfma_f32_16x16x32_bf16 v[76:79], v[148:151], v[234:237], v[76:79]
	s_setprio 0
	s_setprio 1
	v_mfma_f32_16x16x32_bf16 v[116:119], v[190:193], v[206:209], v[116:119]
	v_mfma_f32_16x16x32_bf16 v[112:115], v[198:201], v[206:209], v[112:115]
	v_mfma_f32_16x16x32_bf16 v[96:99], v[198:201], v[214:217], v[96:99]
	v_mfma_f32_16x16x32_bf16 v[100:103], v[190:193], v[214:217], v[100:103]
	v_mfma_f32_16x16x32_bf16 v[84:87], v[190:193], v[222:225], v[84:87]
	v_mfma_f32_16x16x32_bf16 v[80:83], v[198:201], v[222:225], v[80:83]
	v_mfma_f32_16x16x32_bf16 v[64:67], v[198:201], v[230:233], v[64:67]
	v_mfma_f32_16x16x32_bf16 v[68:71], v[190:193], v[230:233], v[68:71]
	v_mfma_f32_16x16x32_bf16 v[116:119], v[194:197], v[210:213], v[116:119]
	v_mfma_f32_16x16x32_bf16 v[112:115], v[202:205], v[210:213], v[112:115]
	v_mfma_f32_16x16x32_bf16 v[96:99], v[202:205], v[218:221], v[96:99]
	v_mfma_f32_16x16x32_bf16 v[100:103], v[194:197], v[218:221], v[100:103]
	v_mfma_f32_16x16x32_bf16 v[84:87], v[194:197], v[226:229], v[84:87]
	v_mfma_f32_16x16x32_bf16 v[80:83], v[202:205], v[226:229], v[80:83]
	v_mfma_f32_16x16x32_bf16 v[64:67], v[202:205], v[234:237], v[64:67]
	v_mfma_f32_16x16x32_bf16 v[68:71], v[194:197], v[234:237], v[68:71]
	s_setprio 0
	s_barrier
	s_add_i32 s15, vcc_hi, s71
	s_add_u32 s98, s66, s42
	s_addc_u32 s99, s67, s43
	s_add_u32 s100, s68, s42
	s_addc_u32 s101, s69, s43
	s_mov_b32 m0, s15
	ds_read_b128 v[206:209], v186 offset:49152
	ds_read_b128 v[210:213], v186 offset:50176
	ds_read_b128 v[214:217], v186 offset:51200
	ds_read_b128 v[218:221], v186 offset:52224
	ds_read_b128 v[222:225], v186 offset:53248
	ds_read_b128 v[226:229], v186 offset:54272
	ds_read_b128 v[230:233], v186 offset:55296
	ds_read_b128 v[234:237], v186 offset:56320
	global_load_lds_dwordx4 v134, s[98:99]
	s_add_i32 m0, s15, 0x2000
	s_add_u32 s34, s66, 0x40080
	s_addc_u32 s35, s67, 0
	s_add_i32 s14, s14, s71
	global_load_lds_dwordx4 v138, s[98:99]
	s_mov_b32 m0, s14
	s_nop 0
	global_load_lds_dwordx4 v134, s[34:35]
	s_add_i32 m0, s14, 0x2000
	s_nop 0
	global_load_lds_dwordx4 v138, s[34:35]
	s_mov_b32 m0, s78
	s_nop 0
	global_load_lds_dwordx4 v132, s[100:101]
	s_mov_b32 m0, s79
	s_nop 0
	global_load_lds_dwordx4 v136, s[100:101]
	s_waitcnt vmcnt(8)
	s_waitcnt lgkmcnt(0)
	s_barrier
	s_setprio 1
	s_waitcnt lgkmcnt(0)
	v_mfma_f32_16x16x32_bf16 v[60:63], v[128:131], v[206:209], v[60:63]
	v_mfma_f32_16x16x32_bf16 v[56:59], v[152:155], v[206:209], v[56:59]
	v_mfma_f32_16x16x32_bf16 v[40:43], v[152:155], v[214:217], v[40:43]
	v_mfma_f32_16x16x32_bf16 v[44:47], v[128:131], v[214:217], v[44:47]
	v_mfma_f32_16x16x32_bf16 v[28:31], v[128:131], v[222:225], v[28:31]
	v_mfma_f32_16x16x32_bf16 v[24:27], v[152:155], v[222:225], v[24:27]
	v_mfma_f32_16x16x32_bf16 v[8:11], v[152:155], v[230:233], v[8:11]
	v_mfma_f32_16x16x32_bf16 v[12:15], v[128:131], v[230:233], v[12:15]
	v_mfma_f32_16x16x32_bf16 v[60:63], v[148:151], v[210:213], v[60:63]
	v_mfma_f32_16x16x32_bf16 v[56:59], v[158:161], v[210:213], v[56:59]
	v_mfma_f32_16x16x32_bf16 v[40:43], v[158:161], v[218:221], v[40:43]
	v_mfma_f32_16x16x32_bf16 v[44:47], v[148:151], v[218:221], v[44:47]
	v_mfma_f32_16x16x32_bf16 v[28:31], v[148:151], v[226:229], v[28:31]
	v_mfma_f32_16x16x32_bf16 v[24:27], v[158:161], v[226:229], v[24:27]
	v_mfma_f32_16x16x32_bf16 v[8:11], v[158:161], v[234:237], v[8:11]
	v_mfma_f32_16x16x32_bf16 v[12:15], v[148:151], v[234:237], v[12:15]
	s_setprio 0
	s_setprio 1
	v_mfma_f32_16x16x32_bf16 v[52:55], v[190:193], v[206:209], v[52:55]
	v_mfma_f32_16x16x32_bf16 v[48:51], v[198:201], v[206:209], v[48:51]
	v_mfma_f32_16x16x32_bf16 v[32:35], v[198:201], v[214:217], v[32:35]
	v_mfma_f32_16x16x32_bf16 v[36:39], v[190:193], v[214:217], v[36:39]
	v_mfma_f32_16x16x32_bf16 v[20:23], v[190:193], v[222:225], v[20:23]
	v_mfma_f32_16x16x32_bf16 v[16:19], v[198:201], v[222:225], v[16:19]
	v_mfma_f32_16x16x32_bf16 v[0:3], v[198:201], v[230:233], v[0:3]
	v_mfma_f32_16x16x32_bf16 v[4:7], v[190:193], v[230:233], v[4:7]
	v_mfma_f32_16x16x32_bf16 v[52:55], v[194:197], v[210:213], v[52:55]
	v_mfma_f32_16x16x32_bf16 v[48:51], v[202:205], v[210:213], v[48:51]
	v_mfma_f32_16x16x32_bf16 v[32:35], v[202:205], v[218:221], v[32:35]
	v_mfma_f32_16x16x32_bf16 v[36:39], v[194:197], v[218:221], v[36:39]
	v_mfma_f32_16x16x32_bf16 v[20:23], v[194:197], v[226:229], v[20:23]
	v_mfma_f32_16x16x32_bf16 v[16:19], v[202:205], v[226:229], v[16:19]
	v_mfma_f32_16x16x32_bf16 v[0:3], v[202:205], v[234:237], v[0:3]
	v_mfma_f32_16x16x32_bf16 v[4:7], v[194:197], v[234:237], v[4:7]
	s_setprio 0
	s_barrier
	s_add_i32 vcc_lo, vcc_lo, 2
	s_add_u32 s96, s96, 0x100
	s_addc_u32 s97, s97, 0
	s_add_u32 s10, s10, 0x100
	s_addc_u32 s11, s11, 0
	s_cmp_gt_u32 vcc_lo, 13
	s_cbranch_scc0 .LBB0_510
	s_and_b64 vcc, exec, s[44:45]
	s_cbranch_vccz .LBB0_513
	s_barrier
; #define PG8_LAS __attribute__((address_space(3)))
;     __device__ __forceinline__ void operator()(f32x4 (&acc)[2][2][4][2], const Unit& u, int wr, int wc, int fr, int fq, PG8_LAS unsigned char* sp) const {
;     ...
;         const bool isv = (u.pn >= n1), isq = (u.pn < n0);
;         const int wid = wr * 4 + wc;
;         const int row0 = u.pm * BM + wr * 64 + fr; const int col0 = colt + wc * 32 + 8 * fq;
;         if (PRE) { const PG8_LAS float* spf = (const PG8_LAS float*)sp; const PG8_LAS float* bp = spf + 256 + wc * 32 + 8 * fq;
;             const f32x4 b00 = *(const PG8_LAS f32x4*)(bp), b01 = *(const PG8_LAS f32x4*)(bp + 4), b10 = *(const PG8_LAS f32x4*)(bp + HALF), b11 = *(const PG8_LAS f32x4*)(bp + HALF + 4);
; #pragma unroll
;             for (int ai = 0; ai < 2; ++ai)
; #pragma unroll
;                 for (int m = 0; m < 4; ++m) { const float rr = __builtin_amdgcn_rsqf(spf[ai * HALF + wr * 64 + m * 16 + fr] * (1.0f / 1024.0f) + EPI_EPS);
;                     acc[ai][0][m][0] = acc[ai][0][m][0] * rr + b00; acc[ai][0][m][1] = acc[ai][0][m][1] * rr + b01; acc[ai][1][m][0] = acc[ai][1][m][0] * rr + b10; acc[ai][1][m][1] = acc[ai][1][m][1] * rr + b11; } }
;         float part[16];
;         if (!isv) {
; #pragma unroll
;             for (int ai = 0; ai < 2; ++ai)
; #pragma unroll
;                 for (int m = 0; m < 4; ++m)
; #pragma unroll
;                     for (int bj = 0; bj < 2; ++bj) { const f32x4 a = acc[ai][bj][m][0], b = acc[ai][bj][m][1];
;                         float s = (a[0] * a[0] + a[1] * a[1]) + (a[2] * a[2] + a[3] * a[3]) + (b[0] * b[0] + b[1] * b[1]) + (b[2] * b[2] + b[3] * b[3]);
;                         s += __shfl_xor(s, 16); s += __shfl_xor(s, 32); const int idx = (ai * 4 + m) * 2 + bj; part[idx] = s;
;                         if (fq == 0) xch[wid * 256 + idx * 16 + fr] = s; }
.LBB0_513:
	s_cmp_lt_i32 s64, 5
	s_cselect_b64 s[10:11], -1, 0
	s_cmp_gt_i32 s64, 4
	s_cselect_b64 s[66:67], -1, 0
	v_mov_b32_e32 v190, 0
	s_and_b64 vcc, exec, s[66:67]
	v_mov_b32_e32 v191, 0
	v_mov_b32_e32 v192, 0
	v_mov_b32_e32 v193, 0
	v_mov_b32_e32 v194, 0
	v_mov_b32_e32 v195, 0
	v_mov_b32_e32 v196, 0
	v_mov_b32_e32 v197, 0
	v_mov_b32_e32 v198, 0
	v_mov_b32_e32 v199, 0
	v_mov_b32_e32 v200, 0
	v_mov_b32_e32 v201, 0
	v_mov_b32_e32 v202, 0
	v_mov_b32_e32 v203, 0
	v_mov_b32_e32 v204, 0
	v_mov_b32_e32 v205, 0
	s_cbranch_vccnz .LBB0_547
	v_pk_mul_f32 v[130:131], v[126:127], v[126:127]
	v_pk_mul_f32 v[148:149], v[124:125], v[124:125]
	v_and_b32_e32 v129, 64, v157
	v_pk_mov_b32 v[150:151], v[148:149], v[130:131] op_sel:[1,0]
	v_mov_b32_e32 v149, v131
	v_pk_add_f32 v[130:131], v[150:151], v[148:149]
	v_pk_mul_f32 v[148:149], v[122:123], v[122:123]
	v_pk_mul_f32 v[150:151], v[120:121], v[120:121]
	v_xor_b32_e32 v128, 16, v157
	v_add_u32_e32 v129, 64, v129
	v_mov_b32_e32 v152, v148
	v_mov_b32_e32 v153, v150
	v_mov_b32_e32 v150, v149
	v_cmp_lt_i32_e32 vcc, v128, v129
	v_pk_add_f32 v[148:149], v[152:153], v[150:151]
	v_add_f32_e32 v130, v130, v131
	v_cndmask_b32_e32 v128, v157, v128, vcc
	v_add_f32_e32 v130, v130, v149
	v_lshlrev_b32_e32 v128, 2, v128
	v_add_f32_e32 v130, v148, v130
	v_mov_b32_e32 v131, v130
	s_nop 1
	v_permlane16_swap_b32_e32 v130, v131
	v_xor_b32_e32 v148, 32, v157
	v_cmp_lt_i32_e32 vcc, v148, v129
	s_waitcnt lgkmcnt(0)
	v_add_f32_e32 v130, v130, v131
	v_cndmask_b32_e32 v129, v157, v148, vcc
	v_lshlrev_b32_e32 v129, 2, v129
	v_mov_b32_e32 v131, v130
	s_nop 1
	v_permlane32_swap_b32_e32 v130, v131
	v_add_f32_e32 v205, v130, v131
	s_and_saveexec_b64 s[68:69], s[4:5]
	ds_write_b32 v165, v205
	s_or_b64 exec, exec, s[68:69]
	v_pk_mul_f32 v[130:131], v[118:119], v[118:119]
	v_pk_mul_f32 v[148:149], v[116:117], v[116:117]
	s_nop 0
	v_pk_mov_b32 v[150:151], v[148:149], v[130:131] op_sel:[1,0]
	v_mov_b32_e32 v149, v131
	v_pk_add_f32 v[130:131], v[150:151], v[148:149]
	v_pk_mul_f32 v[148:149], v[114:115], v[114:115]
	v_pk_mul_f32 v[150:151], v[112:113], v[112:113]
	v_mov_b32_e32 v152, v148
	v_mov_b32_e32 v153, v150
	v_mov_b32_e32 v150, v149
	v_pk_add_f32 v[148:149], v[152:153], v[150:151]
	v_add_f32_e32 v130, v130, v131
	v_add_f32_e32 v130, v130, v149
	v_add_f32_e32 v130, v148, v130
	v_mov_b32_e32 v131, v130
	s_nop 1
	v_permlane16_swap_b32_e32 v130, v131
	v_add_f32_e32 v130, v130, v131
	v_mov_b32_e32 v131, v130
	s_nop 1
	v_permlane32_swap_b32_e32 v130, v131
	v_add_f32_e32 v204, v130, v131
	s_and_saveexec_b64 s[68:69], s[4:5]
	ds_write_b32 v165, v204 offset:64
	s_or_b64 exec, exec, s[68:69]
	v_pk_mul_f32 v[130:131], v[110:111], v[110:111]
	v_pk_mul_f32 v[148:149], v[108:109], v[108:109]
	s_nop 0
	v_pk_mov_b32 v[150:151], v[148:149], v[130:131] op_sel:[1,0]
	v_mov_b32_e32 v149, v131
	v_pk_add_f32 v[130:131], v[150:151], v[148:149]
	v_pk_mul_f32 v[148:149], v[106:107], v[106:107]
	v_pk_mul_f32 v[150:151], v[104:105], v[104:105]
	v_mov_b32_e32 v152, v148
	v_mov_b32_e32 v153, v150
	v_mov_b32_e32 v150, v149
	v_pk_add_f32 v[148:149], v[152:153], v[150:151]
	v_add_f32_e32 v130, v130, v131
	v_add_f32_e32 v130, v130, v149
	v_add_f32_e32 v130, v148, v130
	v_mov_b32_e32 v131, v130
	s_nop 1
	v_permlane16_swap_b32_e32 v130, v131
	v_add_f32_e32 v130, v130, v131
	v_mov_b32_e32 v131, v130
	s_nop 1
	v_permlane32_swap_b32_e32 v130, v131
	v_add_f32_e32 v203, v130, v131
	s_and_saveexec_b64 s[68:69], s[4:5]
	ds_write_b32 v165, v203 offset:128
	s_or_b64 exec, exec, s[68:69]
	v_pk_mul_f32 v[130:131], v[102:103], v[102:103]
	v_pk_mul_f32 v[148:149], v[100:101], v[100:101]
	s_nop 0
	v_pk_mov_b32 v[150:151], v[148:149], v[130:131] op_sel:[1,0]
	v_mov_b32_e32 v149, v131
	v_pk_add_f32 v[130:131], v[150:151], v[148:149]
	v_pk_mul_f32 v[148:149], v[98:99], v[98:99]
	v_pk_mul_f32 v[150:151], v[96:97], v[96:97]
	v_mov_b32_e32 v152, v148
	v_mov_b32_e32 v153, v150
	v_mov_b32_e32 v150, v149
	v_pk_add_f32 v[148:149], v[152:153], v[150:151]
	v_add_f32_e32 v130, v130, v131
	v_add_f32_e32 v130, v130, v149
	v_add_f32_e32 v130, v148, v130
	v_mov_b32_e32 v131, v130
	s_nop 1
	v_permlane16_swap_b32_e32 v130, v131
	v_add_f32_e32 v130, v130, v131
	v_mov_b32_e32 v131, v130
	s_nop 1
	v_permlane32_swap_b32_e32 v130, v131
	v_add_f32_e32 v202, v130, v131
	s_and_saveexec_b64 s[68:69], s[4:5]
	ds_write_b32 v165, v202 offset:192
	s_or_b64 exec, exec, s[68:69]
	v_pk_mul_f32 v[130:131], v[94:95], v[94:95]
	v_pk_mul_f32 v[148:149], v[92:93], v[92:93]
	s_nop 0
	v_pk_mov_b32 v[150:151], v[148:149], v[130:131] op_sel:[1,0]
	v_mov_b32_e32 v149, v131
	v_pk_add_f32 v[130:131], v[150:151], v[148:149]
	v_pk_mul_f32 v[148:149], v[90:91], v[90:91]
	v_pk_mul_f32 v[150:151], v[88:89], v[88:89]
	v_mov_b32_e32 v152, v148
	v_mov_b32_e32 v153, v150
	v_mov_b32_e32 v150, v149
	v_pk_add_f32 v[148:149], v[152:153], v[150:151]
	v_add_f32_e32 v130, v130, v131
	v_add_f32_e32 v130, v130, v149
	v_add_f32_e32 v130, v148, v130
	v_mov_b32_e32 v131, v130
	s_nop 1
	v_permlane16_swap_b32_e32 v130, v131
	v_add_f32_e32 v130, v130, v131
	v_mov_b32_e32 v131, v130
	s_nop 1
	v_permlane32_swap_b32_e32 v130, v131
	v_add_f32_e32 v201, v130, v131
	s_and_saveexec_b64 s[68:69], s[4:5]
	ds_write_b32 v165, v201 offset:256
	s_or_b64 exec, exec, s[68:69]
	v_pk_mul_f32 v[130:131], v[86:87], v[86:87]
	v_pk_mul_f32 v[148:149], v[84:85], v[84:85]
	s_nop 0
	v_pk_mov_b32 v[150:151], v[148:149], v[130:131] op_sel:[1,0]
	v_mov_b32_e32 v149, v131
	v_pk_add_f32 v[130:131], v[150:151], v[148:149]
	v_pk_mul_f32 v[148:149], v[82:83], v[82:83]
	v_pk_mul_f32 v[150:151], v[80:81], v[80:81]
	v_mov_b32_e32 v152, v148
	v_mov_b32_e32 v153, v150
;     __device__ __forceinline__ void operator()(f32x4 (&acc)[2][2][4][2], const Unit& u, int wr, int wc, int fr, int fq, PG8_LAS unsigned char* sp) const {
;     ...
;             for (int ai = 0; ai < 2; ++ai)
; #pragma unroll
;                 for (int m = 0; m < 4; ++m)
; #pragma unroll
;                     for (int bj = 0; bj < 2; ++bj) { const f32x4 a = acc[ai][bj][m][0], b = acc[ai][bj][m][1];
;                         float s = (a[0] * a[0] + a[1] * a[1]) + (a[2] * a[2] + a[3] * a[3]) + (b[0] * b[0] + b[1] * b[1]) + (b[2] * b[2] + b[3] * b[3]);
;                         s += __shfl_xor(s, 16); s += __shfl_xor(s, 32); const int idx = (ai * 4 + m) * 2 + bj; part[idx] = s;
;                         if (fq == 0) xch[wid * 256 + idx * 16 + fr] = s; }
	v_mov_b32_e32 v150, v149
	v_pk_add_f32 v[148:149], v[152:153], v[150:151]
	v_add_f32_e32 v130, v130, v131
	v_add_f32_e32 v130, v130, v149
	v_add_f32_e32 v130, v148, v130
	v_mov_b32_e32 v131, v130
	s_nop 1
	v_permlane16_swap_b32_e32 v130, v131
	v_add_f32_e32 v130, v130, v131
	v_mov_b32_e32 v131, v130
	s_nop 1
	v_permlane32_swap_b32_e32 v130, v131
	v_add_f32_e32 v200, v130, v131
	s_and_saveexec_b64 s[68:69], s[4:5]
	ds_write_b32 v165, v200 offset:320
	s_or_b64 exec, exec, s[68:69]
	v_pk_mul_f32 v[130:131], v[78:79], v[78:79]
	v_pk_mul_f32 v[148:149], v[76:77], v[76:77]
	s_nop 0
	v_pk_mov_b32 v[150:151], v[148:149], v[130:131] op_sel:[1,0]
	v_mov_b32_e32 v149, v131
	v_pk_add_f32 v[130:131], v[150:151], v[148:149]
	v_pk_mul_f32 v[148:149], v[74:75], v[74:75]
	v_pk_mul_f32 v[150:151], v[72:73], v[72:73]
	v_mov_b32_e32 v152, v148
	v_mov_b32_e32 v153, v150
	v_mov_b32_e32 v150, v149
	v_pk_add_f32 v[148:149], v[152:153], v[150:151]
	v_add_f32_e32 v130, v130, v131
	v_add_f32_e32 v130, v130, v149
	v_add_f32_e32 v130, v148, v130
	v_mov_b32_e32 v131, v130
	s_nop 1
	v_permlane16_swap_b32_e32 v130, v131
	v_add_f32_e32 v130, v130, v131
	v_mov_b32_e32 v131, v130
	s_nop 1
	v_permlane32_swap_b32_e32 v130, v131
	v_add_f32_e32 v199, v130, v131
	s_and_saveexec_b64 s[68:69], s[4:5]
	ds_write_b32 v165, v199 offset:384
	s_or_b64 exec, exec, s[68:69]
	v_pk_mul_f32 v[130:131], v[70:71], v[70:71]
	v_pk_mul_f32 v[148:149], v[68:69], v[68:69]
	s_nop 0
	v_pk_mov_b32 v[150:151], v[148:149], v[130:131] op_sel:[1,0]
	v_mov_b32_e32 v149, v131
	v_pk_add_f32 v[130:131], v[150:151], v[148:149]
	v_pk_mul_f32 v[148:149], v[66:67], v[66:67]
	v_pk_mul_f32 v[150:151], v[64:65], v[64:65]
	v_mov_b32_e32 v152, v148
	v_mov_b32_e32 v153, v150
	v_mov_b32_e32 v150, v149
	v_pk_add_f32 v[148:149], v[152:153], v[150:151]
	v_add_f32_e32 v130, v130, v131
	v_add_f32_e32 v130, v130, v149
	v_add_f32_e32 v130, v148, v130
	v_mov_b32_e32 v131, v130
	s_nop 1
	v_permlane16_swap_b32_e32 v130, v131
	v_add_f32_e32 v130, v130, v131
	v_mov_b32_e32 v131, v130
	s_nop 1
	v_permlane32_swap_b32_e32 v130, v131
	v_add_f32_e32 v198, v130, v131
	s_and_saveexec_b64 s[68:69], s[4:5]
	ds_write_b32 v165, v198 offset:448
	s_or_b64 exec, exec, s[68:69]
	v_pk_mul_f32 v[130:131], v[62:63], v[62:63]
	v_pk_mul_f32 v[148:149], v[60:61], v[60:61]
	s_nop 0
	v_pk_mov_b32 v[150:151], v[148:149], v[130:131] op_sel:[1,0]
	v_mov_b32_e32 v149, v131
	v_pk_add_f32 v[130:131], v[150:151], v[148:149]
	v_pk_mul_f32 v[148:149], v[58:59], v[58:59]
	v_pk_mul_f32 v[150:151], v[56:57], v[56:57]
	v_mov_b32_e32 v152, v148
	v_mov_b32_e32 v153, v150
	v_mov_b32_e32 v150, v149
	v_pk_add_f32 v[148:149], v[152:153], v[150:151]
	v_add_f32_e32 v130, v130, v131
	v_add_f32_e32 v130, v130, v149
	v_add_f32_e32 v130, v148, v130
	v_mov_b32_e32 v131, v130
	s_nop 1
	v_permlane16_swap_b32_e32 v130, v131
	v_add_f32_e32 v130, v130, v131
	v_mov_b32_e32 v131, v130
	s_nop 1
	v_permlane32_swap_b32_e32 v130, v131
	v_add_f32_e32 v197, v130, v131
	s_and_saveexec_b64 s[68:69], s[4:5]
	ds_write_b32 v165, v197 offset:512
	s_or_b64 exec, exec, s[68:69]
	v_pk_mul_f32 v[130:131], v[54:55], v[54:55]
	v_pk_mul_f32 v[148:149], v[52:53], v[52:53]
	s_nop 0
	v_pk_mov_b32 v[150:151], v[148:149], v[130:131] op_sel:[1,0]
	v_mov_b32_e32 v149, v131
	v_pk_add_f32 v[130:131], v[150:151], v[148:149]
	v_pk_mul_f32 v[148:149], v[50:51], v[50:51]
	v_pk_mul_f32 v[150:151], v[48:49], v[48:49]
	v_mov_b32_e32 v152, v148
	v_mov_b32_e32 v153, v150
	v_mov_b32_e32 v150, v149
	v_pk_add_f32 v[148:149], v[152:153], v[150:151]
	v_add_f32_e32 v130, v130, v131
	v_add_f32_e32 v130, v130, v149
	v_add_f32_e32 v130, v148, v130
	v_mov_b32_e32 v131, v130
	s_nop 1
	v_permlane16_swap_b32_e32 v130, v131
	v_add_f32_e32 v130, v130, v131
	v_mov_b32_e32 v131, v130
	s_nop 1
	v_permlane32_swap_b32_e32 v130, v131
	v_add_f32_e32 v196, v130, v131
	s_and_saveexec_b64 s[68:69], s[4:5]
	ds_write_b32 v165, v196 offset:576
	s_or_b64 exec, exec, s[68:69]
	v_pk_mul_f32 v[130:131], v[46:47], v[46:47]
	v_pk_mul_f32 v[148:149], v[44:45], v[44:45]
	s_nop 0
	v_pk_mov_b32 v[150:151], v[148:149], v[130:131] op_sel:[1,0]
	v_mov_b32_e32 v149, v131
	v_pk_add_f32 v[130:131], v[150:151], v[148:149]
	v_pk_mul_f32 v[148:149], v[42:43], v[42:43]
	v_pk_mul_f32 v[150:151], v[40:41], v[40:41]
	v_mov_b32_e32 v152, v148
	v_mov_b32_e32 v153, v150
	v_mov_b32_e32 v150, v149
	v_pk_add_f32 v[148:149], v[152:153], v[150:151]
	v_add_f32_e32 v130, v130, v131
	v_add_f32_e32 v130, v130, v149
	v_add_f32_e32 v130, v148, v130
	v_mov_b32_e32 v131, v130
	s_nop 1
	v_permlane16_swap_b32_e32 v130, v131
;     __device__ __forceinline__ void operator()(f32x4 (&acc)[2][2][4][2], const Unit& u, int wr, int wc, int fr, int fq, PG8_LAS unsigned char* sp) const {
;     ...
;             for (int ai = 0; ai < 2; ++ai)
; #pragma unroll
;                 for (int m = 0; m < 4; ++m)
; #pragma unroll
;                     for (int bj = 0; bj < 2; ++bj) { const f32x4 a = acc[ai][bj][m][0], b = acc[ai][bj][m][1];
;                         float s = (a[0] * a[0] + a[1] * a[1]) + (a[2] * a[2] + a[3] * a[3]) + (b[0] * b[0] + b[1] * b[1]) + (b[2] * b[2] + b[3] * b[3]);
;                         s += __shfl_xor(s, 16); s += __shfl_xor(s, 32); const int idx = (ai * 4 + m) * 2 + bj; part[idx] = s;
;                         if (fq == 0) xch[wid * 256 + idx * 16 + fr] = s; }
	v_add_f32_e32 v130, v130, v131
	v_mov_b32_e32 v131, v130
	s_nop 1
	v_permlane32_swap_b32_e32 v130, v131
	v_add_f32_e32 v195, v130, v131
	s_and_saveexec_b64 s[68:69], s[4:5]
	ds_write_b32 v165, v195 offset:640
	s_or_b64 exec, exec, s[68:69]
	v_pk_mul_f32 v[130:131], v[38:39], v[38:39]
	v_pk_mul_f32 v[148:149], v[36:37], v[36:37]
	s_nop 0
	v_pk_mov_b32 v[150:151], v[148:149], v[130:131] op_sel:[1,0]
	v_mov_b32_e32 v149, v131
	v_pk_add_f32 v[130:131], v[150:151], v[148:149]
	v_pk_mul_f32 v[148:149], v[34:35], v[34:35]
	v_pk_mul_f32 v[150:151], v[32:33], v[32:33]
	v_mov_b32_e32 v152, v148
	v_mov_b32_e32 v153, v150
	v_mov_b32_e32 v150, v149
	v_pk_add_f32 v[148:149], v[152:153], v[150:151]
	v_add_f32_e32 v130, v130, v131
	v_add_f32_e32 v130, v130, v149
	v_add_f32_e32 v130, v148, v130
	v_mov_b32_e32 v131, v130
	s_nop 1
	v_permlane16_swap_b32_e32 v130, v131
	v_add_f32_e32 v130, v130, v131
	v_mov_b32_e32 v131, v130
	s_nop 1
	v_permlane32_swap_b32_e32 v130, v131
	v_add_f32_e32 v194, v130, v131
	s_and_saveexec_b64 s[68:69], s[4:5]
	ds_write_b32 v165, v194 offset:704
	s_or_b64 exec, exec, s[68:69]
	v_pk_mul_f32 v[130:131], v[30:31], v[30:31]
	v_pk_mul_f32 v[148:149], v[28:29], v[28:29]
	s_nop 0
	v_pk_mov_b32 v[150:151], v[148:149], v[130:131] op_sel:[1,0]
	v_mov_b32_e32 v149, v131
	v_pk_add_f32 v[130:131], v[150:151], v[148:149]
	v_pk_mul_f32 v[148:149], v[26:27], v[26:27]
	v_pk_mul_f32 v[150:151], v[24:25], v[24:25]
	v_mov_b32_e32 v152, v148
	v_mov_b32_e32 v153, v150
	v_mov_b32_e32 v150, v149
	v_pk_add_f32 v[148:149], v[152:153], v[150:151]
	v_add_f32_e32 v130, v130, v131
	v_add_f32_e32 v130, v130, v149
	v_add_f32_e32 v130, v148, v130
	v_mov_b32_e32 v131, v130
	s_nop 1
	v_permlane16_swap_b32_e32 v130, v131
	v_add_f32_e32 v130, v130, v131
	v_mov_b32_e32 v131, v130
	s_nop 1
	v_permlane32_swap_b32_e32 v130, v131
	v_add_f32_e32 v193, v130, v131
	s_and_saveexec_b64 s[68:69], s[4:5]
	ds_write_b32 v165, v193 offset:768
	s_or_b64 exec, exec, s[68:69]
	v_pk_mul_f32 v[130:131], v[22:23], v[22:23]
	v_pk_mul_f32 v[148:149], v[20:21], v[20:21]
	s_nop 0
	v_pk_mov_b32 v[150:151], v[148:149], v[130:131] op_sel:[1,0]
	v_mov_b32_e32 v149, v131
	v_pk_add_f32 v[130:131], v[150:151], v[148:149]
	v_pk_mul_f32 v[148:149], v[18:19], v[18:19]
	v_pk_mul_f32 v[150:151], v[16:17], v[16:17]
	v_mov_b32_e32 v152, v148
	v_mov_b32_e32 v153, v150
	v_mov_b32_e32 v150, v149
	v_pk_add_f32 v[148:149], v[152:153], v[150:151]
	v_add_f32_e32 v130, v130, v131
	v_add_f32_e32 v130, v130, v149
	v_add_f32_e32 v130, v148, v130
	v_mov_b32_e32 v131, v130
	s_nop 1
	v_permlane16_swap_b32_e32 v130, v131
	v_add_f32_e32 v130, v130, v131
	v_mov_b32_e32 v131, v130
	s_nop 1
	v_permlane32_swap_b32_e32 v130, v131
	v_add_f32_e32 v192, v130, v131
	s_and_saveexec_b64 s[68:69], s[4:5]
	ds_write_b32 v165, v192 offset:832
	s_or_b64 exec, exec, s[68:69]
	v_pk_mul_f32 v[130:131], v[14:15], v[14:15]
	v_pk_mul_f32 v[148:149], v[12:13], v[12:13]
	s_nop 0
	v_pk_mov_b32 v[150:151], v[148:149], v[130:131] op_sel:[1,0]
	v_mov_b32_e32 v149, v131
	v_pk_add_f32 v[130:131], v[150:151], v[148:149]
	v_pk_mul_f32 v[148:149], v[10:11], v[10:11]
	v_pk_mul_f32 v[150:151], v[8:9], v[8:9]
	v_mov_b32_e32 v152, v148
	v_mov_b32_e32 v153, v150
	v_mov_b32_e32 v150, v149
	v_pk_add_f32 v[148:149], v[152:153], v[150:151]
	v_add_f32_e32 v130, v130, v131
	v_add_f32_e32 v130, v130, v149
	v_add_f32_e32 v130, v148, v130
	v_mov_b32_e32 v131, v130
	s_nop 1
	v_permlane16_swap_b32_e32 v130, v131
	v_add_f32_e32 v130, v130, v131
	v_mov_b32_e32 v131, v130
	s_nop 1
	v_permlane32_swap_b32_e32 v130, v131
	v_add_f32_e32 v191, v130, v131
	s_and_saveexec_b64 s[68:69], s[4:5]
	ds_write_b32 v165, v191 offset:896
	s_or_b64 exec, exec, s[68:69]
	v_pk_mul_f32 v[130:131], v[6:7], v[6:7]
	v_pk_mul_f32 v[148:149], v[4:5], v[4:5]
	s_nop 0
	v_pk_mov_b32 v[150:151], v[148:149], v[130:131] op_sel:[1,0]
	v_mov_b32_e32 v149, v131
	v_pk_add_f32 v[130:131], v[150:151], v[148:149]
	v_pk_mul_f32 v[148:149], v[2:3], v[2:3]
	v_pk_mul_f32 v[150:151], v[0:1], v[0:1]
	v_mov_b32_e32 v152, v148
	v_mov_b32_e32 v153, v150
	v_mov_b32_e32 v150, v149
	v_pk_add_f32 v[148:149], v[152:153], v[150:151]
	v_add_f32_e32 v130, v130, v131
	v_add_f32_e32 v130, v130, v149
	v_add_f32_e32 v130, v148, v130
	v_mov_b32_e32 v128, v130
	s_nop 1
	v_permlane16_swap_b32_e32 v130, v128
	v_add_f32_e32 v128, v130, v128
	v_mov_b32_e32 v129, v128
	s_nop 1
	v_permlane32_swap_b32_e32 v128, v129
	v_add_f32_e32 v190, v128, v129
	s_and_saveexec_b64 s[68:69], s[4:5]
	ds_write_b32 v165, v190 offset:960
	s_or_b64 exec, exec, s[68:69]

; #define PG8_STAGE(bufoff, gbase, voff) do { _Pragma("unroll") for (int _i = 0; _i < 2; ++_i) \
;         __builtin_amdgcn_global_load_lds((const unsigned*)((const char*)(gbase) + (voff)[_i]), (PG8_LAS unsigned*)(lds + (bufoff) + ldsw + _i * 8192), 16, 0, 0); } while (0)
; #define PG8_LDA(dst, b, h) do { _Pragma("unroll") for (int m = 0; m < 4; ++m) _Pragma("unroll") for (int k = 0; k < 2; ++k) dst[m][k] = *(const PG8_LAS bf16x8*)(lds + PG8_SA(b, h) + aoff + m * 2048 + k * 1024); } while (0)
; #define PG8_LDB(dst, b, h) do { _Pragma("unroll") for (int n = 0; n < 2; ++n) _Pragma("unroll") for (int k = 0; k < 2; ++k) dst[n][k] = *(const PG8_LAS bf16x8*)(lds + PG8_SB(b, h) + boff + n * 2048 + k * 1024); } while (0)
; #define PG8_MMA(ai, bj, At, Bt) do { __builtin_amdgcn_s_setprio(1); _Pragma("unroll") for (int m = 0; m < 4; ++m) _Pragma("unroll") for (int n = 0; n < 2; ++n) _Pragma("unroll") for (int k = 0; k < 2; ++k) \
;         acc[ai][bj][m][n] = __builtin_amdgcn_mfma_f32_16x16x32_bf16(Bt[n][k], At[m][k], acc[ai][bj][m][n], 0, 0, 0); __builtin_amdgcn_s_setprio(0); } while (0)
; #define PG8_WAIT_V(n) asm volatile("s_waitcnt vmcnt(" #n ")" ::: "memory")
; #define PG8_BAR __builtin_amdgcn_s_barrier()
; template <class Epi, class Sched, bool ALIGN_EPI = false, bool SP2 = false>
; __device__ __forceinline__ void gemm_phase(PG8_LAS unsigned char* lds, const Gemm g, const Sched& S, const Epi& E) {
;     ...
;             const bool last = (t == nt - 2);
;             const char* a1 = cA + (size_t)(t + 1) * kstep;
;             const char* a2 = last ? nA : cA + (size_t)(t + 2) * kstep; const char* b2 = last ? nB : cB + (size_t)(t + 2) * kstep;
;             const char* a3 = a2 + kstep; const char* b3 = b2 + kstep;
;             if (last && has_next) S.a_ready(nxt);
;             if (last) E.prefetch(lds + 139264, cur, wid, lane);
;             if constexpr (SP2) {
;             PG8_LDB(B0, 0, 0); PG8_LDB(B1, 0, 1); PG8_SCHED; PG8_LDA(At, 0, 0); PG8_STAGE(PG8_SA(1, 1), a1 + hstep, voffA);
;             PG8_WAIT_V(8); PG8_WAIT_L(0); PG8_BAR; PG8_MMA(0, 0, At, B0); PG8_MMA(0, 1, At, B1); PG8_BAR; PG8_SCHED;
;             PG8_LDA(At, 0, 1); PG8_STAGE(PG8_SB(0, 0), b2, voffB); PG8_STAGE(PG8_SB(0, 1), b2 + hstep, voffB); PG8_STAGE(PG8_SA(0, 0), a2, voffA);
;             PG8_WAIT_V(8); PG8_WAIT_L(0); PG8_BAR; PG8_MMA(1, 0, At, B0); PG8_MMA(1, 1, At, B1); PG8_BAR; PG8_SCHED;
.LBB0_710:
	ds_read_b128 v[128:131], v169
	ds_read_b128 v[132:135], v169 offset:1024
	ds_read_b128 v[136:139], v169 offset:2048
	ds_read_b128 v[140:143], v169 offset:3072
	ds_read_b128 v[162:165], v170
	ds_read_b128 v[172:175], v170 offset:1024
	ds_read_b128 v[176:179], v170 offset:2048
	ds_read_b128 v[184:187], v170 offset:3072
	s_add_u32 s14, s54, 0xfffc0080
	s_addc_u32 s15, s55, -1
	s_cmp_eq_u32 s84, 12
	s_cselect_b32 s59, s45, s15
	s_cselect_b32 s58, s51, s14
	s_cselect_b32 s57, s43, s83
	s_cselect_b32 s56, s53, s82
	s_add_i32 m0, s64, 0xc000
	ds_read_b128 v[188:191], v171
	ds_read_b128 v[192:195], v171 offset:1024
	ds_read_b128 v[196:199], v171 offset:2048
	ds_read_b128 v[200:203], v171 offset:3072
	ds_read_b128 v[204:207], v171 offset:4096
	ds_read_b128 v[208:211], v171 offset:5120
	ds_read_b128 v[212:215], v171 offset:6144
	ds_read_b128 v[216:219], v171 offset:7168
	global_load_lds_dwordx4 v154, s[54:55]
	s_add_i32 m0, s64, 0xe000
	s_nop 0
	global_load_lds_dwordx4 v152, s[54:55]
	s_waitcnt vmcnt(8)
	s_waitcnt lgkmcnt(0)
	s_barrier
	s_setprio 1
	s_waitcnt lgkmcnt(0)
	v_mfma_f32_16x16x32_bf16 v[124:127], v[128:131], v[188:191], v[124:127]
	v_mfma_f32_16x16x32_bf16 v[120:123], v[136:139], v[188:191], v[120:123]
	v_mfma_f32_16x16x32_bf16 v[108:111], v[136:139], v[196:199], v[108:111]
	v_mfma_f32_16x16x32_bf16 v[116:119], v[128:131], v[196:199], v[116:119]
	v_mfma_f32_16x16x32_bf16 v[100:103], v[128:131], v[204:207], v[100:103]
	v_mfma_f32_16x16x32_bf16 v[92:95], v[136:139], v[204:207], v[92:95]
	v_mfma_f32_16x16x32_bf16 v[76:79], v[136:139], v[212:215], v[76:79]
	v_mfma_f32_16x16x32_bf16 v[84:87], v[128:131], v[212:215], v[84:87]
	v_mfma_f32_16x16x32_bf16 v[124:127], v[132:135], v[192:195], v[124:127]
	v_mfma_f32_16x16x32_bf16 v[120:123], v[140:143], v[192:195], v[120:123]
	v_mfma_f32_16x16x32_bf16 v[108:111], v[140:143], v[200:203], v[108:111]
	v_mfma_f32_16x16x32_bf16 v[116:119], v[132:135], v[200:203], v[116:119]
	v_mfma_f32_16x16x32_bf16 v[100:103], v[132:135], v[208:211], v[100:103]
	v_mfma_f32_16x16x32_bf16 v[92:95], v[140:143], v[208:211], v[92:95]
	v_mfma_f32_16x16x32_bf16 v[76:79], v[140:143], v[216:219], v[76:79]
	v_mfma_f32_16x16x32_bf16 v[84:87], v[132:135], v[216:219], v[84:87]
	s_setprio 0
	s_setprio 1
	v_mfma_f32_16x16x32_bf16 v[112:115], v[162:165], v[188:191], v[112:115]
	v_mfma_f32_16x16x32_bf16 v[104:107], v[176:179], v[188:191], v[104:107]
	v_mfma_f32_16x16x32_bf16 v[88:91], v[176:179], v[196:199], v[88:91]
	v_mfma_f32_16x16x32_bf16 v[96:99], v[162:165], v[196:199], v[96:99]
	v_mfma_f32_16x16x32_bf16 v[80:83], v[162:165], v[204:207], v[80:83]
	v_mfma_f32_16x16x32_bf16 v[72:75], v[176:179], v[204:207], v[72:75]
	v_mfma_f32_16x16x32_bf16 v[64:67], v[176:179], v[212:215], v[64:67]
	v_mfma_f32_16x16x32_bf16 v[68:71], v[162:165], v[212:215], v[68:71]
	v_mfma_f32_16x16x32_bf16 v[112:115], v[172:175], v[192:195], v[112:115]
	v_mfma_f32_16x16x32_bf16 v[104:107], v[184:187], v[192:195], v[104:107]
	v_mfma_f32_16x16x32_bf16 v[88:91], v[184:187], v[200:203], v[88:91]
	v_mfma_f32_16x16x32_bf16 v[96:99], v[172:175], v[200:203], v[96:99]
	v_mfma_f32_16x16x32_bf16 v[80:83], v[172:175], v[208:211], v[80:83]
	v_mfma_f32_16x16x32_bf16 v[72:75], v[184:187], v[208:211], v[72:75]
	v_mfma_f32_16x16x32_bf16 v[64:67], v[184:187], v[216:219], v[64:67]
	v_mfma_f32_16x16x32_bf16 v[68:71], v[172:175], v[216:219], v[68:71]
	s_setprio 0
	s_barrier
	s_add_i32 s14, s80, s63
	s_mov_b32 m0, s14
	ds_read_b128 v[188:191], v171 offset:16384
	ds_read_b128 v[192:195], v171 offset:17408
	ds_read_b128 v[196:199], v171 offset:18432
	ds_read_b128 v[200:203], v171 offset:19456
	ds_read_b128 v[204:207], v171 offset:20480
	ds_read_b128 v[208:211], v171 offset:21504
	ds_read_b128 v[212:215], v171 offset:22528
	ds_read_b128 v[216:219], v171 offset:23552
	global_load_lds_dwordx4 v146, s[56:57]
	s_add_i32 m0, s14, 0x2000
	s_add_u32 s34, s56, 0x40000
	s_addc_u32 s35, s57, 0
	s_add_i32 s14, s81, s63
	global_load_lds_dwordx4 v150, s[56:57]
	s_mov_b32 m0, s14
	s_nop 0
	global_load_lds_dwordx4 v146, s[34:35]
	s_add_i32 m0, s14, 0x2000
	s_nop 0
	global_load_lds_dwordx4 v150, s[34:35]
	s_mov_b32 m0, s64
	s_nop 0
	global_load_lds_dwordx4 v144, s[58:59]
	s_mov_b32 m0, s65
	s_nop 0
	global_load_lds_dwordx4 v148, s[58:59]
	s_waitcnt vmcnt(8)
	s_waitcnt lgkmcnt(0)
	s_barrier
	s_setprio 1
	s_waitcnt lgkmcnt(0)
	v_mfma_f32_16x16x32_bf16 v[60:63], v[128:131], v[188:191], v[60:63]
	v_mfma_f32_16x16x32_bf16 v[56:59], v[136:139], v[188:191], v[56:59]
	v_mfma_f32_16x16x32_bf16 v[44:47], v[136:139], v[196:199], v[44:47]
	v_mfma_f32_16x16x32_bf16 v[48:51], v[128:131], v[196:199], v[48:51]
	v_mfma_f32_16x16x32_bf16 v[36:39], v[128:131], v[204:207], v[36:39]
	v_mfma_f32_16x16x32_bf16 v[28:31], v[136:139], v[204:207], v[28:31]
	v_mfma_f32_16x16x32_bf16 v[12:15], v[136:139], v[212:215], v[12:15]
	v_mfma_f32_16x16x32_bf16 v[20:23], v[128:131], v[212:215], v[20:23]
	v_mfma_f32_16x16x32_bf16 v[60:63], v[132:135], v[192:195], v[60:63]
	v_mfma_f32_16x16x32_bf16 v[56:59], v[140:143], v[192:195], v[56:59]
	v_mfma_f32_16x16x32_bf16 v[44:47], v[140:143], v[200:203], v[44:47]
	v_mfma_f32_16x16x32_bf16 v[48:51], v[132:135], v[200:203], v[48:51]
	v_mfma_f32_16x16x32_bf16 v[36:39], v[132:135], v[208:211], v[36:39]
	v_mfma_f32_16x16x32_bf16 v[28:31], v[140:143], v[208:211], v[28:31]
	v_mfma_f32_16x16x32_bf16 v[12:15], v[140:143], v[216:219], v[12:15]
	v_mfma_f32_16x16x32_bf16 v[20:23], v[132:135], v[216:219], v[20:23]
	s_setprio 0
	s_setprio 1
	v_mfma_f32_16x16x32_bf16 v[52:55], v[162:165], v[188:191], v[52:55]
	v_mfma_f32_16x16x32_bf16 v[40:43], v[176:179], v[188:191], v[40:43]
	v_mfma_f32_16x16x32_bf16 v[24:27], v[176:179], v[196:199], v[24:27]
	v_mfma_f32_16x16x32_bf16 v[32:35], v[162:165], v[196:199], v[32:35]
	v_mfma_f32_16x16x32_bf16 v[16:19], v[162:165], v[204:207], v[16:19]
	v_mfma_f32_16x16x32_bf16 v[8:11], v[176:179], v[204:207], v[8:11]
	v_mfma_f32_16x16x32_bf16 v[0:3], v[176:179], v[212:215], v[0:3]
	v_mfma_f32_16x16x32_bf16 v[4:7], v[162:165], v[212:215], v[4:7]
	v_mfma_f32_16x16x32_bf16 v[52:55], v[172:175], v[192:195], v[52:55]
	v_mfma_f32_16x16x32_bf16 v[40:43], v[184:187], v[192:195], v[40:43]
	v_mfma_f32_16x16x32_bf16 v[24:27], v[184:187], v[200:203], v[24:27]
	v_mfma_f32_16x16x32_bf16 v[32:35], v[172:175], v[200:203], v[32:35]
	v_mfma_f32_16x16x32_bf16 v[16:19], v[172:175], v[208:211], v[16:19]
	v_mfma_f32_16x16x32_bf16 v[8:11], v[184:187], v[208:211], v[8:11]
	v_mfma_f32_16x16x32_bf16 v[0:3], v[184:187], v[216:219], v[0:3]
	v_mfma_f32_16x16x32_bf16 v[4:7], v[172:175], v[216:219], v[4:7]
	s_setprio 0
	s_barrier
; #define PG8_STAGE(bufoff, gbase, voff) do { _Pragma("unroll") for (int _i = 0; _i < 2; ++_i) \
;         __builtin_amdgcn_global_load_lds((const unsigned*)((const char*)(gbase) + (voff)[_i]), (PG8_LAS unsigned*)(lds + (bufoff) + ldsw + _i * 8192), 16, 0, 0); } while (0)
; #define PG8_LDA(dst, b, h) do { _Pragma("unroll") for (int m = 0; m < 4; ++m) _Pragma("unroll") for (int k = 0; k < 2; ++k) dst[m][k] = *(const PG8_LAS bf16x8*)(lds + PG8_SA(b, h) + aoff + m * 2048 + k * 1024); } while (0)
; #define PG8_LDB(dst, b, h) do { _Pragma("unroll") for (int n = 0; n < 2; ++n) _Pragma("unroll") for (int k = 0; k < 2; ++k) dst[n][k] = *(const PG8_LAS bf16x8*)(lds + PG8_SB(b, h) + boff + n * 2048 + k * 1024); } while (0)
; #define PG8_MMA(ai, bj, At, Bt) do { __builtin_amdgcn_s_setprio(1); _Pragma("unroll") for (int m = 0; m < 4; ++m) _Pragma("unroll") for (int n = 0; n < 2; ++n) _Pragma("unroll") for (int k = 0; k < 2; ++k) \
;         acc[ai][bj][m][n] = __builtin_amdgcn_mfma_f32_16x16x32_bf16(Bt[n][k], At[m][k], acc[ai][bj][m][n], 0, 0, 0); __builtin_amdgcn_s_setprio(0); } while (0)
; #define PG8_WAIT_V(n) asm volatile("s_waitcnt vmcnt(" #n ")" ::: "memory")
; #define PG8_WAIT_L(n) asm volatile("s_waitcnt lgkmcnt(" #n ")" ::: "memory")
; #define PG8_BAR __builtin_amdgcn_s_barrier()
; #define PG8_SCHED __builtin_amdgcn_sched_barrier(0)
; template <class Epi, class Sched, bool ALIGN_EPI = false, bool SP2 = false>
; __device__ __forceinline__ void gemm_phase(PG8_LAS unsigned char* lds, const Gemm g, const Sched& S, const Epi& E) {
;     ...
;             PG8_LDB(B0, 1, 0); PG8_LDB(B1, 1, 1); PG8_SCHED; PG8_LDA(At, 1, 0); PG8_STAGE(PG8_SA(0, 1), a2 + hstep, voffA);
;             PG8_WAIT_V(8); PG8_WAIT_L(0); PG8_BAR; PG8_MMA(0, 0, At, B0); PG8_MMA(0, 1, At, B1); PG8_BAR; PG8_SCHED;
;             PG8_LDA(At, 1, 1); PG8_STAGE(PG8_SB(1, 0), b3, voffB); PG8_STAGE(PG8_SB(1, 1), b3 + hstep, voffB); PG8_STAGE(PG8_SA(1, 0), a3, voffA);
;             PG8_WAIT_V(8); PG8_WAIT_L(0); PG8_BAR; PG8_MMA(1, 0, At, B0); PG8_MMA(1, 1, At, B1); PG8_BAR; PG8_SCHED;
;     ...
;         if constexpr (ALIGN_EPI) { if (wr == 0) PG8_BAR; }
	s_add_i32 s14, 0, 0x18000
	s_add_i32 s15, 0, 0x1c000
	v_add_u32_e32 v140, s14, v167
	v_add_u32_e32 v183, s15, v167
	ds_read_b128 v[128:131], v140
	ds_read_b128 v[132:135], v140 offset:1024
	ds_read_b128 v[136:139], v140 offset:2048
	ds_read_b128 v[140:143], v140 offset:3072
	ds_read_b128 v[162:165], v183
	ds_read_b128 v[172:175], v183 offset:1024
	ds_read_b128 v[176:179], v183 offset:2048
	ds_read_b128 v[184:187], v183 offset:3072
	s_add_u32 s34, s58, 0x40000
	s_addc_u32 s35, s59, 0
	s_mov_b32 m0, s66
	ds_read_b128 v[188:191], v171 offset:32768
	ds_read_b128 v[192:195], v171 offset:33792
	ds_read_b128 v[196:199], v171 offset:34816
	ds_read_b128 v[200:203], v171 offset:35840
	ds_read_b128 v[204:207], v171 offset:36864
	ds_read_b128 v[208:211], v171 offset:37888
	ds_read_b128 v[212:215], v171 offset:38912
	ds_read_b128 v[216:219], v171 offset:39936
	global_load_lds_dwordx4 v144, s[34:35]
	s_mov_b32 m0, s67
	s_nop 0
	global_load_lds_dwordx4 v148, s[34:35]
	s_waitcnt vmcnt(8)
	s_waitcnt lgkmcnt(0)
	s_barrier
	s_setprio 1
	s_waitcnt lgkmcnt(0)
	v_mfma_f32_16x16x32_bf16 v[124:127], v[128:131], v[188:191], v[124:127]
	v_mfma_f32_16x16x32_bf16 v[120:123], v[136:139], v[188:191], v[120:123]
	v_mfma_f32_16x16x32_bf16 v[108:111], v[136:139], v[196:199], v[108:111]
	v_mfma_f32_16x16x32_bf16 v[116:119], v[128:131], v[196:199], v[116:119]
	v_mfma_f32_16x16x32_bf16 v[100:103], v[128:131], v[204:207], v[100:103]
	v_mfma_f32_16x16x32_bf16 v[92:95], v[136:139], v[204:207], v[92:95]
	v_mfma_f32_16x16x32_bf16 v[76:79], v[136:139], v[212:215], v[76:79]
	v_mfma_f32_16x16x32_bf16 v[84:87], v[128:131], v[212:215], v[84:87]
	v_mfma_f32_16x16x32_bf16 v[124:127], v[132:135], v[192:195], v[124:127]
	v_mfma_f32_16x16x32_bf16 v[120:123], v[140:143], v[192:195], v[120:123]
	v_mfma_f32_16x16x32_bf16 v[108:111], v[140:143], v[200:203], v[108:111]
	v_mfma_f32_16x16x32_bf16 v[116:119], v[132:135], v[200:203], v[116:119]
	v_mfma_f32_16x16x32_bf16 v[100:103], v[132:135], v[208:211], v[100:103]
	v_mfma_f32_16x16x32_bf16 v[92:95], v[140:143], v[208:211], v[92:95]
	v_mfma_f32_16x16x32_bf16 v[76:79], v[140:143], v[216:219], v[76:79]
	v_mfma_f32_16x16x32_bf16 v[84:87], v[132:135], v[216:219], v[84:87]
	s_setprio 0
	s_setprio 1
	v_mfma_f32_16x16x32_bf16 v[112:115], v[162:165], v[188:191], v[112:115]
	v_mfma_f32_16x16x32_bf16 v[104:107], v[176:179], v[188:191], v[104:107]
	v_mfma_f32_16x16x32_bf16 v[88:91], v[176:179], v[196:199], v[88:91]
	v_mfma_f32_16x16x32_bf16 v[96:99], v[162:165], v[196:199], v[96:99]
	v_mfma_f32_16x16x32_bf16 v[80:83], v[162:165], v[204:207], v[80:83]
	v_mfma_f32_16x16x32_bf16 v[72:75], v[176:179], v[204:207], v[72:75]
	v_mfma_f32_16x16x32_bf16 v[64:67], v[176:179], v[212:215], v[64:67]
	v_mfma_f32_16x16x32_bf16 v[68:71], v[162:165], v[212:215], v[68:71]
	v_mfma_f32_16x16x32_bf16 v[112:115], v[172:175], v[192:195], v[112:115]
	v_mfma_f32_16x16x32_bf16 v[104:107], v[184:187], v[192:195], v[104:107]
	v_mfma_f32_16x16x32_bf16 v[88:91], v[184:187], v[200:203], v[88:91]
	v_mfma_f32_16x16x32_bf16 v[96:99], v[172:175], v[200:203], v[96:99]
	v_mfma_f32_16x16x32_bf16 v[80:83], v[172:175], v[208:211], v[80:83]
	v_mfma_f32_16x16x32_bf16 v[72:75], v[184:187], v[208:211], v[72:75]
	v_mfma_f32_16x16x32_bf16 v[64:67], v[184:187], v[216:219], v[64:67]
	v_mfma_f32_16x16x32_bf16 v[68:71], v[172:175], v[216:219], v[68:71]
	s_setprio 0
	s_barrier
	s_add_i32 s14, s14, s63
	s_add_u32 s98, s56, s36
	s_addc_u32 s99, s57, s37
	s_add_u32 s100, s58, s36
	s_addc_u32 s101, s59, s37
	s_mov_b32 m0, s14
	ds_read_b128 v[188:191], v171 offset:49152
	ds_read_b128 v[192:195], v171 offset:50176
	ds_read_b128 v[196:199], v171 offset:51200
	ds_read_b128 v[200:203], v171 offset:52224
	ds_read_b128 v[204:207], v171 offset:53248
	ds_read_b128 v[208:211], v171 offset:54272
	ds_read_b128 v[212:215], v171 offset:55296
	ds_read_b128 v[216:219], v171 offset:56320
	global_load_lds_dwordx4 v146, s[98:99]
	s_add_i32 m0, s14, 0x2000
	s_add_u32 s34, s56, 0x40080
	s_addc_u32 s35, s57, 0
	s_add_i32 s14, s15, s63
	global_load_lds_dwordx4 v150, s[98:99]
	s_mov_b32 m0, s14
	s_nop 0
	global_load_lds_dwordx4 v146, s[34:35]
	s_add_i32 m0, s14, 0x2000
	s_nop 0
	global_load_lds_dwordx4 v150, s[34:35]
	s_mov_b32 m0, s74
	s_nop 0
	global_load_lds_dwordx4 v144, s[100:101]
	s_mov_b32 m0, s75
	s_nop 0
	global_load_lds_dwordx4 v148, s[100:101]
	s_waitcnt vmcnt(8)
	s_waitcnt lgkmcnt(0)
	s_barrier
	s_setprio 1
	s_waitcnt lgkmcnt(0)
	v_mfma_f32_16x16x32_bf16 v[60:63], v[128:131], v[188:191], v[60:63]
	v_mfma_f32_16x16x32_bf16 v[56:59], v[136:139], v[188:191], v[56:59]
	v_mfma_f32_16x16x32_bf16 v[44:47], v[136:139], v[196:199], v[44:47]
	v_mfma_f32_16x16x32_bf16 v[48:51], v[128:131], v[196:199], v[48:51]
	v_mfma_f32_16x16x32_bf16 v[36:39], v[128:131], v[204:207], v[36:39]
	v_mfma_f32_16x16x32_bf16 v[28:31], v[136:139], v[204:207], v[28:31]
	v_mfma_f32_16x16x32_bf16 v[12:15], v[136:139], v[212:215], v[12:15]
	v_mfma_f32_16x16x32_bf16 v[20:23], v[128:131], v[212:215], v[20:23]
	v_mfma_f32_16x16x32_bf16 v[60:63], v[132:135], v[192:195], v[60:63]
	v_mfma_f32_16x16x32_bf16 v[56:59], v[140:143], v[192:195], v[56:59]
	v_mfma_f32_16x16x32_bf16 v[44:47], v[140:143], v[200:203], v[44:47]
	v_mfma_f32_16x16x32_bf16 v[48:51], v[132:135], v[200:203], v[48:51]
	v_mfma_f32_16x16x32_bf16 v[36:39], v[132:135], v[208:211], v[36:39]
	v_mfma_f32_16x16x32_bf16 v[28:31], v[140:143], v[208:211], v[28:31]
	v_mfma_f32_16x16x32_bf16 v[12:15], v[140:143], v[216:219], v[12:15]
	v_mfma_f32_16x16x32_bf16 v[20:23], v[132:135], v[216:219], v[20:23]
	s_setprio 0
	s_setprio 1
	v_mfma_f32_16x16x32_bf16 v[52:55], v[162:165], v[188:191], v[52:55]
	v_mfma_f32_16x16x32_bf16 v[40:43], v[176:179], v[188:191], v[40:43]
	v_mfma_f32_16x16x32_bf16 v[24:27], v[176:179], v[196:199], v[24:27]
	v_mfma_f32_16x16x32_bf16 v[32:35], v[162:165], v[196:199], v[32:35]
	v_mfma_f32_16x16x32_bf16 v[16:19], v[162:165], v[204:207], v[16:19]
	v_mfma_f32_16x16x32_bf16 v[8:11], v[176:179], v[204:207], v[8:11]
	v_mfma_f32_16x16x32_bf16 v[0:3], v[176:179], v[212:215], v[0:3]
	v_mfma_f32_16x16x32_bf16 v[4:7], v[162:165], v[212:215], v[4:7]
	v_mfma_f32_16x16x32_bf16 v[52:55], v[172:175], v[192:195], v[52:55]
	v_mfma_f32_16x16x32_bf16 v[40:43], v[184:187], v[192:195], v[40:43]
	v_mfma_f32_16x16x32_bf16 v[24:27], v[184:187], v[200:203], v[24:27]
	v_mfma_f32_16x16x32_bf16 v[32:35], v[172:175], v[200:203], v[32:35]
	v_mfma_f32_16x16x32_bf16 v[16:19], v[172:175], v[208:211], v[16:19]
	v_mfma_f32_16x16x32_bf16 v[8:11], v[184:187], v[208:211], v[8:11]
	v_mfma_f32_16x16x32_bf16 v[0:3], v[184:187], v[216:219], v[0:3]
	v_mfma_f32_16x16x32_bf16 v[4:7], v[172:175], v[216:219], v[4:7]
	s_setprio 0
	s_barrier
	s_add_i32 s84, s84, 2
	s_add_u32 s82, s82, 0x100
	s_addc_u32 s83, s83, 0
	s_add_u32 s54, s54, 0x100
	s_addc_u32 s55, s55, 0
	s_cmp_gt_u32 s84, 13
	s_cbranch_scc0 .LBB0_710
	s_and_b64 vcc, exec, s[40:41]
	s_cbranch_vccz .LBB0_713
	s_barrier

; #define PG8_STAGE(bufoff, gbase, voff) do { _Pragma("unroll") for (int _i = 0; _i < 2; ++_i) \
;         __builtin_amdgcn_global_load_lds((const unsigned*)((const char*)(gbase) + (voff)[_i]), (PG8_LAS unsigned*)(lds + (bufoff) + ldsw + _i * 8192), 16, 0, 0); } while (0)
; #define PG8_LDA(dst, b, h) do { _Pragma("unroll") for (int m = 0; m < 4; ++m) _Pragma("unroll") for (int k = 0; k < 2; ++k) dst[m][k] = *(const PG8_LAS bf16x8*)(lds + PG8_SA(b, h) + aoff + m * 2048 + k * 1024); } while (0)
; #define PG8_LDB(dst, b, h) do { _Pragma("unroll") for (int n = 0; n < 2; ++n) _Pragma("unroll") for (int k = 0; k < 2; ++k) dst[n][k] = *(const PG8_LAS bf16x8*)(lds + PG8_SB(b, h) + boff + n * 2048 + k * 1024); } while (0)
; #define PG8_MMA(ai, bj, At, Bt) do { __builtin_amdgcn_s_setprio(1); _Pragma("unroll") for (int m = 0; m < 4; ++m) _Pragma("unroll") for (int n = 0; n < 2; ++n) _Pragma("unroll") for (int k = 0; k < 2; ++k) \
;         acc[ai][bj][m][n] = __builtin_amdgcn_mfma_f32_16x16x32_bf16(Bt[n][k], At[m][k], acc[ai][bj][m][n], 0, 0, 0); __builtin_amdgcn_s_setprio(0); } while (0)
; #define PG8_WAIT_V(n) asm volatile("s_waitcnt vmcnt(" #n ")" ::: "memory")
; #define PG8_BAR __builtin_amdgcn_s_barrier()
; template <class Epi, class Sched, bool ALIGN_EPI = false, bool SP2 = false>
; __device__ __forceinline__ void gemm_phase(PG8_LAS unsigned char* lds, const Gemm g, const Sched& S, const Epi& E) {
;     ...
;             const bool last = (t == nt - 2);
;             const char* a1 = cA + (size_t)(t + 1) * kstep;
;             const char* a2 = last ? nA : cA + (size_t)(t + 2) * kstep; const char* b2 = last ? nB : cB + (size_t)(t + 2) * kstep;
;             const char* a3 = a2 + kstep; const char* b3 = b2 + kstep;
;             if (last && has_next) S.a_ready(nxt);
;             if (last) E.prefetch(lds + 139264, cur, wid, lane);
;             if constexpr (SP2) {
;             PG8_LDB(B0, 0, 0); PG8_LDB(B1, 0, 1); PG8_SCHED; PG8_LDA(At, 0, 0); PG8_STAGE(PG8_SA(1, 1), a1 + hstep, voffA);
;             PG8_WAIT_V(8); PG8_WAIT_L(0); PG8_BAR; PG8_MMA(0, 0, At, B0); PG8_MMA(0, 1, At, B1); PG8_BAR; PG8_SCHED;
;             PG8_LDA(At, 0, 1); PG8_STAGE(PG8_SB(0, 0), b2, voffB); PG8_STAGE(PG8_SB(0, 1), b2 + hstep, voffB); PG8_STAGE(PG8_SA(0, 0), a2, voffA);
;             PG8_WAIT_V(8); PG8_WAIT_L(0); PG8_BAR; PG8_MMA(1, 0, At, B0); PG8_MMA(1, 1, At, B1); PG8_BAR; PG8_SCHED;
.LBB0_796:
	v_add_u32_e32 v130, s76, v165
	ds_read_b128 v[118:121], v130
	ds_read_b128 v[122:125], v130 offset:1024
	ds_read_b128 v[126:129], v130 offset:2048
	ds_read_b128 v[172:175], v130 offset:3072
	v_add_u32_e32 v130, s77, v165
	ds_read_b128 v[176:179], v130
	ds_read_b128 v[184:187], v130 offset:1024
	ds_read_b128 v[188:191], v130 offset:2048
	ds_read_b128 v[192:195], v130 offset:3072
	s_add_u32 s12, s52, 0xfffc0080
	s_addc_u32 s13, s53, -1
	s_and_b64 s[34:35], s[54:55], exec
	s_cselect_b32 s57, s43, s13
	s_cselect_b32 s56, s78, s12
	s_cselect_b32 s55, s41, s51
	s_cselect_b32 s54, s79, s49
	s_add_i32 m0, s62, 0xc000
	ds_read_b128 v[196:199], v170
	ds_read_b128 v[200:203], v170 offset:1024
	ds_read_b128 v[204:207], v170 offset:2048
	ds_read_b128 v[208:211], v170 offset:3072
	ds_read_b128 v[212:215], v170 offset:4096
	ds_read_b128 v[216:219], v170 offset:5120
	ds_read_b128 v[220:223], v170 offset:6144
	ds_read_b128 v[224:227], v170 offset:7168
	global_load_lds_dwordx4 v154, s[52:53]
	s_add_i32 m0, s62, 0xe000
	s_nop 0
	global_load_lds_dwordx4 v152, s[52:53]
	s_waitcnt vmcnt(8)
	s_waitcnt lgkmcnt(0)
	s_barrier
	s_setprio 1
	s_waitcnt lgkmcnt(0)
	v_mfma_f32_16x16x32_bf16 v[140:143], v[118:121], v[196:199], v[140:143]
	v_mfma_f32_16x16x32_bf16 v[136:139], v[126:129], v[196:199], v[136:139]
	v_mfma_f32_16x16x32_bf16 v[104:107], v[126:129], v[204:207], v[104:107]
	v_mfma_f32_16x16x32_bf16 v[108:111], v[118:121], v[204:207], v[108:111]
	v_mfma_f32_16x16x32_bf16 v[92:95], v[118:121], v[212:215], v[92:95]
	v_mfma_f32_16x16x32_bf16 v[88:91], v[126:129], v[212:215], v[88:91]
	v_mfma_f32_16x16x32_bf16 v[72:75], v[126:129], v[220:223], v[72:75]
	v_mfma_f32_16x16x32_bf16 v[76:79], v[118:121], v[220:223], v[76:79]
	v_mfma_f32_16x16x32_bf16 v[140:143], v[122:125], v[200:203], v[140:143]
	v_mfma_f32_16x16x32_bf16 v[136:139], v[172:175], v[200:203], v[136:139]
	v_mfma_f32_16x16x32_bf16 v[104:107], v[172:175], v[208:211], v[104:107]
	v_mfma_f32_16x16x32_bf16 v[108:111], v[122:125], v[208:211], v[108:111]
	v_mfma_f32_16x16x32_bf16 v[92:95], v[122:125], v[216:219], v[92:95]
	v_mfma_f32_16x16x32_bf16 v[88:91], v[172:175], v[216:219], v[88:91]
	v_mfma_f32_16x16x32_bf16 v[72:75], v[172:175], v[224:227], v[72:75]
	v_mfma_f32_16x16x32_bf16 v[76:79], v[122:125], v[224:227], v[76:79]
	s_setprio 0
	s_setprio 1
	v_mfma_f32_16x16x32_bf16 v[130:133], v[176:179], v[196:199], v[132:135]
	v_mfma_f32_16x16x32_bf16 v[112:115], v[188:191], v[196:199], v[112:115]
	v_mfma_f32_16x16x32_bf16 v[96:99], v[188:191], v[204:207], v[96:99]
	v_mfma_f32_16x16x32_bf16 v[100:103], v[176:179], v[204:207], v[100:103]
	v_mfma_f32_16x16x32_bf16 v[84:87], v[176:179], v[212:215], v[84:87]
	v_mfma_f32_16x16x32_bf16 v[80:83], v[188:191], v[212:215], v[80:83]
	v_mfma_f32_16x16x32_bf16 v[64:67], v[188:191], v[220:223], v[64:67]
	v_mfma_f32_16x16x32_bf16 v[68:71], v[176:179], v[220:223], v[68:71]
	v_mfma_f32_16x16x32_bf16 v[130:133], v[184:187], v[200:203], v[130:133]
	v_mfma_f32_16x16x32_bf16 v[112:115], v[192:195], v[200:203], v[112:115]
	v_mfma_f32_16x16x32_bf16 v[96:99], v[192:195], v[208:211], v[96:99]
	v_mfma_f32_16x16x32_bf16 v[100:103], v[184:187], v[208:211], v[100:103]
	v_mfma_f32_16x16x32_bf16 v[84:87], v[184:187], v[216:219], v[84:87]
	v_mfma_f32_16x16x32_bf16 v[80:83], v[192:195], v[216:219], v[80:83]
	v_mfma_f32_16x16x32_bf16 v[64:67], v[192:195], v[224:227], v[64:67]
	v_mfma_f32_16x16x32_bf16 v[68:71], v[184:187], v[224:227], v[68:71]
	s_setprio 0
	s_barrier
	s_add_i32 s12, s76, s59
	s_mov_b32 m0, s12
	ds_read_b128 v[196:199], v170 offset:16384
	ds_read_b128 v[200:203], v170 offset:17408
	ds_read_b128 v[204:207], v170 offset:18432
	ds_read_b128 v[208:211], v170 offset:19456
	ds_read_b128 v[212:215], v170 offset:20480
	ds_read_b128 v[216:219], v170 offset:21504
	ds_read_b128 v[220:223], v170 offset:22528
	ds_read_b128 v[224:227], v170 offset:23552
	global_load_lds_dwordx4 v148, s[54:55]
	s_add_i32 m0, s12, 0x2000
	s_add_u32 s34, s54, 0x40000
	s_addc_u32 s35, s55, 0
	s_add_i32 s12, s77, s59
	global_load_lds_dwordx4 v144, s[54:55]
	s_mov_b32 m0, s12
	s_nop 0
	global_load_lds_dwordx4 v148, s[34:35]
	s_add_i32 m0, s12, 0x2000
	s_nop 0
	global_load_lds_dwordx4 v144, s[34:35]
	s_mov_b32 m0, s62
	s_nop 0
	global_load_lds_dwordx4 v150, s[56:57]
	s_mov_b32 m0, s63
	s_nop 0
	global_load_lds_dwordx4 v146, s[56:57]
	s_waitcnt vmcnt(8)
	s_waitcnt lgkmcnt(0)
	s_barrier
	s_setprio 1
	s_waitcnt lgkmcnt(0)
	v_mfma_f32_16x16x32_bf16 v[60:63], v[118:121], v[196:199], v[60:63]
	v_mfma_f32_16x16x32_bf16 v[56:59], v[126:129], v[196:199], v[56:59]
	v_mfma_f32_16x16x32_bf16 v[40:43], v[126:129], v[204:207], v[40:43]
	v_mfma_f32_16x16x32_bf16 v[44:47], v[118:121], v[204:207], v[44:47]
	v_mfma_f32_16x16x32_bf16 v[28:31], v[118:121], v[212:215], v[28:31]
	v_mfma_f32_16x16x32_bf16 v[24:27], v[126:129], v[212:215], v[24:27]
	v_mfma_f32_16x16x32_bf16 v[8:11], v[126:129], v[220:223], v[8:11]
	v_mfma_f32_16x16x32_bf16 v[12:15], v[118:121], v[220:223], v[12:15]
	v_mfma_f32_16x16x32_bf16 v[60:63], v[122:125], v[200:203], v[60:63]
	v_mfma_f32_16x16x32_bf16 v[56:59], v[172:175], v[200:203], v[56:59]
	v_mfma_f32_16x16x32_bf16 v[40:43], v[172:175], v[208:211], v[40:43]
	v_mfma_f32_16x16x32_bf16 v[44:47], v[122:125], v[208:211], v[44:47]
	v_mfma_f32_16x16x32_bf16 v[28:31], v[122:125], v[216:219], v[28:31]
	v_mfma_f32_16x16x32_bf16 v[24:27], v[172:175], v[216:219], v[24:27]
	v_mfma_f32_16x16x32_bf16 v[8:11], v[172:175], v[224:227], v[8:11]
	v_mfma_f32_16x16x32_bf16 v[12:15], v[122:125], v[224:227], v[12:15]
	s_setprio 0
	s_setprio 1
	v_mfma_f32_16x16x32_bf16 v[52:55], v[176:179], v[196:199], v[52:55]
	v_mfma_f32_16x16x32_bf16 v[48:51], v[188:191], v[196:199], v[48:51]
	v_mfma_f32_16x16x32_bf16 v[32:35], v[188:191], v[204:207], v[32:35]
	v_mfma_f32_16x16x32_bf16 v[36:39], v[176:179], v[204:207], v[36:39]
	v_mfma_f32_16x16x32_bf16 v[20:23], v[176:179], v[212:215], v[20:23]
	v_mfma_f32_16x16x32_bf16 v[16:19], v[188:191], v[212:215], v[16:19]
	v_mfma_f32_16x16x32_bf16 v[0:3], v[188:191], v[220:223], v[0:3]
	v_mfma_f32_16x16x32_bf16 v[4:7], v[176:179], v[220:223], v[4:7]
	v_mfma_f32_16x16x32_bf16 v[52:55], v[184:187], v[200:203], v[52:55]
	v_mfma_f32_16x16x32_bf16 v[48:51], v[192:195], v[200:203], v[48:51]
	v_mfma_f32_16x16x32_bf16 v[32:35], v[192:195], v[208:211], v[32:35]
	v_mfma_f32_16x16x32_bf16 v[36:39], v[184:187], v[208:211], v[36:39]
	v_mfma_f32_16x16x32_bf16 v[20:23], v[184:187], v[216:219], v[20:23]
	v_mfma_f32_16x16x32_bf16 v[16:19], v[192:195], v[216:219], v[16:19]
	v_mfma_f32_16x16x32_bf16 v[0:3], v[192:195], v[224:227], v[0:3]
	v_mfma_f32_16x16x32_bf16 v[4:7], v[184:187], v[224:227], v[4:7]
	s_setprio 0
	s_barrier
; #define PG8_STAGE(bufoff, gbase, voff) do { _Pragma("unroll") for (int _i = 0; _i < 2; ++_i) \
;         __builtin_amdgcn_global_load_lds((const unsigned*)((const char*)(gbase) + (voff)[_i]), (PG8_LAS unsigned*)(lds + (bufoff) + ldsw + _i * 8192), 16, 0, 0); } while (0)
; #define PG8_LDA(dst, b, h) do { _Pragma("unroll") for (int m = 0; m < 4; ++m) _Pragma("unroll") for (int k = 0; k < 2; ++k) dst[m][k] = *(const PG8_LAS bf16x8*)(lds + PG8_SA(b, h) + aoff + m * 2048 + k * 1024); } while (0)
; #define PG8_LDB(dst, b, h) do { _Pragma("unroll") for (int n = 0; n < 2; ++n) _Pragma("unroll") for (int k = 0; k < 2; ++k) dst[n][k] = *(const PG8_LAS bf16x8*)(lds + PG8_SB(b, h) + boff + n * 2048 + k * 1024); } while (0)
; #define PG8_MMA(ai, bj, At, Bt) do { __builtin_amdgcn_s_setprio(1); _Pragma("unroll") for (int m = 0; m < 4; ++m) _Pragma("unroll") for (int n = 0; n < 2; ++n) _Pragma("unroll") for (int k = 0; k < 2; ++k) \
;         acc[ai][bj][m][n] = __builtin_amdgcn_mfma_f32_16x16x32_bf16(Bt[n][k], At[m][k], acc[ai][bj][m][n], 0, 0, 0); __builtin_amdgcn_s_setprio(0); } while (0)
; #define PG8_WAIT_V(n) asm volatile("s_waitcnt vmcnt(" #n ")" ::: "memory")
; #define PG8_WAIT_L(n) asm volatile("s_waitcnt lgkmcnt(" #n ")" ::: "memory")
; #define PG8_BAR __builtin_amdgcn_s_barrier()
; #define PG8_SCHED __builtin_amdgcn_sched_barrier(0)
; template <class Epi, class Sched, bool ALIGN_EPI = false, bool SP2 = false>
; __device__ __forceinline__ void gemm_phase(PG8_LAS unsigned char* lds, const Gemm g, const Sched& S, const Epi& E) {
;     ...
;             PG8_LDB(B0, 1, 0); PG8_LDB(B1, 1, 1); PG8_SCHED; PG8_LDA(At, 1, 0); PG8_STAGE(PG8_SA(0, 1), a2 + hstep, voffA);
;             PG8_WAIT_V(8); PG8_WAIT_L(0); PG8_BAR; PG8_MMA(0, 0, At, B0); PG8_MMA(0, 1, At, B1); PG8_BAR; PG8_SCHED;
;             PG8_LDA(At, 1, 1); PG8_STAGE(PG8_SB(1, 0), b3, voffB); PG8_STAGE(PG8_SB(1, 1), b3 + hstep, voffB); PG8_STAGE(PG8_SA(1, 0), a3, voffA);
;             PG8_WAIT_V(8); PG8_WAIT_L(0); PG8_BAR; PG8_MMA(1, 0, At, B0); PG8_MMA(1, 1, At, B1); PG8_BAR; PG8_SCHED;
	s_add_i32 s12, 0, 0x18000
	v_add_u32_e32 v134, s12, v165
	s_add_i32 s13, 0, 0x1c000
	ds_read_b128 v[118:121], v134
	ds_read_b128 v[122:125], v134 offset:1024
	ds_read_b128 v[126:129], v134 offset:2048
	ds_read_b128 v[172:175], v134 offset:3072
	v_add_u32_e32 v134, s13, v165
	ds_read_b128 v[176:179], v134
	ds_read_b128 v[184:187], v134 offset:1024
	ds_read_b128 v[188:191], v134 offset:2048
	ds_read_b128 v[192:195], v134 offset:3072
	s_add_u32 s34, s56, 0x40000
	s_addc_u32 s35, s57, 0
	s_mov_b32 m0, s64
	ds_read_b128 v[196:199], v170 offset:32768
	ds_read_b128 v[200:203], v170 offset:33792
	ds_read_b128 v[204:207], v170 offset:34816
	ds_read_b128 v[208:211], v170 offset:35840
	ds_read_b128 v[212:215], v170 offset:36864
	ds_read_b128 v[216:219], v170 offset:37888
	ds_read_b128 v[220:223], v170 offset:38912
	ds_read_b128 v[224:227], v170 offset:39936
	global_load_lds_dwordx4 v150, s[34:35]
	s_mov_b32 m0, s65
	s_nop 0
	global_load_lds_dwordx4 v146, s[34:35]
	s_waitcnt vmcnt(8)
	s_waitcnt lgkmcnt(0)
	s_barrier
	s_setprio 1
	s_waitcnt lgkmcnt(0)
	v_mfma_f32_16x16x32_bf16 v[140:143], v[118:121], v[196:199], v[140:143]
	v_mfma_f32_16x16x32_bf16 v[134:137], v[126:129], v[196:199], v[136:139]
	v_mfma_f32_16x16x32_bf16 v[104:107], v[126:129], v[204:207], v[104:107]
	v_mfma_f32_16x16x32_bf16 v[108:111], v[118:121], v[204:207], v[108:111]
	v_mfma_f32_16x16x32_bf16 v[92:95], v[118:121], v[212:215], v[92:95]
	v_mfma_f32_16x16x32_bf16 v[88:91], v[126:129], v[212:215], v[88:91]
	v_mfma_f32_16x16x32_bf16 v[72:75], v[126:129], v[220:223], v[72:75]
	v_mfma_f32_16x16x32_bf16 v[76:79], v[118:121], v[220:223], v[76:79]
	v_mfma_f32_16x16x32_bf16 v[140:143], v[122:125], v[200:203], v[140:143]
	v_mfma_f32_16x16x32_bf16 v[136:139], v[172:175], v[200:203], v[134:137]
	v_mfma_f32_16x16x32_bf16 v[104:107], v[172:175], v[208:211], v[104:107]
	v_mfma_f32_16x16x32_bf16 v[108:111], v[122:125], v[208:211], v[108:111]
	v_mfma_f32_16x16x32_bf16 v[92:95], v[122:125], v[216:219], v[92:95]
	v_mfma_f32_16x16x32_bf16 v[88:91], v[172:175], v[216:219], v[88:91]
	v_mfma_f32_16x16x32_bf16 v[72:75], v[172:175], v[224:227], v[72:75]
	v_mfma_f32_16x16x32_bf16 v[76:79], v[122:125], v[224:227], v[76:79]
	s_setprio 0
	s_setprio 1
	v_mfma_f32_16x16x32_bf16 v[130:133], v[176:179], v[196:199], v[130:133]
	v_mfma_f32_16x16x32_bf16 v[112:115], v[188:191], v[196:199], v[112:115]
	v_mfma_f32_16x16x32_bf16 v[96:99], v[188:191], v[204:207], v[96:99]
	v_mfma_f32_16x16x32_bf16 v[100:103], v[176:179], v[204:207], v[100:103]
	v_mfma_f32_16x16x32_bf16 v[84:87], v[176:179], v[212:215], v[84:87]
	v_mfma_f32_16x16x32_bf16 v[80:83], v[188:191], v[212:215], v[80:83]
	v_mfma_f32_16x16x32_bf16 v[64:67], v[188:191], v[220:223], v[64:67]
	v_mfma_f32_16x16x32_bf16 v[68:71], v[176:179], v[220:223], v[68:71]
	v_mfma_f32_16x16x32_bf16 v[132:135], v[184:187], v[200:203], v[130:133]
	v_mfma_f32_16x16x32_bf16 v[112:115], v[192:195], v[200:203], v[112:115]
	v_mfma_f32_16x16x32_bf16 v[96:99], v[192:195], v[208:211], v[96:99]
	v_mfma_f32_16x16x32_bf16 v[100:103], v[184:187], v[208:211], v[100:103]
	v_mfma_f32_16x16x32_bf16 v[84:87], v[184:187], v[216:219], v[84:87]
	v_mfma_f32_16x16x32_bf16 v[80:83], v[192:195], v[216:219], v[80:83]
	v_mfma_f32_16x16x32_bf16 v[64:67], v[192:195], v[224:227], v[64:67]
	v_mfma_f32_16x16x32_bf16 v[68:71], v[184:187], v[224:227], v[68:71]
	s_setprio 0
	s_barrier
	s_add_i32 s12, s12, s59
	s_add_u32 s98, s54, s18
	s_addc_u32 s99, s55, s19
	s_add_u32 s100, s56, s18
	s_addc_u32 s101, s57, s19
	s_mov_b32 m0, s12
	ds_read_b128 v[196:199], v170 offset:49152
	ds_read_b128 v[200:203], v170 offset:50176
	ds_read_b128 v[204:207], v170 offset:51200
	ds_read_b128 v[208:211], v170 offset:52224
	ds_read_b128 v[212:215], v170 offset:53248
	ds_read_b128 v[216:219], v170 offset:54272
	ds_read_b128 v[220:223], v170 offset:55296
	ds_read_b128 v[224:227], v170 offset:56320
	global_load_lds_dwordx4 v148, s[98:99]
	s_add_i32 m0, s12, 0x2000
	s_add_u32 s34, s54, 0x40080
	s_addc_u32 s35, s55, 0
	s_add_i32 s12, s13, s59
	global_load_lds_dwordx4 v144, s[98:99]
	s_mov_b32 m0, s12
	s_nop 0
	global_load_lds_dwordx4 v148, s[34:35]
	s_add_i32 m0, s12, 0x2000
	s_nop 0
	global_load_lds_dwordx4 v144, s[34:35]
	s_mov_b32 m0, s68
	s_nop 0
	global_load_lds_dwordx4 v150, s[100:101]
	s_mov_b32 m0, s69
	s_nop 0
	global_load_lds_dwordx4 v146, s[100:101]
	s_waitcnt vmcnt(8)
	s_waitcnt lgkmcnt(0)
	s_barrier
	s_setprio 1
	s_waitcnt lgkmcnt(0)
	v_mfma_f32_16x16x32_bf16 v[60:63], v[118:121], v[196:199], v[60:63]
	v_mfma_f32_16x16x32_bf16 v[56:59], v[126:129], v[196:199], v[56:59]
	v_mfma_f32_16x16x32_bf16 v[40:43], v[126:129], v[204:207], v[40:43]
	v_mfma_f32_16x16x32_bf16 v[44:47], v[118:121], v[204:207], v[44:47]
	v_mfma_f32_16x16x32_bf16 v[28:31], v[118:121], v[212:215], v[28:31]
	v_mfma_f32_16x16x32_bf16 v[24:27], v[126:129], v[212:215], v[24:27]
	v_mfma_f32_16x16x32_bf16 v[8:11], v[126:129], v[220:223], v[8:11]
	v_mfma_f32_16x16x32_bf16 v[12:15], v[118:121], v[220:223], v[12:15]
	v_mfma_f32_16x16x32_bf16 v[60:63], v[122:125], v[200:203], v[60:63]
	v_mfma_f32_16x16x32_bf16 v[56:59], v[172:175], v[200:203], v[56:59]
	v_mfma_f32_16x16x32_bf16 v[40:43], v[172:175], v[208:211], v[40:43]
	v_mfma_f32_16x16x32_bf16 v[44:47], v[122:125], v[208:211], v[44:47]
	v_mfma_f32_16x16x32_bf16 v[28:31], v[122:125], v[216:219], v[28:31]
	v_mfma_f32_16x16x32_bf16 v[24:27], v[172:175], v[216:219], v[24:27]
	v_mfma_f32_16x16x32_bf16 v[8:11], v[172:175], v[224:227], v[8:11]
	v_mfma_f32_16x16x32_bf16 v[12:15], v[122:125], v[224:227], v[12:15]
	s_setprio 0
	s_setprio 1
	v_mfma_f32_16x16x32_bf16 v[52:55], v[176:179], v[196:199], v[52:55]
	v_mfma_f32_16x16x32_bf16 v[48:51], v[188:191], v[196:199], v[48:51]
	v_mfma_f32_16x16x32_bf16 v[32:35], v[188:191], v[204:207], v[32:35]
	v_mfma_f32_16x16x32_bf16 v[36:39], v[176:179], v[204:207], v[36:39]
	v_mfma_f32_16x16x32_bf16 v[20:23], v[176:179], v[212:215], v[20:23]
	v_mfma_f32_16x16x32_bf16 v[16:19], v[188:191], v[212:215], v[16:19]
	v_mfma_f32_16x16x32_bf16 v[0:3], v[188:191], v[220:223], v[0:3]
	v_mfma_f32_16x16x32_bf16 v[4:7], v[176:179], v[220:223], v[4:7]
	v_mfma_f32_16x16x32_bf16 v[52:55], v[184:187], v[200:203], v[52:55]
	v_mfma_f32_16x16x32_bf16 v[48:51], v[192:195], v[200:203], v[48:51]
	v_mfma_f32_16x16x32_bf16 v[32:35], v[192:195], v[208:211], v[32:35]
	v_mfma_f32_16x16x32_bf16 v[36:39], v[184:187], v[208:211], v[36:39]
	v_mfma_f32_16x16x32_bf16 v[20:23], v[184:187], v[216:219], v[20:23]
	v_mfma_f32_16x16x32_bf16 v[16:19], v[192:195], v[216:219], v[16:19]
	v_mfma_f32_16x16x32_bf16 v[0:3], v[192:195], v[224:227], v[0:3]
	v_mfma_f32_16x16x32_bf16 v[4:7], v[184:187], v[224:227], v[4:7]
	s_setprio 0
	s_barrier
	s_add_i32 s80, s80, 2
	s_add_u32 s49, s49, 0x100
	s_addc_u32 s51, s51, 0
	s_add_u32 s52, s52, 0x100
	s_addc_u32 s53, s53, 0
	s_cmp_gt_u32 s80, 13
	s_cbranch_scc1 .LBB0_799

; #define PG8_STAGE(bufoff, gbase, voff) do { _Pragma("unroll") for (int _i = 0; _i < 2; ++_i) \
;         __builtin_amdgcn_global_load_lds((const unsigned*)((const char*)(gbase) + (voff)[_i]), (PG8_LAS unsigned*)(lds + (bufoff) + ldsw + _i * 8192), 16, 0, 0); } while (0)
; #define PG8_LDA(dst, b, h) do { _Pragma("unroll") for (int m = 0; m < 4; ++m) _Pragma("unroll") for (int k = 0; k < 2; ++k) dst[m][k] = *(const PG8_LAS bf16x8*)(lds + PG8_SA(b, h) + aoff + m * 2048 + k * 1024); } while (0)
; #define PG8_LDB(dst, b, h) do { _Pragma("unroll") for (int n = 0; n < 2; ++n) _Pragma("unroll") for (int k = 0; k < 2; ++k) dst[n][k] = *(const PG8_LAS bf16x8*)(lds + PG8_SB(b, h) + boff + n * 2048 + k * 1024); } while (0)
; #define PG8_MMA(ai, bj, At, Bt) do { __builtin_amdgcn_s_setprio(1); _Pragma("unroll") for (int m = 0; m < 4; ++m) _Pragma("unroll") for (int n = 0; n < 2; ++n) _Pragma("unroll") for (int k = 0; k < 2; ++k) \
;         acc[ai][bj][m][n] = __builtin_amdgcn_mfma_f32_16x16x32_bf16(Bt[n][k], At[m][k], acc[ai][bj][m][n], 0, 0, 0); __builtin_amdgcn_s_setprio(0); } while (0)
; #define PG8_WAIT_V(n) asm volatile("s_waitcnt vmcnt(" #n ")" ::: "memory")
; #define PG8_BAR __builtin_amdgcn_s_barrier()
; template <class Epi, class Sched, bool ALIGN_EPI = false, bool SP2 = false>
; __device__ __forceinline__ void gemm_phase(PG8_LAS unsigned char* lds, const Gemm g, const Sched& S, const Epi& E) {
;     ...
;             const bool last = (t == nt - 2);
;             const char* a1 = cA + (size_t)(t + 1) * kstep;
;             const char* a2 = last ? nA : cA + (size_t)(t + 2) * kstep; const char* b2 = last ? nB : cB + (size_t)(t + 2) * kstep;
;             const char* a3 = a2 + kstep; const char* b3 = b2 + kstep;
;             if (last && has_next) S.a_ready(nxt);
;             if (last) E.prefetch(lds + 139264, cur, wid, lane);
;             if constexpr (SP2) {
;             PG8_LDB(B0, 0, 0); PG8_LDB(B1, 0, 1); PG8_SCHED; PG8_LDA(At, 0, 0); PG8_STAGE(PG8_SA(1, 1), a1 + hstep, voffA);
;             PG8_WAIT_V(8); PG8_WAIT_L(0); PG8_BAR; PG8_MMA(0, 0, At, B0); PG8_MMA(0, 1, At, B1); PG8_BAR; PG8_SCHED;
;             PG8_LDA(At, 0, 1); PG8_STAGE(PG8_SB(0, 0), b2, voffB); PG8_STAGE(PG8_SB(0, 1), b2 + hstep, voffB); PG8_STAGE(PG8_SA(0, 0), a2, voffA);
;             PG8_WAIT_V(8); PG8_WAIT_L(0); PG8_BAR; PG8_MMA(1, 0, At, B0); PG8_MMA(1, 1, At, B1); PG8_BAR; PG8_SCHED;
.LBB0_872:
	ds_read_b128 v[128:131], v169
	ds_read_b128 v[132:135], v169 offset:1024
	ds_read_b128 v[136:139], v169 offset:2048
	ds_read_b128 v[140:143], v169 offset:3072
	ds_read_b128 v[162:165], v170
	ds_read_b128 v[172:175], v170 offset:1024
	ds_read_b128 v[176:179], v170 offset:2048
	ds_read_b128 v[184:187], v170 offset:3072
	s_add_u32 s42, s40, 0x100
	s_addc_u32 s43, s41, 0
	s_cmp_eq_u32 s74, 40
	s_cselect_b32 s47, s11, s43
	s_cselect_b32 s46, s10, s42
	s_cselect_b32 s45, s37, s73
	s_cselect_b32 s44, s36, s71
	v_lshl_add_u64 v[180:181], s[40:41], 0, v[154:155]
	s_add_i32 m0, s50, 0xc000
	ds_read_b128 v[188:191], v171
	ds_read_b128 v[192:195], v171 offset:1024
	ds_read_b128 v[196:199], v171 offset:2048
	ds_read_b128 v[200:203], v171 offset:3072
	ds_read_b128 v[204:207], v171 offset:4096
	ds_read_b128 v[208:211], v171 offset:5120
	ds_read_b128 v[212:215], v171 offset:6144
	ds_read_b128 v[216:219], v171 offset:7168
	global_load_lds_dwordx4 v[180:181], off
	v_lshl_add_u64 v[180:181], s[40:41], 0, v[152:153]
	s_add_i32 m0, s50, 0xe000
	s_nop 0
	global_load_lds_dwordx4 v[180:181], off
	s_waitcnt vmcnt(8)
	s_waitcnt lgkmcnt(0)
	s_barrier
	s_setprio 1
	s_waitcnt lgkmcnt(0)
	v_mfma_f32_16x16x32_bf16 v[124:127], v[128:131], v[188:191], v[124:127]
	v_mfma_f32_16x16x32_bf16 v[120:123], v[136:139], v[188:191], v[120:123]
	v_mfma_f32_16x16x32_bf16 v[108:111], v[136:139], v[196:199], v[108:111]
	v_mfma_f32_16x16x32_bf16 v[116:119], v[128:131], v[196:199], v[116:119]
	v_mfma_f32_16x16x32_bf16 v[100:103], v[128:131], v[204:207], v[100:103]
	v_mfma_f32_16x16x32_bf16 v[92:95], v[136:139], v[204:207], v[92:95]
	v_mfma_f32_16x16x32_bf16 v[76:79], v[136:139], v[212:215], v[76:79]
	v_mfma_f32_16x16x32_bf16 v[84:87], v[128:131], v[212:215], v[84:87]
	v_mfma_f32_16x16x32_bf16 v[124:127], v[132:135], v[192:195], v[124:127]
	v_mfma_f32_16x16x32_bf16 v[120:123], v[140:143], v[192:195], v[120:123]
	v_mfma_f32_16x16x32_bf16 v[108:111], v[140:143], v[200:203], v[108:111]
	v_mfma_f32_16x16x32_bf16 v[116:119], v[132:135], v[200:203], v[116:119]
	v_mfma_f32_16x16x32_bf16 v[100:103], v[132:135], v[208:211], v[100:103]
	v_mfma_f32_16x16x32_bf16 v[92:95], v[140:143], v[208:211], v[92:95]
	v_mfma_f32_16x16x32_bf16 v[76:79], v[140:143], v[216:219], v[76:79]
	v_mfma_f32_16x16x32_bf16 v[84:87], v[132:135], v[216:219], v[84:87]
	s_setprio 0
	s_setprio 1
	v_mfma_f32_16x16x32_bf16 v[112:115], v[162:165], v[188:191], v[112:115]
	v_mfma_f32_16x16x32_bf16 v[104:107], v[176:179], v[188:191], v[104:107]
	v_mfma_f32_16x16x32_bf16 v[88:91], v[176:179], v[196:199], v[88:91]
	v_mfma_f32_16x16x32_bf16 v[96:99], v[162:165], v[196:199], v[96:99]
	v_mfma_f32_16x16x32_bf16 v[80:83], v[162:165], v[204:207], v[80:83]
	v_mfma_f32_16x16x32_bf16 v[72:75], v[176:179], v[204:207], v[72:75]
	v_mfma_f32_16x16x32_bf16 v[64:67], v[176:179], v[212:215], v[64:67]
	v_mfma_f32_16x16x32_bf16 v[68:71], v[162:165], v[212:215], v[68:71]
	v_mfma_f32_16x16x32_bf16 v[112:115], v[172:175], v[192:195], v[112:115]
	v_mfma_f32_16x16x32_bf16 v[104:107], v[184:187], v[192:195], v[104:107]
	v_mfma_f32_16x16x32_bf16 v[88:91], v[184:187], v[200:203], v[88:91]
	v_mfma_f32_16x16x32_bf16 v[96:99], v[172:175], v[200:203], v[96:99]
	v_mfma_f32_16x16x32_bf16 v[80:83], v[172:175], v[208:211], v[80:83]
	v_mfma_f32_16x16x32_bf16 v[72:75], v[184:187], v[208:211], v[72:75]
	v_mfma_f32_16x16x32_bf16 v[64:67], v[184:187], v[216:219], v[64:67]
	v_mfma_f32_16x16x32_bf16 v[68:71], v[172:175], v[216:219], v[68:71]
	s_setprio 0
	s_barrier
	s_add_i32 s12, s65, s49
	s_mov_b32 m0, s12
	ds_read_b128 v[188:191], v171 offset:16384
	ds_read_b128 v[192:195], v171 offset:17408
	ds_read_b128 v[196:199], v171 offset:18432
	ds_read_b128 v[200:203], v171 offset:19456
	ds_read_b128 v[204:207], v171 offset:20480
	ds_read_b128 v[208:211], v171 offset:21504
	ds_read_b128 v[212:215], v171 offset:22528
	ds_read_b128 v[216:219], v171 offset:23552
	global_load_lds_dwordx4 v146, s[44:45]
	s_add_i32 m0, s12, 0x2000
	s_add_u32 s40, s44, 0xb0000
	s_addc_u32 s41, s45, 0
	s_add_i32 s12, s66, s49
	global_load_lds_dwordx4 v150, s[44:45]
	s_mov_b32 m0, s12
	s_nop 0
	global_load_lds_dwordx4 v146, s[40:41]
	s_add_i32 m0, s12, 0x2000
	s_nop 0
	global_load_lds_dwordx4 v150, s[40:41]
	s_mov_b32 m0, s50
	s_nop 0
	global_load_lds_dwordx4 v144, s[46:47]
	s_mov_b32 m0, s51
	s_nop 0
	global_load_lds_dwordx4 v148, s[46:47]
	s_waitcnt vmcnt(8)
	s_waitcnt lgkmcnt(0)
	s_barrier
	s_setprio 1
	s_waitcnt lgkmcnt(0)
	v_mfma_f32_16x16x32_bf16 v[60:63], v[128:131], v[188:191], v[60:63]
	v_mfma_f32_16x16x32_bf16 v[56:59], v[136:139], v[188:191], v[56:59]
	v_mfma_f32_16x16x32_bf16 v[44:47], v[136:139], v[196:199], v[44:47]
	v_mfma_f32_16x16x32_bf16 v[48:51], v[128:131], v[196:199], v[48:51]
	v_mfma_f32_16x16x32_bf16 v[36:39], v[128:131], v[204:207], v[36:39]
	v_mfma_f32_16x16x32_bf16 v[28:31], v[136:139], v[204:207], v[28:31]
	v_mfma_f32_16x16x32_bf16 v[12:15], v[136:139], v[212:215], v[12:15]
	v_mfma_f32_16x16x32_bf16 v[20:23], v[128:131], v[212:215], v[20:23]
	v_mfma_f32_16x16x32_bf16 v[60:63], v[132:135], v[192:195], v[60:63]
	v_mfma_f32_16x16x32_bf16 v[56:59], v[140:143], v[192:195], v[56:59]
	v_mfma_f32_16x16x32_bf16 v[44:47], v[140:143], v[200:203], v[44:47]
	v_mfma_f32_16x16x32_bf16 v[48:51], v[132:135], v[200:203], v[48:51]
	v_mfma_f32_16x16x32_bf16 v[36:39], v[132:135], v[208:211], v[36:39]
	v_mfma_f32_16x16x32_bf16 v[28:31], v[140:143], v[208:211], v[28:31]
	v_mfma_f32_16x16x32_bf16 v[12:15], v[140:143], v[216:219], v[12:15]
	v_mfma_f32_16x16x32_bf16 v[20:23], v[132:135], v[216:219], v[20:23]
	s_setprio 0
	s_setprio 1
	v_mfma_f32_16x16x32_bf16 v[52:55], v[162:165], v[188:191], v[52:55]
	v_mfma_f32_16x16x32_bf16 v[40:43], v[176:179], v[188:191], v[40:43]
	v_mfma_f32_16x16x32_bf16 v[24:27], v[176:179], v[196:199], v[24:27]
	v_mfma_f32_16x16x32_bf16 v[32:35], v[162:165], v[196:199], v[32:35]
	v_mfma_f32_16x16x32_bf16 v[16:19], v[162:165], v[204:207], v[16:19]
	v_mfma_f32_16x16x32_bf16 v[8:11], v[176:179], v[204:207], v[8:11]
	v_mfma_f32_16x16x32_bf16 v[0:3], v[176:179], v[212:215], v[0:3]
	v_mfma_f32_16x16x32_bf16 v[4:7], v[162:165], v[212:215], v[4:7]
	v_mfma_f32_16x16x32_bf16 v[52:55], v[172:175], v[192:195], v[52:55]
	v_mfma_f32_16x16x32_bf16 v[40:43], v[184:187], v[192:195], v[40:43]
	v_mfma_f32_16x16x32_bf16 v[24:27], v[184:187], v[200:203], v[24:27]
	v_mfma_f32_16x16x32_bf16 v[32:35], v[172:175], v[200:203], v[32:35]
	v_mfma_f32_16x16x32_bf16 v[16:19], v[172:175], v[208:211], v[16:19]
	v_mfma_f32_16x16x32_bf16 v[8:11], v[184:187], v[208:211], v[8:11]
	v_mfma_f32_16x16x32_bf16 v[0:3], v[184:187], v[216:219], v[0:3]
	v_mfma_f32_16x16x32_bf16 v[4:7], v[172:175], v[216:219], v[4:7]
	s_setprio 0
	s_barrier
; #define PG8_STAGE(bufoff, gbase, voff) do { _Pragma("unroll") for (int _i = 0; _i < 2; ++_i) \
;         __builtin_amdgcn_global_load_lds((const unsigned*)((const char*)(gbase) + (voff)[_i]), (PG8_LAS unsigned*)(lds + (bufoff) + ldsw + _i * 8192), 16, 0, 0); } while (0)
; #define PG8_LDA(dst, b, h) do { _Pragma("unroll") for (int m = 0; m < 4; ++m) _Pragma("unroll") for (int k = 0; k < 2; ++k) dst[m][k] = *(const PG8_LAS bf16x8*)(lds + PG8_SA(b, h) + aoff + m * 2048 + k * 1024); } while (0)
; #define PG8_LDB(dst, b, h) do { _Pragma("unroll") for (int n = 0; n < 2; ++n) _Pragma("unroll") for (int k = 0; k < 2; ++k) dst[n][k] = *(const PG8_LAS bf16x8*)(lds + PG8_SB(b, h) + boff + n * 2048 + k * 1024); } while (0)
; #define PG8_MMA(ai, bj, At, Bt) do { __builtin_amdgcn_s_setprio(1); _Pragma("unroll") for (int m = 0; m < 4; ++m) _Pragma("unroll") for (int n = 0; n < 2; ++n) _Pragma("unroll") for (int k = 0; k < 2; ++k) \
;         acc[ai][bj][m][n] = __builtin_amdgcn_mfma_f32_16x16x32_bf16(Bt[n][k], At[m][k], acc[ai][bj][m][n], 0, 0, 0); __builtin_amdgcn_s_setprio(0); } while (0)
; #define PG8_WAIT_V(n) asm volatile("s_waitcnt vmcnt(" #n ")" ::: "memory")
; #define PG8_WAIT_L(n) asm volatile("s_waitcnt lgkmcnt(" #n ")" ::: "memory")
; #define PG8_BAR __builtin_amdgcn_s_barrier()
; #define PG8_SCHED __builtin_amdgcn_sched_barrier(0)
; template <class Epi, class Sched, bool ALIGN_EPI = false, bool SP2 = false>
; __device__ __forceinline__ void gemm_phase(PG8_LAS unsigned char* lds, const Gemm g, const Sched& S, const Epi& E) {
;     ...
;             PG8_LDB(B0, 1, 0); PG8_LDB(B1, 1, 1); PG8_SCHED; PG8_LDA(At, 1, 0); PG8_STAGE(PG8_SA(0, 1), a2 + hstep, voffA);
;             PG8_WAIT_V(8); PG8_WAIT_L(0); PG8_BAR; PG8_MMA(0, 0, At, B0); PG8_MMA(0, 1, At, B1); PG8_BAR; PG8_SCHED;
;             PG8_LDA(At, 1, 1); PG8_STAGE(PG8_SB(1, 0), b3, voffB); PG8_STAGE(PG8_SB(1, 1), b3 + hstep, voffB); PG8_STAGE(PG8_SA(1, 0), a3, voffA);
;             PG8_WAIT_V(8); PG8_WAIT_L(0); PG8_BAR; PG8_MMA(1, 0, At, B0); PG8_MMA(1, 1, At, B1); PG8_BAR; PG8_SCHED;
	s_add_i32 s12, 0, 0x18000
	s_add_i32 s13, 0, 0x1c000
	v_add_u32_e32 v140, s12, v167
	v_add_u32_e32 v183, s13, v167
	ds_read_b128 v[128:131], v140
	ds_read_b128 v[132:135], v140 offset:1024
	ds_read_b128 v[136:139], v140 offset:2048
	ds_read_b128 v[140:143], v140 offset:3072
	ds_read_b128 v[162:165], v183
	ds_read_b128 v[172:175], v183 offset:1024
	ds_read_b128 v[176:179], v183 offset:2048
	ds_read_b128 v[184:187], v183 offset:3072
	s_add_u32 s40, s46, 0xb0000
	s_addc_u32 s41, s47, 0
	s_mov_b32 m0, s52
	ds_read_b128 v[188:191], v171 offset:32768
	ds_read_b128 v[192:195], v171 offset:33792
	ds_read_b128 v[196:199], v171 offset:34816
	ds_read_b128 v[200:203], v171 offset:35840
	ds_read_b128 v[204:207], v171 offset:36864
	ds_read_b128 v[208:211], v171 offset:37888
	ds_read_b128 v[212:215], v171 offset:38912
	ds_read_b128 v[216:219], v171 offset:39936
	global_load_lds_dwordx4 v144, s[40:41]
	s_mov_b32 m0, s53
	s_nop 0
	global_load_lds_dwordx4 v148, s[40:41]
	s_waitcnt vmcnt(8)
	s_waitcnt lgkmcnt(0)
	s_barrier
	s_setprio 1
	s_waitcnt lgkmcnt(0)
	v_mfma_f32_16x16x32_bf16 v[124:127], v[128:131], v[188:191], v[124:127]
	v_mfma_f32_16x16x32_bf16 v[120:123], v[136:139], v[188:191], v[120:123]
	v_mfma_f32_16x16x32_bf16 v[108:111], v[136:139], v[196:199], v[108:111]
	v_mfma_f32_16x16x32_bf16 v[116:119], v[128:131], v[196:199], v[116:119]
	v_mfma_f32_16x16x32_bf16 v[100:103], v[128:131], v[204:207], v[100:103]
	v_mfma_f32_16x16x32_bf16 v[92:95], v[136:139], v[204:207], v[92:95]
	v_mfma_f32_16x16x32_bf16 v[76:79], v[136:139], v[212:215], v[76:79]
	v_mfma_f32_16x16x32_bf16 v[84:87], v[128:131], v[212:215], v[84:87]
	v_mfma_f32_16x16x32_bf16 v[124:127], v[132:135], v[192:195], v[124:127]
	v_mfma_f32_16x16x32_bf16 v[120:123], v[140:143], v[192:195], v[120:123]
	v_mfma_f32_16x16x32_bf16 v[108:111], v[140:143], v[200:203], v[108:111]
	v_mfma_f32_16x16x32_bf16 v[116:119], v[132:135], v[200:203], v[116:119]
	v_mfma_f32_16x16x32_bf16 v[100:103], v[132:135], v[208:211], v[100:103]
	v_mfma_f32_16x16x32_bf16 v[92:95], v[140:143], v[208:211], v[92:95]
	v_mfma_f32_16x16x32_bf16 v[76:79], v[140:143], v[216:219], v[76:79]
	v_mfma_f32_16x16x32_bf16 v[84:87], v[132:135], v[216:219], v[84:87]
	s_setprio 0
	s_setprio 1
	v_mfma_f32_16x16x32_bf16 v[112:115], v[162:165], v[188:191], v[112:115]
	v_mfma_f32_16x16x32_bf16 v[104:107], v[176:179], v[188:191], v[104:107]
	v_mfma_f32_16x16x32_bf16 v[88:91], v[176:179], v[196:199], v[88:91]
	v_mfma_f32_16x16x32_bf16 v[96:99], v[162:165], v[196:199], v[96:99]
	v_mfma_f32_16x16x32_bf16 v[80:83], v[162:165], v[204:207], v[80:83]
	v_mfma_f32_16x16x32_bf16 v[72:75], v[176:179], v[204:207], v[72:75]
	v_mfma_f32_16x16x32_bf16 v[64:67], v[176:179], v[212:215], v[64:67]
	v_mfma_f32_16x16x32_bf16 v[68:71], v[162:165], v[212:215], v[68:71]
	v_mfma_f32_16x16x32_bf16 v[112:115], v[172:175], v[192:195], v[112:115]
	v_mfma_f32_16x16x32_bf16 v[104:107], v[184:187], v[192:195], v[104:107]
	v_mfma_f32_16x16x32_bf16 v[88:91], v[184:187], v[200:203], v[88:91]
	v_mfma_f32_16x16x32_bf16 v[96:99], v[172:175], v[200:203], v[96:99]
	v_mfma_f32_16x16x32_bf16 v[80:83], v[172:175], v[208:211], v[80:83]
	v_mfma_f32_16x16x32_bf16 v[72:75], v[184:187], v[208:211], v[72:75]
	v_mfma_f32_16x16x32_bf16 v[64:67], v[184:187], v[216:219], v[64:67]
	v_mfma_f32_16x16x32_bf16 v[68:71], v[172:175], v[216:219], v[68:71]
	s_setprio 0
	s_barrier
	s_add_i32 s12, s12, s49
	s_add_u32 s98, s44, s30
	s_addc_u32 s99, s45, s31
	s_add_u32 s100, s46, s30
	s_addc_u32 s101, s47, s31
	s_mov_b32 m0, s12
	ds_read_b128 v[188:191], v171 offset:49152
	ds_read_b128 v[192:195], v171 offset:50176
	ds_read_b128 v[196:199], v171 offset:51200
	ds_read_b128 v[200:203], v171 offset:52224
	ds_read_b128 v[204:207], v171 offset:53248
	ds_read_b128 v[208:211], v171 offset:54272
	ds_read_b128 v[212:215], v171 offset:55296
	ds_read_b128 v[216:219], v171 offset:56320
	global_load_lds_dwordx4 v146, s[98:99]
	s_add_i32 m0, s12, 0x2000
	s_add_u32 s40, s44, 0xb0080
	s_addc_u32 s41, s45, 0
	s_add_i32 s12, s13, s49
	global_load_lds_dwordx4 v150, s[98:99]
	s_mov_b32 m0, s12
	s_nop 0
	global_load_lds_dwordx4 v146, s[40:41]
	s_add_i32 m0, s12, 0x2000
	s_nop 0
	global_load_lds_dwordx4 v150, s[40:41]
	s_mov_b32 m0, s59
	s_nop 0
	global_load_lds_dwordx4 v144, s[100:101]
	s_mov_b32 m0, s60
	s_nop 0
	global_load_lds_dwordx4 v148, s[100:101]
	s_waitcnt vmcnt(8)
	s_waitcnt lgkmcnt(0)
	s_barrier
	s_setprio 1
	s_waitcnt lgkmcnt(0)
	v_mfma_f32_16x16x32_bf16 v[60:63], v[128:131], v[188:191], v[60:63]
	v_mfma_f32_16x16x32_bf16 v[56:59], v[136:139], v[188:191], v[56:59]
	v_mfma_f32_16x16x32_bf16 v[44:47], v[136:139], v[196:199], v[44:47]
	v_mfma_f32_16x16x32_bf16 v[48:51], v[128:131], v[196:199], v[48:51]
	v_mfma_f32_16x16x32_bf16 v[36:39], v[128:131], v[204:207], v[36:39]
	v_mfma_f32_16x16x32_bf16 v[28:31], v[136:139], v[204:207], v[28:31]
	v_mfma_f32_16x16x32_bf16 v[12:15], v[136:139], v[212:215], v[12:15]
	v_mfma_f32_16x16x32_bf16 v[20:23], v[128:131], v[212:215], v[20:23]
	v_mfma_f32_16x16x32_bf16 v[60:63], v[132:135], v[192:195], v[60:63]
	v_mfma_f32_16x16x32_bf16 v[56:59], v[140:143], v[192:195], v[56:59]
	v_mfma_f32_16x16x32_bf16 v[44:47], v[140:143], v[200:203], v[44:47]
	v_mfma_f32_16x16x32_bf16 v[48:51], v[132:135], v[200:203], v[48:51]
	v_mfma_f32_16x16x32_bf16 v[36:39], v[132:135], v[208:211], v[36:39]
	v_mfma_f32_16x16x32_bf16 v[28:31], v[140:143], v[208:211], v[28:31]
	v_mfma_f32_16x16x32_bf16 v[12:15], v[140:143], v[216:219], v[12:15]
	v_mfma_f32_16x16x32_bf16 v[20:23], v[132:135], v[216:219], v[20:23]
	s_setprio 0
	s_setprio 1
	v_mfma_f32_16x16x32_bf16 v[52:55], v[162:165], v[188:191], v[52:55]
	v_mfma_f32_16x16x32_bf16 v[40:43], v[176:179], v[188:191], v[40:43]
	v_mfma_f32_16x16x32_bf16 v[24:27], v[176:179], v[196:199], v[24:27]
	v_mfma_f32_16x16x32_bf16 v[32:35], v[162:165], v[196:199], v[32:35]
	v_mfma_f32_16x16x32_bf16 v[16:19], v[162:165], v[204:207], v[16:19]
	v_mfma_f32_16x16x32_bf16 v[8:11], v[176:179], v[204:207], v[8:11]
	v_mfma_f32_16x16x32_bf16 v[0:3], v[176:179], v[212:215], v[0:3]
	v_mfma_f32_16x16x32_bf16 v[4:7], v[162:165], v[212:215], v[4:7]
	v_mfma_f32_16x16x32_bf16 v[52:55], v[172:175], v[192:195], v[52:55]
	v_mfma_f32_16x16x32_bf16 v[40:43], v[184:187], v[192:195], v[40:43]
	v_mfma_f32_16x16x32_bf16 v[24:27], v[184:187], v[200:203], v[24:27]
	v_mfma_f32_16x16x32_bf16 v[32:35], v[172:175], v[200:203], v[32:35]
	v_mfma_f32_16x16x32_bf16 v[16:19], v[172:175], v[208:211], v[16:19]
	v_mfma_f32_16x16x32_bf16 v[8:11], v[184:187], v[208:211], v[8:11]
	v_mfma_f32_16x16x32_bf16 v[0:3], v[184:187], v[216:219], v[0:3]
	v_mfma_f32_16x16x32_bf16 v[4:7], v[172:175], v[216:219], v[4:7]
	s_setprio 0
	s_barrier
	s_add_i32 s74, s74, 2
	s_add_u32 s71, s71, 0x100
	s_addc_u32 s73, s73, 0
	s_cmp_gt_u32 s74, 41
	s_mov_b64 s[40:41], s[42:43]
	s_cbranch_scc0 .LBB0_872
	s_and_b64 vcc, exec, s[34:35]
	s_cbranch_vccz .LBB0_875
	s_barrier

; #define PG8_STAGE(bufoff, gbase, voff) do { _Pragma("unroll") for (int _i = 0; _i < 2; ++_i) \
;         __builtin_amdgcn_global_load_lds((const unsigned*)((const char*)(gbase) + (voff)[_i]), (PG8_LAS unsigned*)(lds + (bufoff) + ldsw + _i * 8192), 16, 0, 0); } while (0)
; #define PG8_LDA(dst, b, h) do { _Pragma("unroll") for (int m = 0; m < 4; ++m) _Pragma("unroll") for (int k = 0; k < 2; ++k) dst[m][k] = *(const PG8_LAS bf16x8*)(lds + PG8_SA(b, h) + aoff + m * 2048 + k * 1024); } while (0)
; #define PG8_LDB(dst, b, h) do { _Pragma("unroll") for (int n = 0; n < 2; ++n) _Pragma("unroll") for (int k = 0; k < 2; ++k) dst[n][k] = *(const PG8_LAS bf16x8*)(lds + PG8_SB(b, h) + boff + n * 2048 + k * 1024); } while (0)
; #define PG8_MMA(ai, bj, At, Bt) do { __builtin_amdgcn_s_setprio(1); _Pragma("unroll") for (int m = 0; m < 4; ++m) _Pragma("unroll") for (int n = 0; n < 2; ++n) _Pragma("unroll") for (int k = 0; k < 2; ++k) \
;         acc[ai][bj][m][n] = __builtin_amdgcn_mfma_f32_16x16x32_bf16(Bt[n][k], At[m][k], acc[ai][bj][m][n], 0, 0, 0); __builtin_amdgcn_s_setprio(0); } while (0)
; #define PG8_WAIT_V(n) asm volatile("s_waitcnt vmcnt(" #n ")" ::: "memory")
; #define PG8_WAIT_L(n) asm volatile("s_waitcnt lgkmcnt(" #n ")" ::: "memory")
; #define PG8_BAR __builtin_amdgcn_s_barrier()
; template <class Epi, class Sched, bool ALIGN_EPI = false, bool SP2 = false>
; __device__ __forceinline__ void gemm_phase(PG8_LAS unsigned char* lds, const Gemm g, const Sched& S, const Epi& E) {
;     ...
;             const char* a2 = last ? nA : cA + (size_t)(t + 2) * kstep; const char* b2 = last ? nB : cB + (size_t)(t + 2) * kstep;
;             const char* a3 = a2 + kstep; const char* b3 = b2 + kstep;
;             if (last && has_next) S.a_ready(nxt);
;             if (last) E.prefetch(lds + 139264, cur, wid, lane);
;             if constexpr (SP2) {
;             PG8_LDB(B0, 0, 0); PG8_LDB(B1, 0, 1); PG8_SCHED; PG8_LDA(At, 0, 0); PG8_STAGE(PG8_SA(1, 1), a1 + hstep, voffA);
;             PG8_WAIT_V(8); PG8_WAIT_L(0); PG8_BAR; PG8_MMA(0, 0, At, B0); PG8_MMA(0, 1, At, B1); PG8_BAR; PG8_SCHED;
;             PG8_LDA(At, 0, 1); PG8_STAGE(PG8_SB(0, 0), b2, voffB); PG8_STAGE(PG8_SB(0, 1), b2 + hstep, voffB); PG8_STAGE(PG8_SA(0, 0), a2, voffA);
;             PG8_WAIT_V(8); PG8_WAIT_L(0); PG8_BAR; PG8_MMA(1, 0, At, B0); PG8_MMA(1, 1, At, B1); PG8_BAR; PG8_SCHED;
.LBB0_960:
	v_add_u32_e32 v130, s89, v169
	ds_read_b128 v[150:153], v130
	ds_read_b128 v[158:161], v130 offset:1024
	ds_read_b128 v[162:165], v130 offset:2048
	ds_read_b128 v[196:199], v130 offset:3072
	v_add_u32_e32 v130, s90, v169
	ds_read_b128 v[200:203], v130
	ds_read_b128 v[204:207], v130 offset:1024
	ds_read_b128 v[208:211], v130 offset:2048
	ds_read_b128 v[212:215], v130 offset:3072
	s_add_u32 s12, s10, 0xfffc0080
	s_addc_u32 s13, s11, -1
	s_and_b64 s[66:67], s[66:67], exec
	s_cselect_b32 s69, s57, s13
	s_cselect_b32 s68, s63, s12
	s_cselect_b32 s67, s55, s71
	s_cselect_b32 s66, s70, s65
	s_add_i32 m0, s75, 0xc000
	ds_read_b128 v[216:219], v191
	ds_read_b128 v[220:223], v191 offset:1024
	ds_read_b128 v[224:227], v191 offset:2048
	ds_read_b128 v[228:231], v191 offset:3072
	ds_read_b128 v[232:235], v191 offset:4096
	ds_read_b128 v[236:239], v191 offset:5120
	ds_read_b128 v[240:243], v191 offset:6144
	ds_read_b128 v[244:247], v191 offset:7168
	global_load_lds_dwordx4 v142, s[10:11]
	s_add_i32 m0, s75, 0xe000
	s_nop 0
	global_load_lds_dwordx4 v140, s[10:11]
	s_waitcnt vmcnt(8)
	s_waitcnt lgkmcnt(0)
	s_barrier
	s_setprio 1
	s_waitcnt lgkmcnt(0)
	v_mfma_f32_16x16x32_bf16 v[124:127], v[150:153], v[216:219], v[124:127]
	v_mfma_f32_16x16x32_bf16 v[120:123], v[162:165], v[216:219], v[120:123]
	v_mfma_f32_16x16x32_bf16 v[104:107], v[162:165], v[224:227], v[104:107]
	v_mfma_f32_16x16x32_bf16 v[112:115], v[150:153], v[224:227], v[112:115]
	v_mfma_f32_16x16x32_bf16 v[100:103], v[150:153], v[232:235], v[100:103]
	v_mfma_f32_16x16x32_bf16 v[96:99], v[162:165], v[232:235], v[96:99]
	v_mfma_f32_16x16x32_bf16 v[72:75], v[162:165], v[240:243], v[72:75]
	v_mfma_f32_16x16x32_bf16 v[80:83], v[150:153], v[240:243], v[80:83]
	v_mfma_f32_16x16x32_bf16 v[124:127], v[158:161], v[220:223], v[124:127]
	v_mfma_f32_16x16x32_bf16 v[120:123], v[196:199], v[220:223], v[120:123]
	v_mfma_f32_16x16x32_bf16 v[104:107], v[196:199], v[228:231], v[104:107]
	v_mfma_f32_16x16x32_bf16 v[112:115], v[158:161], v[228:231], v[112:115]
	v_mfma_f32_16x16x32_bf16 v[100:103], v[158:161], v[236:239], v[100:103]
	v_mfma_f32_16x16x32_bf16 v[96:99], v[196:199], v[236:239], v[96:99]
	v_mfma_f32_16x16x32_bf16 v[72:75], v[196:199], v[244:247], v[72:75]
	v_mfma_f32_16x16x32_bf16 v[80:83], v[158:161], v[244:247], v[80:83]
	s_setprio 0
	s_setprio 1
	v_mfma_f32_16x16x32_bf16 v[116:119], v[200:203], v[216:219], v[116:119]
	v_mfma_f32_16x16x32_bf16 v[108:111], v[208:211], v[216:219], v[108:111]
	v_mfma_f32_16x16x32_bf16 v[88:91], v[208:211], v[224:227], v[88:91]
	v_mfma_f32_16x16x32_bf16 v[92:95], v[200:203], v[224:227], v[92:95]
	v_mfma_f32_16x16x32_bf16 v[84:87], v[200:203], v[232:235], v[84:87]
	v_mfma_f32_16x16x32_bf16 v[76:79], v[208:211], v[232:235], v[76:79]
	v_mfma_f32_16x16x32_bf16 v[64:67], v[208:211], v[240:243], v[64:67]
	v_mfma_f32_16x16x32_bf16 v[68:71], v[200:203], v[240:243], v[68:71]
	v_mfma_f32_16x16x32_bf16 v[116:119], v[204:207], v[220:223], v[116:119]
	v_mfma_f32_16x16x32_bf16 v[108:111], v[212:215], v[220:223], v[108:111]
	v_mfma_f32_16x16x32_bf16 v[88:91], v[212:215], v[228:231], v[88:91]
	v_mfma_f32_16x16x32_bf16 v[92:95], v[204:207], v[228:231], v[92:95]
	v_mfma_f32_16x16x32_bf16 v[84:87], v[204:207], v[236:239], v[84:87]
	v_mfma_f32_16x16x32_bf16 v[76:79], v[212:215], v[236:239], v[76:79]
	v_mfma_f32_16x16x32_bf16 v[64:67], v[212:215], v[244:247], v[64:67]
	v_mfma_f32_16x16x32_bf16 v[68:71], v[204:207], v[244:247], v[68:71]
	s_setprio 0
	s_barrier
	s_add_i32 s12, s89, s74
	s_mov_b32 m0, s12
	ds_read_b128 v[216:219], v191 offset:16384
	ds_read_b128 v[220:223], v191 offset:17408
	ds_read_b128 v[224:227], v191 offset:18432
	ds_read_b128 v[228:231], v191 offset:19456
	ds_read_b128 v[232:235], v191 offset:20480
	ds_read_b128 v[236:239], v191 offset:21504
	ds_read_b128 v[240:243], v191 offset:22528
	ds_read_b128 v[244:247], v191 offset:23552
	global_load_lds_dwordx4 v134, s[66:67]
	s_add_i32 m0, s12, 0x2000
	s_add_u32 vcc_lo, s66, 0x40000
	v_lshl_add_u64 v[154:155], s[66:67], 0, v[138:139]
	s_addc_u32 vcc_hi, s67, 0
	s_add_i32 s12, s90, s74
	global_load_lds_dwordx4 v138, s[66:67]
	v_lshl_add_u64 v[166:167], vcc, 0, v[134:135]
	s_mov_b32 m0, s12
	v_lshl_add_u64 v[248:249], s[68:69], 0, v[136:137]
	global_load_lds_dwordx4 v[166:167], off
	v_lshl_add_u64 v[166:167], vcc, 0, v[138:139]
	s_add_i32 m0, s12, 0x2000
	s_nop 0
	global_load_lds_dwordx4 v[166:167], off
	v_lshl_add_u64 v[166:167], s[68:69], 0, v[132:133]
	s_mov_b32 m0, s75
	s_nop 0
	global_load_lds_dwordx4 v132, s[68:69]
	s_mov_b32 m0, s76
	s_nop 0
	global_load_lds_dwordx4 v136, s[68:69]
	s_waitcnt vmcnt(8)
	s_waitcnt lgkmcnt(0)
	s_barrier
; #define PG8_STAGE(bufoff, gbase, voff) do { _Pragma("unroll") for (int _i = 0; _i < 2; ++_i) \
;         __builtin_amdgcn_global_load_lds((const unsigned*)((const char*)(gbase) + (voff)[_i]), (PG8_LAS unsigned*)(lds + (bufoff) + ldsw + _i * 8192), 16, 0, 0); } while (0)
; #define PG8_LDA(dst, b, h) do { _Pragma("unroll") for (int m = 0; m < 4; ++m) _Pragma("unroll") for (int k = 0; k < 2; ++k) dst[m][k] = *(const PG8_LAS bf16x8*)(lds + PG8_SA(b, h) + aoff + m * 2048 + k * 1024); } while (0)
; #define PG8_LDB(dst, b, h) do { _Pragma("unroll") for (int n = 0; n < 2; ++n) _Pragma("unroll") for (int k = 0; k < 2; ++k) dst[n][k] = *(const PG8_LAS bf16x8*)(lds + PG8_SB(b, h) + boff + n * 2048 + k * 1024); } while (0)
; #define PG8_MMA(ai, bj, At, Bt) do { __builtin_amdgcn_s_setprio(1); _Pragma("unroll") for (int m = 0; m < 4; ++m) _Pragma("unroll") for (int n = 0; n < 2; ++n) _Pragma("unroll") for (int k = 0; k < 2; ++k) \
;         acc[ai][bj][m][n] = __builtin_amdgcn_mfma_f32_16x16x32_bf16(Bt[n][k], At[m][k], acc[ai][bj][m][n], 0, 0, 0); __builtin_amdgcn_s_setprio(0); } while (0)
; #define PG8_WAIT_V(n) asm volatile("s_waitcnt vmcnt(" #n ")" ::: "memory")
; #define PG8_WAIT_L(n) asm volatile("s_waitcnt lgkmcnt(" #n ")" ::: "memory")
; #define PG8_BAR __builtin_amdgcn_s_barrier()
; #define PG8_SCHED __builtin_amdgcn_sched_barrier(0)
; template <class Epi, class Sched, bool ALIGN_EPI = false, bool SP2 = false>
; __device__ __forceinline__ void gemm_phase(PG8_LAS unsigned char* lds, const Gemm g, const Sched& S, const Epi& E) {
;     ...
;             PG8_WAIT_V(8); PG8_WAIT_L(0); PG8_BAR; PG8_MMA(1, 0, At, B0); PG8_MMA(1, 1, At, B1); PG8_BAR; PG8_SCHED;
;             PG8_LDB(B0, 1, 0); PG8_LDB(B1, 1, 1); PG8_SCHED; PG8_LDA(At, 1, 0); PG8_STAGE(PG8_SA(0, 1), a2 + hstep, voffA);
;             PG8_WAIT_V(8); PG8_WAIT_L(0); PG8_BAR; PG8_MMA(0, 0, At, B0); PG8_MMA(0, 1, At, B1); PG8_BAR; PG8_SCHED;
	s_setprio 1
	s_waitcnt lgkmcnt(0)
	v_mfma_f32_16x16x32_bf16 v[60:63], v[150:153], v[216:219], v[60:63]
	v_mfma_f32_16x16x32_bf16 v[56:59], v[162:165], v[216:219], v[56:59]
	v_mfma_f32_16x16x32_bf16 v[40:43], v[162:165], v[224:227], v[40:43]
	v_mfma_f32_16x16x32_bf16 v[48:51], v[150:153], v[224:227], v[48:51]
	v_mfma_f32_16x16x32_bf16 v[36:39], v[150:153], v[232:235], v[36:39]
	v_mfma_f32_16x16x32_bf16 v[32:35], v[162:165], v[232:235], v[32:35]
	v_mfma_f32_16x16x32_bf16 v[16:19], v[162:165], v[240:243], v[16:19]
	v_mfma_f32_16x16x32_bf16 v[20:23], v[150:153], v[240:243], v[20:23]
	v_mfma_f32_16x16x32_bf16 v[60:63], v[158:161], v[220:223], v[60:63]
	v_mfma_f32_16x16x32_bf16 v[56:59], v[196:199], v[220:223], v[56:59]
	v_mfma_f32_16x16x32_bf16 v[40:43], v[196:199], v[228:231], v[40:43]
	v_mfma_f32_16x16x32_bf16 v[48:51], v[158:161], v[228:231], v[48:51]
	v_mfma_f32_16x16x32_bf16 v[36:39], v[158:161], v[236:239], v[36:39]
	v_mfma_f32_16x16x32_bf16 v[32:35], v[196:199], v[236:239], v[32:35]
	v_mfma_f32_16x16x32_bf16 v[16:19], v[196:199], v[244:247], v[16:19]
	v_mfma_f32_16x16x32_bf16 v[20:23], v[158:161], v[244:247], v[20:23]
	s_setprio 0
	s_setprio 1
	v_mfma_f32_16x16x32_bf16 v[52:55], v[200:203], v[216:219], v[52:55]
	v_mfma_f32_16x16x32_bf16 v[44:47], v[208:211], v[216:219], v[44:47]
	v_mfma_f32_16x16x32_bf16 v[24:27], v[208:211], v[224:227], v[24:27]
	v_mfma_f32_16x16x32_bf16 v[28:31], v[200:203], v[224:227], v[28:31]
	v_mfma_f32_16x16x32_bf16 v[12:15], v[200:203], v[232:235], v[12:15]
	v_mfma_f32_16x16x32_bf16 v[8:11], v[208:211], v[232:235], v[8:11]
	v_mfma_f32_16x16x32_bf16 v[0:3], v[208:211], v[240:243], v[0:3]
	v_mfma_f32_16x16x32_bf16 v[4:7], v[200:203], v[240:243], v[4:7]
	v_mfma_f32_16x16x32_bf16 v[52:55], v[204:207], v[220:223], v[52:55]
	v_mfma_f32_16x16x32_bf16 v[44:47], v[212:215], v[220:223], v[44:47]
	v_mfma_f32_16x16x32_bf16 v[24:27], v[212:215], v[228:231], v[24:27]
	v_mfma_f32_16x16x32_bf16 v[28:31], v[204:207], v[228:231], v[28:31]
	v_mfma_f32_16x16x32_bf16 v[12:15], v[204:207], v[236:239], v[12:15]
	v_mfma_f32_16x16x32_bf16 v[8:11], v[212:215], v[236:239], v[8:11]
	v_mfma_f32_16x16x32_bf16 v[0:3], v[212:215], v[244:247], v[0:3]
	v_mfma_f32_16x16x32_bf16 v[4:7], v[204:207], v[244:247], v[4:7]
	s_setprio 0
	s_barrier
	s_add_i32 s12, 0, 0x18000
	v_add_u32_e32 v195, s12, v169
	s_add_i32 s13, 0, 0x1c000
	ds_read_b128 v[150:153], v195
	ds_read_b128 v[158:161], v195 offset:1024
	ds_read_b128 v[162:165], v195 offset:2048
	ds_read_b128 v[196:199], v195 offset:3072
	v_add_u32_e32 v195, s13, v169
	ds_read_b128 v[200:203], v195
	ds_read_b128 v[204:207], v195 offset:1024
	ds_read_b128 v[208:211], v195 offset:2048
	ds_read_b128 v[212:215], v195 offset:3072
	s_add_u32 s68, s68, 0x40000
	s_addc_u32 s69, s69, 0
	s_mov_b32 m0, s77
	ds_read_b128 v[216:219], v191 offset:32768
	ds_read_b128 v[220:223], v191 offset:33792
	ds_read_b128 v[224:227], v191 offset:34816
	ds_read_b128 v[228:231], v191 offset:35840
	ds_read_b128 v[232:235], v191 offset:36864
	ds_read_b128 v[236:239], v191 offset:37888
	ds_read_b128 v[240:243], v191 offset:38912
	ds_read_b128 v[244:247], v191 offset:39936
	global_load_lds_dwordx4 v132, s[68:69]
	s_mov_b32 m0, s78
	s_nop 0
	global_load_lds_dwordx4 v136, s[68:69]
	s_waitcnt vmcnt(8)
	s_waitcnt lgkmcnt(0)
	s_barrier
	s_setprio 1
	s_waitcnt lgkmcnt(0)
	v_mfma_f32_16x16x32_bf16 v[124:127], v[150:153], v[216:219], v[124:127]
	v_mfma_f32_16x16x32_bf16 v[120:123], v[162:165], v[216:219], v[120:123]
	v_mfma_f32_16x16x32_bf16 v[104:107], v[162:165], v[224:227], v[104:107]
	v_mfma_f32_16x16x32_bf16 v[112:115], v[150:153], v[224:227], v[112:115]
	v_mfma_f32_16x16x32_bf16 v[100:103], v[150:153], v[232:235], v[100:103]
	v_mfma_f32_16x16x32_bf16 v[96:99], v[162:165], v[232:235], v[96:99]
	v_mfma_f32_16x16x32_bf16 v[72:75], v[162:165], v[240:243], v[72:75]
	v_mfma_f32_16x16x32_bf16 v[80:83], v[150:153], v[240:243], v[80:83]
	v_mfma_f32_16x16x32_bf16 v[124:127], v[158:161], v[220:223], v[124:127]
	v_mfma_f32_16x16x32_bf16 v[120:123], v[196:199], v[220:223], v[120:123]
	v_mfma_f32_16x16x32_bf16 v[104:107], v[196:199], v[228:231], v[104:107]
	v_mfma_f32_16x16x32_bf16 v[112:115], v[158:161], v[228:231], v[112:115]
	v_mfma_f32_16x16x32_bf16 v[100:103], v[158:161], v[236:239], v[100:103]
	v_mfma_f32_16x16x32_bf16 v[96:99], v[196:199], v[236:239], v[96:99]
	v_mfma_f32_16x16x32_bf16 v[72:75], v[196:199], v[244:247], v[72:75]
	v_mfma_f32_16x16x32_bf16 v[80:83], v[158:161], v[244:247], v[80:83]
	s_setprio 0
	s_setprio 1
	v_mfma_f32_16x16x32_bf16 v[116:119], v[200:203], v[216:219], v[116:119]
	v_mfma_f32_16x16x32_bf16 v[108:111], v[208:211], v[216:219], v[108:111]
	v_mfma_f32_16x16x32_bf16 v[88:91], v[208:211], v[224:227], v[88:91]
	v_mfma_f32_16x16x32_bf16 v[92:95], v[200:203], v[224:227], v[92:95]
	v_mfma_f32_16x16x32_bf16 v[84:87], v[200:203], v[232:235], v[84:87]
	v_mfma_f32_16x16x32_bf16 v[76:79], v[208:211], v[232:235], v[76:79]
	v_mfma_f32_16x16x32_bf16 v[64:67], v[208:211], v[240:243], v[64:67]
	v_mfma_f32_16x16x32_bf16 v[68:71], v[200:203], v[240:243], v[68:71]
	v_mfma_f32_16x16x32_bf16 v[116:119], v[204:207], v[220:223], v[116:119]
	v_mfma_f32_16x16x32_bf16 v[108:111], v[212:215], v[220:223], v[108:111]
	v_mfma_f32_16x16x32_bf16 v[88:91], v[212:215], v[228:231], v[88:91]
	v_mfma_f32_16x16x32_bf16 v[92:95], v[204:207], v[228:231], v[92:95]
	v_mfma_f32_16x16x32_bf16 v[84:87], v[204:207], v[236:239], v[84:87]
	v_mfma_f32_16x16x32_bf16 v[76:79], v[212:215], v[236:239], v[76:79]
	v_mfma_f32_16x16x32_bf16 v[64:67], v[212:215], v[244:247], v[64:67]
	v_mfma_f32_16x16x32_bf16 v[68:71], v[204:207], v[244:247], v[68:71]
	s_setprio 0
	s_barrier
; #define PG8_STAGE(bufoff, gbase, voff) do { _Pragma("unroll") for (int _i = 0; _i < 2; ++_i) \
;         __builtin_amdgcn_global_load_lds((const unsigned*)((const char*)(gbase) + (voff)[_i]), (PG8_LAS unsigned*)(lds + (bufoff) + ldsw + _i * 8192), 16, 0, 0); } while (0)
; #define PG8_LDA(dst, b, h) do { _Pragma("unroll") for (int m = 0; m < 4; ++m) _Pragma("unroll") for (int k = 0; k < 2; ++k) dst[m][k] = *(const PG8_LAS bf16x8*)(lds + PG8_SA(b, h) + aoff + m * 2048 + k * 1024); } while (0)
; #define PG8_MMA(ai, bj, At, Bt) do { __builtin_amdgcn_s_setprio(1); _Pragma("unroll") for (int m = 0; m < 4; ++m) _Pragma("unroll") for (int n = 0; n < 2; ++n) _Pragma("unroll") for (int k = 0; k < 2; ++k) \
;         acc[ai][bj][m][n] = __builtin_amdgcn_mfma_f32_16x16x32_bf16(Bt[n][k], At[m][k], acc[ai][bj][m][n], 0, 0, 0); __builtin_amdgcn_s_setprio(0); } while (0)
; #define PG8_WAIT_V(n) asm volatile("s_waitcnt vmcnt(" #n ")" ::: "memory")
; #define PG8_WAIT_L(n) asm volatile("s_waitcnt lgkmcnt(" #n ")" ::: "memory")
; #define PG8_BAR __builtin_amdgcn_s_barrier()
; #define PG8_SCHED __builtin_amdgcn_sched_barrier(0)
; template <class Epi, class Sched, bool ALIGN_EPI = false, bool SP2 = false>
; __device__ __forceinline__ void gemm_phase(PG8_LAS unsigned char* lds, const Gemm g, const Sched& S, const Epi& E) {
;     ...
;             PG8_LDA(At, 1, 1); PG8_STAGE(PG8_SB(1, 0), b3, voffB); PG8_STAGE(PG8_SB(1, 1), b3 + hstep, voffB); PG8_STAGE(PG8_SA(1, 0), a3, voffA);
;             PG8_WAIT_V(8); PG8_WAIT_L(0); PG8_BAR; PG8_MMA(1, 0, At, B0); PG8_MMA(1, 1, At, B1); PG8_BAR; PG8_SCHED;
	s_add_i32 s12, s12, s74
	s_add_u32 s98, s66, s42
	s_addc_u32 s99, s67, s43
	s_mov_b32 m0, s12
	ds_read_b128 v[216:219], v191 offset:49152
	ds_read_b128 v[220:223], v191 offset:50176
	ds_read_b128 v[224:227], v191 offset:51200
	ds_read_b128 v[228:231], v191 offset:52224
	ds_read_b128 v[232:235], v191 offset:53248
	ds_read_b128 v[236:239], v191 offset:54272
	ds_read_b128 v[240:243], v191 offset:55296
	ds_read_b128 v[244:247], v191 offset:56320
	global_load_lds_dwordx4 v134, s[98:99]
	s_add_i32 m0, s12, 0x2000
	s_add_u32 s66, s66, 0x40080
	v_lshl_add_u64 v[130:131], v[154:155], 0, s[42:43]
	s_addc_u32 s67, s67, 0
	s_add_i32 s12, s13, s74
	global_load_lds_dwordx4 v[130:131], off
	s_mov_b32 m0, s12
	s_nop 0
	global_load_lds_dwordx4 v134, s[66:67]
	s_add_i32 m0, s12, 0x2000
	s_nop 0
	global_load_lds_dwordx4 v138, s[66:67]
	v_lshl_add_u64 v[130:131], v[166:167], 0, s[42:43]
	s_mov_b32 m0, s79
	s_nop 0
	global_load_lds_dwordx4 v[130:131], off
	v_lshl_add_u64 v[130:131], v[248:249], 0, s[42:43]
	s_mov_b32 m0, s80
	s_nop 0
	global_load_lds_dwordx4 v[130:131], off
	s_waitcnt vmcnt(8)
	s_waitcnt lgkmcnt(0)
	s_barrier
	s_setprio 1
	s_waitcnt lgkmcnt(0)
	v_mfma_f32_16x16x32_bf16 v[60:63], v[150:153], v[216:219], v[60:63]
	v_mfma_f32_16x16x32_bf16 v[56:59], v[162:165], v[216:219], v[56:59]
	v_mfma_f32_16x16x32_bf16 v[40:43], v[162:165], v[224:227], v[40:43]
	v_mfma_f32_16x16x32_bf16 v[48:51], v[150:153], v[224:227], v[48:51]
	v_mfma_f32_16x16x32_bf16 v[36:39], v[150:153], v[232:235], v[36:39]
	v_mfma_f32_16x16x32_bf16 v[32:35], v[162:165], v[232:235], v[32:35]
	v_mfma_f32_16x16x32_bf16 v[16:19], v[162:165], v[240:243], v[16:19]
	v_mfma_f32_16x16x32_bf16 v[20:23], v[150:153], v[240:243], v[20:23]
	v_mfma_f32_16x16x32_bf16 v[60:63], v[158:161], v[220:223], v[60:63]
	v_mfma_f32_16x16x32_bf16 v[56:59], v[196:199], v[220:223], v[56:59]
	v_mfma_f32_16x16x32_bf16 v[40:43], v[196:199], v[228:231], v[40:43]
	v_mfma_f32_16x16x32_bf16 v[48:51], v[158:161], v[228:231], v[48:51]
	v_mfma_f32_16x16x32_bf16 v[36:39], v[158:161], v[236:239], v[36:39]
	v_mfma_f32_16x16x32_bf16 v[32:35], v[196:199], v[236:239], v[32:35]
	v_mfma_f32_16x16x32_bf16 v[16:19], v[196:199], v[244:247], v[16:19]
	v_mfma_f32_16x16x32_bf16 v[20:23], v[158:161], v[244:247], v[20:23]
	s_setprio 0
	s_setprio 1
	v_mfma_f32_16x16x32_bf16 v[52:55], v[200:203], v[216:219], v[52:55]
	v_mfma_f32_16x16x32_bf16 v[44:47], v[208:211], v[216:219], v[44:47]
	v_mfma_f32_16x16x32_bf16 v[24:27], v[208:211], v[224:227], v[24:27]
	v_mfma_f32_16x16x32_bf16 v[28:31], v[200:203], v[224:227], v[28:31]
	v_mfma_f32_16x16x32_bf16 v[12:15], v[200:203], v[232:235], v[12:15]
	v_mfma_f32_16x16x32_bf16 v[8:11], v[208:211], v[232:235], v[8:11]
	v_mfma_f32_16x16x32_bf16 v[0:3], v[208:211], v[240:243], v[0:3]
	v_mfma_f32_16x16x32_bf16 v[4:7], v[200:203], v[240:243], v[4:7]
	v_mfma_f32_16x16x32_bf16 v[52:55], v[204:207], v[220:223], v[52:55]
	v_mfma_f32_16x16x32_bf16 v[44:47], v[212:215], v[220:223], v[44:47]
	v_mfma_f32_16x16x32_bf16 v[24:27], v[212:215], v[228:231], v[24:27]
	v_mfma_f32_16x16x32_bf16 v[28:31], v[204:207], v[228:231], v[28:31]
	v_mfma_f32_16x16x32_bf16 v[12:15], v[204:207], v[236:239], v[12:15]
	v_mfma_f32_16x16x32_bf16 v[8:11], v[212:215], v[236:239], v[8:11]
	v_mfma_f32_16x16x32_bf16 v[0:3], v[212:215], v[244:247], v[0:3]
	v_mfma_f32_16x16x32_bf16 v[4:7], v[204:207], v[244:247], v[4:7]
	s_setprio 0
	s_barrier
	s_add_i32 s96, s96, 2
	s_add_u32 s65, s65, 0x100
	s_addc_u32 s71, s71, 0
	s_add_u32 s10, s10, 0x100
	s_addc_u32 s11, s11, 0
	s_cmp_gt_u32 s96, 13
	s_cbranch_scc1 .LBB0_963

; #define PG8_LAS __attribute__((address_space(3)))
;     __device__ __forceinline__ void operator()(f32x4 (&acc)[2][2][4][2], const Unit& u, int wr, int wc, int fr, int fq, PG8_LAS unsigned char* sp) const {
;     ...
;         if (PRE) { const PG8_LAS float* spf = (const PG8_LAS float*)sp; const PG8_LAS float* bp = spf + 256 + wc * 32 + 8 * fq;
;             const f32x4 b00 = *(const PG8_LAS f32x4*)(bp), b01 = *(const PG8_LAS f32x4*)(bp + 4), b10 = *(const PG8_LAS f32x4*)(bp + HALF), b11 = *(const PG8_LAS f32x4*)(bp + HALF + 4);
; #pragma unroll
;             for (int ai = 0; ai < 2; ++ai)
; #pragma unroll
;                 for (int m = 0; m < 4; ++m) { const float rr = __builtin_amdgcn_rsqf(spf[ai * HALF + wr * 64 + m * 16 + fr] * (1.0f / 1024.0f) + EPI_EPS);
;                     acc[ai][0][m][0] = acc[ai][0][m][0] * rr + b00; acc[ai][0][m][1] = acc[ai][0][m][1] * rr + b01; acc[ai][1][m][0] = acc[ai][1][m][0] * rr + b10; acc[ai][1][m][1] = acc[ai][1][m][1] * rr + b11; } }
.LBB0_972:
	ds_read2_b32 v[200:201], v171 offset1:16
	ds_read_b128 v[160:163], v170
	v_mov_b32_e32 v195, 0
	s_andn2_b64 vcc, exec, s[70:71]
	v_mov_b32_e32 v204, 0
	s_waitcnt lgkmcnt(0)
	v_fmamk_f32 v128, v200, 0x3a800000, v192
	v_rsq_f32_e32 v200, v128
	ds_read_b128 v[164:167], v170 offset:16
	ds_read_b128 v[196:199], v170 offset:512
	ds_read_b128 v[128:131], v170 offset:528
	v_mov_b32_e32 v205, 0
	v_mov_b32_e32 v206, 0
	v_pk_fma_f32 v[150:151], v[126:127], v[200:201], v[162:163] op_sel_hi:[1,0,1]
	v_pk_fma_f32 v[152:153], v[124:125], v[200:201], v[160:161] op_sel_hi:[1,0,1]
	s_waitcnt lgkmcnt(0)
	v_pk_fma_f32 v[154:155], v[122:123], v[200:201], v[166:167] op_sel_hi:[1,0,1]
	v_pk_fma_f32 v[158:159], v[120:121], v[200:201], v[164:165] op_sel_hi:[1,0,1]
	v_pk_fma_f32 v[118:119], v[118:119], v[200:201], v[198:199] op_sel_hi:[1,0,1]
	v_fmamk_f32 v120, v201, 0x3a800000, v192
	v_pk_fma_f32 v[126:127], v[116:117], v[200:201], v[196:197] op_sel_hi:[1,0,1]
	v_pk_fma_f32 v[122:123], v[110:111], v[200:201], v[130:131] op_sel_hi:[1,0,1]
	v_pk_fma_f32 v[124:125], v[108:109], v[200:201], v[128:129] op_sel_hi:[1,0,1]
	ds_read2_b32 v[200:201], v171 offset0:32 offset1:48
	v_rsq_f32_e32 v202, v120
	v_mov_b32_e32 v207, 0
	v_mov_b32_e32 v208, 0
	v_mov_b32_e32 v209, 0
	v_pk_fma_f32 v[108:109], v[94:95], v[202:203], v[198:199] op_sel_hi:[1,0,1]
	s_waitcnt lgkmcnt(0)
	v_fmamk_f32 v94, v200, 0x3a800000, v192
	v_rsq_f32_e32 v200, v94
	v_pk_fma_f32 v[120:121], v[112:113], v[202:203], v[160:161] op_sel_hi:[1,0,1]
	v_pk_fma_f32 v[112:113], v[106:107], v[202:203], v[166:167] op_sel_hi:[1,0,1]
	v_pk_fma_f32 v[116:117], v[104:105], v[202:203], v[164:165] op_sel_hi:[1,0,1]
	v_pk_fma_f32 v[110:111], v[92:93], v[202:203], v[196:197] op_sel_hi:[1,0,1]
	v_pk_fma_f32 v[104:105], v[90:91], v[202:203], v[130:131] op_sel_hi:[1,0,1]
	v_pk_fma_f32 v[106:107], v[88:89], v[202:203], v[128:129] op_sel_hi:[1,0,1]
	v_pk_fma_f32 v[102:103], v[102:103], v[200:201], v[162:163] op_sel_hi:[1,0,1]
	v_pk_fma_f32 v[100:101], v[100:101], v[200:201], v[160:161] op_sel_hi:[1,0,1]
	v_pk_fma_f32 v[98:99], v[98:99], v[200:201], v[166:167] op_sel_hi:[1,0,1]
	v_pk_fma_f32 v[96:97], v[96:97], v[200:201], v[164:165] op_sel_hi:[1,0,1]
	v_pk_fma_f32 v[88:89], v[86:87], v[200:201], v[198:199] op_sel_hi:[1,0,1]
	v_fmamk_f32 v86, v201, 0x3a800000, v192
	v_pk_fma_f32 v[94:95], v[84:85], v[200:201], v[196:197] op_sel_hi:[1,0,1]
	v_pk_fma_f32 v[90:91], v[78:79], v[200:201], v[130:131] op_sel_hi:[1,0,1]
	v_pk_fma_f32 v[92:93], v[76:77], v[200:201], v[128:129] op_sel_hi:[1,0,1]
	ds_read2_b32 v[200:201], v171 offset0:128 offset1:144
	v_pk_fma_f32 v[114:115], v[114:115], v[202:203], v[162:163] op_sel_hi:[1,0,1]
	v_rsq_f32_e32 v202, v86
	s_nop 0
	v_pk_fma_f32 v[76:77], v[70:71], v[202:203], v[198:199] op_sel_hi:[1,0,1]
	s_waitcnt lgkmcnt(0)
	v_fmamk_f32 v70, v200, 0x3a800000, v192
	v_rsq_f32_e32 v200, v70
	v_pk_fma_f32 v[86:87], v[80:81], v[202:203], v[160:161] op_sel_hi:[1,0,1]
	v_pk_fma_f32 v[80:81], v[74:75], v[202:203], v[166:167] op_sel_hi:[1,0,1]
	v_pk_fma_f32 v[84:85], v[72:73], v[202:203], v[164:165] op_sel_hi:[1,0,1]
	v_pk_fma_f32 v[78:79], v[68:69], v[202:203], v[196:197] op_sel_hi:[1,0,1]
	v_pk_fma_f32 v[72:73], v[66:67], v[202:203], v[130:131] op_sel_hi:[1,0,1]
	v_pk_fma_f32 v[74:75], v[64:65], v[202:203], v[128:129] op_sel_hi:[1,0,1]
	v_pk_fma_f32 v[66:67], v[62:63], v[200:201], v[162:163] op_sel_hi:[1,0,1]
	v_pk_fma_f32 v[70:71], v[60:61], v[200:201], v[160:161] op_sel_hi:[1,0,1]
	v_pk_fma_f32 v[64:65], v[58:59], v[200:201], v[166:167] op_sel_hi:[1,0,1]
	v_pk_fma_f32 v[68:69], v[56:57], v[200:201], v[164:165] op_sel_hi:[1,0,1]
	v_pk_fma_f32 v[54:55], v[54:55], v[200:201], v[198:199] op_sel_hi:[1,0,1]
	v_fmamk_f32 v56, v201, 0x3a800000, v192
	v_pk_fma_f32 v[62:63], v[52:53], v[200:201], v[196:197] op_sel_hi:[1,0,1]
	v_pk_fma_f32 v[58:59], v[46:47], v[200:201], v[130:131] op_sel_hi:[1,0,1]
	v_pk_fma_f32 v[60:61], v[44:45], v[200:201], v[128:129] op_sel_hi:[1,0,1]
	ds_read2_b32 v[200:201], v171 offset0:160 offset1:176
	v_pk_fma_f32 v[82:83], v[82:83], v[202:203], v[162:163] op_sel_hi:[1,0,1]
	v_rsq_f32_e32 v202, v56
	s_nop 0
	v_pk_fma_f32 v[44:45], v[30:31], v[202:203], v[198:199] op_sel_hi:[1,0,1]
	s_waitcnt lgkmcnt(0)
	v_fmamk_f32 v30, v200, 0x3a800000, v192
	v_rsq_f32_e32 v200, v30
	v_pk_fma_f32 v[56:57], v[48:49], v[202:203], v[160:161] op_sel_hi:[1,0,1]
	v_pk_fma_f32 v[48:49], v[42:43], v[202:203], v[166:167] op_sel_hi:[1,0,1]
	v_pk_fma_f32 v[42:43], v[24:25], v[202:203], v[128:129] op_sel_hi:[1,0,1]
	v_pk_fma_f32 v[24:25], v[14:15], v[200:201], v[198:199] op_sel_hi:[1,0,1]
	v_fmamk_f32 v14, v201, 0x3a800000, v192
	v_pk_fma_f32 v[50:51], v[50:51], v[202:203], v[162:163] op_sel_hi:[1,0,1]
	v_pk_fma_f32 v[52:53], v[40:41], v[202:203], v[164:165] op_sel_hi:[1,0,1]
	v_pk_fma_f32 v[46:47], v[28:29], v[202:203], v[196:197] op_sel_hi:[1,0,1]
	v_pk_fma_f32 v[40:41], v[26:27], v[202:203], v[130:131] op_sel_hi:[1,0,1]
	v_rsq_f32_e32 v202, v14
	v_pk_fma_f32 v[38:39], v[38:39], v[200:201], v[162:163] op_sel_hi:[1,0,1]
	v_pk_fma_f32 v[36:37], v[36:37], v[200:201], v[160:161] op_sel_hi:[1,0,1]
	v_pk_fma_f32 v[34:35], v[34:35], v[200:201], v[166:167] op_sel_hi:[1,0,1]
	v_pk_fma_f32 v[32:33], v[32:33], v[200:201], v[164:165] op_sel_hi:[1,0,1]
	v_pk_fma_f32 v[30:31], v[12:13], v[200:201], v[196:197] op_sel_hi:[1,0,1]
	v_pk_fma_f32 v[26:27], v[10:11], v[200:201], v[130:131] op_sel_hi:[1,0,1]
	v_pk_fma_f32 v[28:29], v[8:9], v[200:201], v[128:129] op_sel_hi:[1,0,1]
	v_pk_fma_f32 v[14:15], v[22:23], v[202:203], v[162:163] op_sel_hi:[1,0,1]
	v_pk_fma_f32 v[20:21], v[20:21], v[202:203], v[160:161] op_sel_hi:[1,0,1]
	v_pk_fma_f32 v[12:13], v[18:19], v[202:203], v[166:167] op_sel_hi:[1,0,1]
	v_pk_fma_f32 v[16:17], v[16:17], v[202:203], v[164:165] op_sel_hi:[1,0,1]
	v_pk_fma_f32 v[6:7], v[6:7], v[202:203], v[198:199] op_sel_hi:[1,0,1]
	v_pk_fma_f32 v[10:11], v[4:5], v[202:203], v[196:197] op_sel_hi:[1,0,1]
	v_pk_fma_f32 v[4:5], v[2:3], v[202:203], v[130:131] op_sel_hi:[1,0,1]
	v_pk_fma_f32 v[8:9], v[0:1], v[202:203], v[128:129] op_sel_hi:[1,0,1]
	v_mov_b32_e32 v196, 0
	v_mov_b32_e32 v197, 0
	v_mov_b32_e32 v198, 0
	v_mov_b32_e32 v199, 0
	v_mov_b32_e32 v200, 0
	v_mov_b32_e32 v201, 0
	v_mov_b32_e32 v202, 0
	v_mov_b32_e32 v203, 0
	v_mov_b32_e32 v22, 0
	s_cbranch_vccnz .LBB0_1006
;     __device__ __forceinline__ void operator()(f32x4 (&acc)[2][2][4][2], const Unit& u, int wr, int wc, int fr, int fq, PG8_LAS unsigned char* sp) const {
;     ...
;                     for (int bj = 0; bj < 2; ++bj) { const f32x4 a = acc[ai][bj][m][0], b = acc[ai][bj][m][1];
;                         float s = (a[0] * a[0] + a[1] * a[1]) + (a[2] * a[2] + a[3] * a[3]) + (b[0] * b[0] + b[1] * b[1]) + (b[2] * b[2] + b[3] * b[3]);
;                         s += __shfl_xor(s, 16); s += __shfl_xor(s, 32); const int idx = (ai * 4 + m) * 2 + bj; part[idx] = s;
;                         if (fq == 0) xch[wid * 256 + idx * 16 + fr] = s; }
	v_pk_mul_f32 v[2:3], v[150:151], v[150:151]
	v_pk_mul_f32 v[18:19], v[152:153], v[152:153]
	v_and_b32_e32 v1, 64, v157
	v_pk_mov_b32 v[22:23], v[18:19], v[2:3] op_sel:[1,0]
	v_mov_b32_e32 v19, v3
	v_pk_add_f32 v[2:3], v[22:23], v[18:19]
	v_pk_mul_f32 v[18:19], v[154:155], v[154:155]
	v_pk_mul_f32 v[22:23], v[158:159], v[158:159]
	v_xor_b32_e32 v0, 16, v157
	v_add_u32_e32 v1, 64, v1
	v_mov_b32_e32 v128, v18
	v_mov_b32_e32 v129, v22
	v_mov_b32_e32 v22, v19
	v_cmp_lt_i32_e32 vcc, v0, v1
	v_pk_add_f32 v[18:19], v[128:129], v[22:23]
	v_add_f32_e32 v2, v2, v3
	v_cndmask_b32_e32 v0, v157, v0, vcc
	v_add_f32_e32 v2, v19, v2
	v_lshlrev_b32_e32 v0, 2, v0
	v_add_f32_e32 v2, v18, v2
	v_mov_b32_e32 v3, v2
	s_nop 1
	v_permlane16_swap_b32_e32 v2, v3
	v_xor_b32_e32 v18, 32, v157
	v_cmp_lt_i32_e32 vcc, v18, v1
	s_waitcnt lgkmcnt(0)
	v_add_f32_e32 v2, v2, v3
	v_cndmask_b32_e32 v1, v157, v18, vcc
	v_lshlrev_b32_e32 v1, 2, v1
	v_mov_b32_e32 v3, v2
	s_nop 1
	v_permlane32_swap_b32_e32 v2, v3
	v_add_f32_e32 v22, v2, v3
	s_and_saveexec_b64 s[70:71], s[6:7]
	ds_write_b32 v172, v22
	s_or_b64 exec, exec, s[70:71]
	v_pk_mul_f32 v[2:3], v[118:119], v[118:119]
	v_pk_mul_f32 v[18:19], v[126:127], v[126:127]
	s_nop 0
	v_pk_mov_b32 v[128:129], v[18:19], v[2:3] op_sel:[1,0]
	v_mov_b32_e32 v19, v3
	v_pk_add_f32 v[2:3], v[128:129], v[18:19]
	v_pk_mul_f32 v[18:19], v[122:123], v[122:123]
	v_pk_mul_f32 v[128:129], v[124:125], v[124:125]
	v_mov_b32_e32 v130, v18
	v_mov_b32_e32 v131, v128
	v_mov_b32_e32 v128, v19
	v_pk_add_f32 v[18:19], v[130:131], v[128:129]
	v_add_f32_e32 v2, v2, v3
	v_add_f32_e32 v2, v19, v2
	v_add_f32_e32 v2, v18, v2
	v_mov_b32_e32 v3, v2
	s_nop 1
	v_permlane16_swap_b32_e32 v2, v3
	v_add_f32_e32 v2, v2, v3
	v_mov_b32_e32 v3, v2
	s_nop 1
	v_permlane32_swap_b32_e32 v2, v3
	v_add_f32_e32 v209, v2, v3
	s_and_saveexec_b64 s[70:71], s[6:7]
	ds_write_b32 v172, v209 offset:64
	s_or_b64 exec, exec, s[70:71]
	v_pk_mul_f32 v[2:3], v[114:115], v[114:115]
	v_pk_mul_f32 v[18:19], v[120:121], v[120:121]
	s_nop 0
	v_pk_mov_b32 v[128:129], v[18:19], v[2:3] op_sel:[1,0]
	v_mov_b32_e32 v19, v3
	v_pk_add_f32 v[2:3], v[128:129], v[18:19]
	v_pk_mul_f32 v[18:19], v[112:113], v[112:113]
	v_pk_mul_f32 v[128:129], v[116:117], v[116:117]
	v_mov_b32_e32 v130, v18
	v_mov_b32_e32 v131, v128
	v_mov_b32_e32 v128, v19
	v_pk_add_f32 v[18:19], v[130:131], v[128:129]
	v_add_f32_e32 v2, v2, v3
	v_add_f32_e32 v2, v19, v2
	v_add_f32_e32 v2, v18, v2
	v_mov_b32_e32 v3, v2
	s_nop 1
	v_permlane16_swap_b32_e32 v2, v3
	v_add_f32_e32 v2, v2, v3
	v_mov_b32_e32 v3, v2
	s_nop 1
	v_permlane32_swap_b32_e32 v2, v3
	v_add_f32_e32 v208, v2, v3
	s_and_saveexec_b64 s[70:71], s[6:7]
	ds_write_b32 v172, v208 offset:128
	s_or_b64 exec, exec, s[70:71]
	v_pk_mul_f32 v[2:3], v[108:109], v[108:109]
	v_pk_mul_f32 v[18:19], v[110:111], v[110:111]
	s_nop 0
	v_pk_mov_b32 v[128:129], v[18:19], v[2:3] op_sel:[1,0]
	v_mov_b32_e32 v19, v3
	v_pk_add_f32 v[2:3], v[128:129], v[18:19]
	v_pk_mul_f32 v[18:19], v[104:105], v[104:105]
	v_pk_mul_f32 v[128:129], v[106:107], v[106:107]
	v_mov_b32_e32 v130, v18
	v_mov_b32_e32 v131, v128
	v_mov_b32_e32 v128, v19
	v_pk_add_f32 v[18:19], v[130:131], v[128:129]
	v_add_f32_e32 v2, v2, v3
	v_add_f32_e32 v2, v19, v2
	v_add_f32_e32 v2, v18, v2
	v_mov_b32_e32 v3, v2
	s_nop 1
	v_permlane16_swap_b32_e32 v2, v3
	v_add_f32_e32 v2, v2, v3
	v_mov_b32_e32 v3, v2
	s_nop 1
	v_permlane32_swap_b32_e32 v2, v3
	v_add_f32_e32 v207, v2, v3
	s_and_saveexec_b64 s[70:71], s[6:7]
	ds_write_b32 v172, v207 offset:192
	s_or_b64 exec, exec, s[70:71]
	v_pk_mul_f32 v[2:3], v[102:103], v[102:103]
	v_pk_mul_f32 v[18:19], v[100:101], v[100:101]
	s_nop 0
	v_pk_mov_b32 v[128:129], v[18:19], v[2:3] op_sel:[1,0]
	v_mov_b32_e32 v19, v3
	v_pk_add_f32 v[2:3], v[128:129], v[18:19]
	v_pk_mul_f32 v[18:19], v[98:99], v[98:99]
	v_pk_mul_f32 v[128:129], v[96:97], v[96:97]
	v_mov_b32_e32 v130, v18
	v_mov_b32_e32 v131, v128
	v_mov_b32_e32 v128, v19
	v_pk_add_f32 v[18:19], v[130:131], v[128:129]
	v_add_f32_e32 v2, v2, v3
	v_add_f32_e32 v2, v19, v2
	v_add_f32_e32 v2, v18, v2
	v_mov_b32_e32 v3, v2
	s_nop 1
	v_permlane16_swap_b32_e32 v2, v3
	v_add_f32_e32 v2, v2, v3
	v_mov_b32_e32 v3, v2
	s_nop 1
	v_permlane32_swap_b32_e32 v2, v3
	v_add_f32_e32 v206, v2, v3
	s_and_saveexec_b64 s[70:71], s[6:7]
	ds_write_b32 v172, v206 offset:256
	s_or_b64 exec, exec, s[70:71]
	v_pk_mul_f32 v[2:3], v[88:89], v[88:89]
	v_pk_mul_f32 v[18:19], v[94:95], v[94:95]
	s_nop 0
	v_pk_mov_b32 v[128:129], v[18:19], v[2:3] op_sel:[1,0]
	v_mov_b32_e32 v19, v3
	v_pk_add_f32 v[2:3], v[128:129], v[18:19]
	v_pk_mul_f32 v[18:19], v[90:91], v[90:91]
	v_pk_mul_f32 v[128:129], v[92:93], v[92:93]
	v_mov_b32_e32 v130, v18
	v_mov_b32_e32 v131, v128
	v_mov_b32_e32 v128, v19
	v_pk_add_f32 v[18:19], v[130:131], v[128:129]
	v_add_f32_e32 v2, v2, v3
	v_add_f32_e32 v2, v19, v2
	v_add_f32_e32 v2, v18, v2
	v_mov_b32_e32 v3, v2
	s_nop 1
	v_permlane16_swap_b32_e32 v2, v3
	v_add_f32_e32 v2, v2, v3
	v_mov_b32_e32 v3, v2
	s_nop 1
	v_permlane32_swap_b32_e32 v2, v3
	v_add_f32_e32 v205, v2, v3
	s_and_saveexec_b64 s[70:71], s[6:7]
	ds_write_b32 v172, v205 offset:320
	s_or_b64 exec, exec, s[70:71]
	v_pk_mul_f32 v[2:3], v[82:83], v[82:83]
	v_pk_mul_f32 v[18:19], v[86:87], v[86:87]
	s_nop 0
	v_pk_mov_b32 v[128:129], v[18:19], v[2:3] op_sel:[1,0]
	v_mov_b32_e32 v19, v3
	v_pk_add_f32 v[2:3], v[128:129], v[18:19]
	v_pk_mul_f32 v[18:19], v[80:81], v[80:81]
	v_pk_mul_f32 v[128:129], v[84:85], v[84:85]
	v_mov_b32_e32 v130, v18
	v_mov_b32_e32 v131, v128
	v_mov_b32_e32 v128, v19
	v_pk_add_f32 v[18:19], v[130:131], v[128:129]
	v_add_f32_e32 v2, v2, v3
	v_add_f32_e32 v2, v19, v2
	v_add_f32_e32 v2, v18, v2
;     __device__ __forceinline__ void operator()(f32x4 (&acc)[2][2][4][2], const Unit& u, int wr, int wc, int fr, int fq, PG8_LAS unsigned char* sp) const {
;     ...
;                     for (int bj = 0; bj < 2; ++bj) { const f32x4 a = acc[ai][bj][m][0], b = acc[ai][bj][m][1];
;                         float s = (a[0] * a[0] + a[1] * a[1]) + (a[2] * a[2] + a[3] * a[3]) + (b[0] * b[0] + b[1] * b[1]) + (b[2] * b[2] + b[3] * b[3]);
;                         s += __shfl_xor(s, 16); s += __shfl_xor(s, 32); const int idx = (ai * 4 + m) * 2 + bj; part[idx] = s;
;                         if (fq == 0) xch[wid * 256 + idx * 16 + fr] = s; }
	v_mov_b32_e32 v3, v2
	s_nop 1
	v_permlane16_swap_b32_e32 v2, v3
	v_add_f32_e32 v2, v2, v3
	v_mov_b32_e32 v3, v2
	s_nop 1
	v_permlane32_swap_b32_e32 v2, v3
	v_add_f32_e32 v204, v2, v3
	s_and_saveexec_b64 s[70:71], s[6:7]
	ds_write_b32 v172, v204 offset:384
	s_or_b64 exec, exec, s[70:71]
	v_pk_mul_f32 v[2:3], v[76:77], v[76:77]
	v_pk_mul_f32 v[18:19], v[78:79], v[78:79]
	s_nop 0
	v_pk_mov_b32 v[128:129], v[18:19], v[2:3] op_sel:[1,0]
	v_mov_b32_e32 v19, v3
	v_pk_add_f32 v[2:3], v[128:129], v[18:19]
	v_pk_mul_f32 v[18:19], v[72:73], v[72:73]
	v_pk_mul_f32 v[128:129], v[74:75], v[74:75]
	v_mov_b32_e32 v130, v18
	v_mov_b32_e32 v131, v128
	v_mov_b32_e32 v128, v19
	v_pk_add_f32 v[18:19], v[130:131], v[128:129]
	v_add_f32_e32 v2, v2, v3
	v_add_f32_e32 v2, v19, v2
	v_add_f32_e32 v2, v18, v2
	v_mov_b32_e32 v3, v2
	s_nop 1
	v_permlane16_swap_b32_e32 v2, v3
	v_add_f32_e32 v2, v2, v3
	v_mov_b32_e32 v3, v2
	s_nop 1
	v_permlane32_swap_b32_e32 v2, v3
	v_add_f32_e32 v203, v2, v3
	s_and_saveexec_b64 s[70:71], s[6:7]
	ds_write_b32 v172, v203 offset:448
	s_or_b64 exec, exec, s[70:71]
	v_pk_mul_f32 v[2:3], v[66:67], v[66:67]
	v_pk_mul_f32 v[18:19], v[70:71], v[70:71]
	s_nop 0
	v_pk_mov_b32 v[128:129], v[18:19], v[2:3] op_sel:[1,0]
	v_mov_b32_e32 v19, v3
	v_pk_add_f32 v[2:3], v[128:129], v[18:19]
	v_pk_mul_f32 v[18:19], v[64:65], v[64:65]
	v_pk_mul_f32 v[128:129], v[68:69], v[68:69]
	v_mov_b32_e32 v130, v18
	v_mov_b32_e32 v131, v128
	v_mov_b32_e32 v128, v19
	v_pk_add_f32 v[18:19], v[130:131], v[128:129]
	v_add_f32_e32 v2, v2, v3
	v_add_f32_e32 v2, v19, v2
	v_add_f32_e32 v2, v18, v2
	v_mov_b32_e32 v3, v2
	s_nop 1
	v_permlane16_swap_b32_e32 v2, v3
	v_add_f32_e32 v2, v2, v3
	v_mov_b32_e32 v3, v2
	s_nop 1
	v_permlane32_swap_b32_e32 v2, v3
	v_add_f32_e32 v202, v2, v3
	s_and_saveexec_b64 s[70:71], s[6:7]
	ds_write_b32 v172, v202 offset:512
	s_or_b64 exec, exec, s[70:71]
	v_pk_mul_f32 v[2:3], v[54:55], v[54:55]
	v_pk_mul_f32 v[18:19], v[62:63], v[62:63]
	s_nop 0
	v_pk_mov_b32 v[128:129], v[18:19], v[2:3] op_sel:[1,0]
	v_mov_b32_e32 v19, v3
	v_pk_add_f32 v[2:3], v[128:129], v[18:19]
	v_pk_mul_f32 v[18:19], v[58:59], v[58:59]
	v_pk_mul_f32 v[128:129], v[60:61], v[60:61]
	v_mov_b32_e32 v130, v18
	v_mov_b32_e32 v131, v128
	v_mov_b32_e32 v128, v19
	v_pk_add_f32 v[18:19], v[130:131], v[128:129]
	v_add_f32_e32 v2, v2, v3
	v_add_f32_e32 v2, v19, v2
	v_add_f32_e32 v2, v18, v2
	v_mov_b32_e32 v3, v2
	s_nop 1
	v_permlane16_swap_b32_e32 v2, v3
	v_add_f32_e32 v2, v2, v3
	v_mov_b32_e32 v3, v2
	s_nop 1
	v_permlane32_swap_b32_e32 v2, v3
	v_add_f32_e32 v201, v2, v3
	s_and_saveexec_b64 s[70:71], s[6:7]
	ds_write_b32 v172, v201 offset:576
	s_or_b64 exec, exec, s[70:71]
	v_pk_mul_f32 v[2:3], v[50:51], v[50:51]
	v_pk_mul_f32 v[18:19], v[56:57], v[56:57]
	s_nop 0
	v_pk_mov_b32 v[128:129], v[18:19], v[2:3] op_sel:[1,0]
	v_mov_b32_e32 v19, v3
	v_pk_add_f32 v[2:3], v[128:129], v[18:19]
	v_pk_mul_f32 v[18:19], v[48:49], v[48:49]
	v_pk_mul_f32 v[128:129], v[52:53], v[52:53]
	v_mov_b32_e32 v130, v18
	v_mov_b32_e32 v131, v128
	v_mov_b32_e32 v128, v19
	v_pk_add_f32 v[18:19], v[130:131], v[128:129]
	v_add_f32_e32 v2, v2, v3
	v_add_f32_e32 v2, v19, v2
	v_add_f32_e32 v2, v18, v2
	v_mov_b32_e32 v3, v2
	s_nop 1
	v_permlane16_swap_b32_e32 v2, v3
	v_add_f32_e32 v2, v2, v3
	v_mov_b32_e32 v3, v2
	s_nop 1
	v_permlane32_swap_b32_e32 v2, v3
	v_add_f32_e32 v200, v2, v3
	s_and_saveexec_b64 s[70:71], s[6:7]
	ds_write_b32 v172, v200 offset:640
	s_or_b64 exec, exec, s[70:71]
	v_pk_mul_f32 v[2:3], v[44:45], v[44:45]
	v_pk_mul_f32 v[18:19], v[46:47], v[46:47]
	s_nop 0
	v_pk_mov_b32 v[128:129], v[18:19], v[2:3] op_sel:[1,0]
	v_mov_b32_e32 v19, v3
	v_pk_add_f32 v[2:3], v[128:129], v[18:19]
	v_pk_mul_f32 v[18:19], v[40:41], v[40:41]
;     __device__ __forceinline__ void operator()(f32x4 (&acc)[2][2][4][2], const Unit& u, int wr, int wc, int fr, int fq, PG8_LAS unsigned char* sp) const {
;     ...
;                     for (int bj = 0; bj < 2; ++bj) { const f32x4 a = acc[ai][bj][m][0], b = acc[ai][bj][m][1];
;                         float s = (a[0] * a[0] + a[1] * a[1]) + (a[2] * a[2] + a[3] * a[3]) + (b[0] * b[0] + b[1] * b[1]) + (b[2] * b[2] + b[3] * b[3]);
;                         s += __shfl_xor(s, 16); s += __shfl_xor(s, 32); const int idx = (ai * 4 + m) * 2 + bj; part[idx] = s;
;                         if (fq == 0) xch[wid * 256 + idx * 16 + fr] = s; }
	v_pk_mul_f32 v[128:129], v[42:43], v[42:43]
	v_mov_b32_e32 v130, v18
	v_mov_b32_e32 v131, v128
	v_mov_b32_e32 v128, v19
	v_pk_add_f32 v[18:19], v[130:131], v[128:129]
	v_add_f32_e32 v2, v2, v3
	v_add_f32_e32 v2, v19, v2
	v_add_f32_e32 v2, v18, v2
	v_mov_b32_e32 v3, v2
	s_nop 1
	v_permlane16_swap_b32_e32 v2, v3
	v_add_f32_e32 v2, v2, v3
	v_mov_b32_e32 v3, v2
	s_nop 1
	v_permlane32_swap_b32_e32 v2, v3
	v_add_f32_e32 v199, v2, v3
	s_and_saveexec_b64 s[70:71], s[6:7]
	ds_write_b32 v172, v199 offset:704
	s_or_b64 exec, exec, s[70:71]
	v_pk_mul_f32 v[2:3], v[38:39], v[38:39]
	v_pk_mul_f32 v[18:19], v[36:37], v[36:37]
	s_nop 0
	v_pk_mov_b32 v[128:129], v[18:19], v[2:3] op_sel:[1,0]
	v_mov_b32_e32 v19, v3
	v_pk_add_f32 v[2:3], v[128:129], v[18:19]
	v_pk_mul_f32 v[18:19], v[34:35], v[34:35]
	v_pk_mul_f32 v[128:129], v[32:33], v[32:33]
	v_mov_b32_e32 v130, v18
	v_mov_b32_e32 v131, v128
	v_mov_b32_e32 v128, v19
	v_pk_add_f32 v[18:19], v[130:131], v[128:129]
	v_add_f32_e32 v2, v2, v3
	v_add_f32_e32 v2, v19, v2
	v_add_f32_e32 v2, v18, v2
	v_mov_b32_e32 v3, v2
	s_nop 1
	v_permlane16_swap_b32_e32 v2, v3
	v_add_f32_e32 v2, v2, v3
	v_mov_b32_e32 v3, v2
	s_nop 1
	v_permlane32_swap_b32_e32 v2, v3
	v_add_f32_e32 v198, v2, v3
	s_and_saveexec_b64 s[70:71], s[6:7]
	ds_write_b32 v172, v198 offset:768
	s_or_b64 exec, exec, s[70:71]
	v_pk_mul_f32 v[2:3], v[24:25], v[24:25]
	v_pk_mul_f32 v[18:19], v[30:31], v[30:31]
	s_nop 0
	v_pk_mov_b32 v[128:129], v[18:19], v[2:3] op_sel:[1,0]
	v_mov_b32_e32 v19, v3
	v_pk_add_f32 v[2:3], v[128:129], v[18:19]
	v_pk_mul_f32 v[18:19], v[26:27], v[26:27]
	v_pk_mul_f32 v[128:129], v[28:29], v[28:29]
	v_mov_b32_e32 v130, v18
	v_mov_b32_e32 v131, v128
	v_mov_b32_e32 v128, v19
	v_pk_add_f32 v[18:19], v[130:131], v[128:129]
	v_add_f32_e32 v2, v2, v3
	v_add_f32_e32 v2, v19, v2
	v_add_f32_e32 v2, v18, v2
	v_mov_b32_e32 v3, v2
	s_nop 1
	v_permlane16_swap_b32_e32 v2, v3
	v_add_f32_e32 v2, v2, v3
	v_mov_b32_e32 v3, v2
	s_nop 1
	v_permlane32_swap_b32_e32 v2, v3
	v_add_f32_e32 v197, v2, v3
	s_and_saveexec_b64 s[70:71], s[6:7]
	ds_write_b32 v172, v197 offset:832
	s_or_b64 exec, exec, s[70:71]
	v_pk_mul_f32 v[2:3], v[14:15], v[14:15]
	v_pk_mul_f32 v[18:19], v[20:21], v[20:21]
	s_nop 0
	v_pk_mov_b32 v[128:129], v[18:19], v[2:3] op_sel:[1,0]
	v_mov_b32_e32 v19, v3
	v_pk_add_f32 v[2:3], v[128:129], v[18:19]
	v_pk_mul_f32 v[18:19], v[12:13], v[12:13]
	v_pk_mul_f32 v[128:129], v[16:17], v[16:17]
	v_mov_b32_e32 v130, v18
	v_mov_b32_e32 v131, v128
	v_mov_b32_e32 v128, v19
	v_pk_add_f32 v[18:19], v[130:131], v[128:129]
	v_add_f32_e32 v2, v2, v3
	v_add_f32_e32 v2, v19, v2
	v_add_f32_e32 v2, v18, v2
	v_mov_b32_e32 v3, v2
	s_nop 1
	v_permlane16_swap_b32_e32 v2, v3
	v_add_f32_e32 v2, v2, v3
	v_mov_b32_e32 v3, v2
	s_nop 1
	v_permlane32_swap_b32_e32 v2, v3
	v_add_f32_e32 v196, v2, v3
	s_and_saveexec_b64 s[70:71], s[6:7]
	ds_write_b32 v172, v196 offset:896
	s_or_b64 exec, exec, s[70:71]
	v_pk_mul_f32 v[2:3], v[6:7], v[6:7]
	v_pk_mul_f32 v[18:19], v[10:11], v[10:11]
	s_nop 0
	v_pk_mov_b32 v[128:129], v[18:19], v[2:3] op_sel:[1,0]
	v_mov_b32_e32 v19, v3
	v_pk_add_f32 v[2:3], v[128:129], v[18:19]
	v_pk_mul_f32 v[18:19], v[4:5], v[4:5]
	v_pk_mul_f32 v[128:129], v[8:9], v[8:9]
	v_mov_b32_e32 v130, v18
	v_mov_b32_e32 v131, v128
	v_mov_b32_e32 v128, v19
	v_pk_add_f32 v[18:19], v[130:131], v[128:129]
	v_add_f32_e32 v2, v2, v3
	v_add_f32_e32 v2, v19, v2
	v_add_f32_e32 v2, v18, v2
	v_mov_b32_e32 v0, v2
	s_nop 1
	v_permlane16_swap_b32_e32 v2, v0
	v_add_f32_e32 v0, v2, v0
	v_mov_b32_e32 v1, v0
	s_nop 1
	v_permlane32_swap_b32_e32 v0, v1
	v_add_f32_e32 v195, v0, v1
	s_and_saveexec_b64 s[70:71], s[6:7]
	ds_write_b32 v172, v195 offset:960
	s_or_b64 exec, exec, s[70:71]

; #define PG8_STAGE(bufoff, gbase, voff) do { _Pragma("unroll") for (int _i = 0; _i < 2; ++_i) \
;         __builtin_amdgcn_global_load_lds((const unsigned*)((const char*)(gbase) + (voff)[_i]), (PG8_LAS unsigned*)(lds + (bufoff) + ldsw + _i * 8192), 16, 0, 0); } while (0)
; #define PG8_LDA(dst, b, h) do { _Pragma("unroll") for (int m = 0; m < 4; ++m) _Pragma("unroll") for (int k = 0; k < 2; ++k) dst[m][k] = *(const PG8_LAS bf16x8*)(lds + PG8_SA(b, h) + aoff + m * 2048 + k * 1024); } while (0)
; #define PG8_LDB(dst, b, h) do { _Pragma("unroll") for (int n = 0; n < 2; ++n) _Pragma("unroll") for (int k = 0; k < 2; ++k) dst[n][k] = *(const PG8_LAS bf16x8*)(lds + PG8_SB(b, h) + boff + n * 2048 + k * 1024); } while (0)
; #define PG8_MMA(ai, bj, At, Bt) do { __builtin_amdgcn_s_setprio(1); _Pragma("unroll") for (int m = 0; m < 4; ++m) _Pragma("unroll") for (int n = 0; n < 2; ++n) _Pragma("unroll") for (int k = 0; k < 2; ++k) \
;         acc[ai][bj][m][n] = __builtin_amdgcn_mfma_f32_16x16x32_bf16(Bt[n][k], At[m][k], acc[ai][bj][m][n], 0, 0, 0); __builtin_amdgcn_s_setprio(0); } while (0)
; #define PG8_WAIT_V(n) asm volatile("s_waitcnt vmcnt(" #n ")" ::: "memory")
; #define PG8_WAIT_L(n) asm volatile("s_waitcnt lgkmcnt(" #n ")" ::: "memory")
; #define PG8_BAR __builtin_amdgcn_s_barrier()
; template <class Epi, class Sched, bool ALIGN_EPI = false, bool SP2 = false>
; __device__ __forceinline__ void gemm_phase(PG8_LAS unsigned char* lds, const Gemm g, const Sched& S, const Epi& E) {
;     ...
;             const char* a2 = last ? nA : cA + (size_t)(t + 2) * kstep; const char* b2 = last ? nB : cB + (size_t)(t + 2) * kstep;
;             const char* a3 = a2 + kstep; const char* b3 = b2 + kstep;
;             if (last && has_next) S.a_ready(nxt);
;             if (last) E.prefetch(lds + 139264, cur, wid, lane);
;             if constexpr (SP2) {
;             PG8_LDB(B0, 0, 0); PG8_LDB(B1, 0, 1); PG8_SCHED; PG8_LDA(At, 0, 0); PG8_STAGE(PG8_SA(1, 1), a1 + hstep, voffA);
;             PG8_WAIT_V(8); PG8_WAIT_L(0); PG8_BAR; PG8_MMA(0, 0, At, B0); PG8_MMA(0, 1, At, B1); PG8_BAR; PG8_SCHED;
;             PG8_LDA(At, 0, 1); PG8_STAGE(PG8_SB(0, 0), b2, voffB); PG8_STAGE(PG8_SB(0, 1), b2 + hstep, voffB); PG8_STAGE(PG8_SA(0, 0), a2, voffA);
;             PG8_WAIT_V(8); PG8_WAIT_L(0); PG8_BAR; PG8_MMA(1, 0, At, B0); PG8_MMA(1, 1, At, B1); PG8_BAR; PG8_SCHED;
.LBB0_1272:
	ds_read_b128 v[128:131], v167
	ds_read_b128 v[132:135], v167 offset:1024
	ds_read_b128 v[136:139], v167 offset:2048
	ds_read_b128 v[140:143], v167 offset:3072
	ds_read_b128 v[160:163], v168
	ds_read_b128 v[170:173], v168 offset:1024
	ds_read_b128 v[174:177], v168 offset:2048
	ds_read_b128 v[178:181], v168 offset:3072
	s_add_u32 s12, s50, 0xfffc0080
	s_addc_u32 s13, s51, -1
	s_cmp_eq_u32 s79, 12
	s_cselect_b32 s55, s41, s13
	s_cselect_b32 s54, s47, s12
	s_cselect_b32 s53, s39, s78
	s_cselect_b32 s52, s49, s77
	s_add_i32 m0, s60, 0xc000
	ds_read_b128 v[188:191], v169
	ds_read_b128 v[192:195], v169 offset:1024
	ds_read_b128 v[196:199], v169 offset:2048
	ds_read_b128 v[200:203], v169 offset:3072
	ds_read_b128 v[204:207], v169 offset:4096
	ds_read_b128 v[208:211], v169 offset:5120
	ds_read_b128 v[212:215], v169 offset:6144
	ds_read_b128 v[216:219], v169 offset:7168
	global_load_lds_dwordx4 v154, s[50:51]
	s_add_i32 m0, s60, 0xe000
	s_nop 0
	global_load_lds_dwordx4 v152, s[50:51]
	s_waitcnt vmcnt(8)
	s_waitcnt lgkmcnt(0)
	s_barrier
	s_setprio 1
	s_waitcnt lgkmcnt(0)
	v_mfma_f32_16x16x32_bf16 v[124:127], v[128:131], v[188:191], v[124:127]
	v_mfma_f32_16x16x32_bf16 v[120:123], v[136:139], v[188:191], v[120:123]
	v_mfma_f32_16x16x32_bf16 v[108:111], v[136:139], v[196:199], v[108:111]
	v_mfma_f32_16x16x32_bf16 v[116:119], v[128:131], v[196:199], v[116:119]
	v_mfma_f32_16x16x32_bf16 v[100:103], v[128:131], v[204:207], v[100:103]
	v_mfma_f32_16x16x32_bf16 v[92:95], v[136:139], v[204:207], v[92:95]
	v_mfma_f32_16x16x32_bf16 v[76:79], v[136:139], v[212:215], v[76:79]
	v_mfma_f32_16x16x32_bf16 v[84:87], v[128:131], v[212:215], v[84:87]
	v_mfma_f32_16x16x32_bf16 v[124:127], v[132:135], v[192:195], v[124:127]
	v_mfma_f32_16x16x32_bf16 v[120:123], v[140:143], v[192:195], v[120:123]
	v_mfma_f32_16x16x32_bf16 v[108:111], v[140:143], v[200:203], v[108:111]
	v_mfma_f32_16x16x32_bf16 v[116:119], v[132:135], v[200:203], v[116:119]
	v_mfma_f32_16x16x32_bf16 v[100:103], v[132:135], v[208:211], v[100:103]
	v_mfma_f32_16x16x32_bf16 v[92:95], v[140:143], v[208:211], v[92:95]
	v_mfma_f32_16x16x32_bf16 v[76:79], v[140:143], v[216:219], v[76:79]
	v_mfma_f32_16x16x32_bf16 v[84:87], v[132:135], v[216:219], v[84:87]
	s_setprio 0
	s_setprio 1
	v_mfma_f32_16x16x32_bf16 v[112:115], v[160:163], v[188:191], v[112:115]
	v_mfma_f32_16x16x32_bf16 v[104:107], v[174:177], v[188:191], v[104:107]
	v_mfma_f32_16x16x32_bf16 v[88:91], v[174:177], v[196:199], v[88:91]
	v_mfma_f32_16x16x32_bf16 v[96:99], v[160:163], v[196:199], v[96:99]
	v_mfma_f32_16x16x32_bf16 v[80:83], v[160:163], v[204:207], v[80:83]
	v_mfma_f32_16x16x32_bf16 v[72:75], v[174:177], v[204:207], v[72:75]
	v_mfma_f32_16x16x32_bf16 v[64:67], v[174:177], v[212:215], v[64:67]
	v_mfma_f32_16x16x32_bf16 v[68:71], v[160:163], v[212:215], v[68:71]
	v_mfma_f32_16x16x32_bf16 v[112:115], v[170:173], v[192:195], v[112:115]
	v_mfma_f32_16x16x32_bf16 v[104:107], v[178:181], v[192:195], v[104:107]
	v_mfma_f32_16x16x32_bf16 v[88:91], v[178:181], v[200:203], v[88:91]
	v_mfma_f32_16x16x32_bf16 v[96:99], v[170:173], v[200:203], v[96:99]
	v_mfma_f32_16x16x32_bf16 v[80:83], v[170:173], v[208:211], v[80:83]
	v_mfma_f32_16x16x32_bf16 v[72:75], v[178:181], v[208:211], v[72:75]
	v_mfma_f32_16x16x32_bf16 v[64:67], v[178:181], v[216:219], v[64:67]
	v_mfma_f32_16x16x32_bf16 v[68:71], v[170:173], v[216:219], v[68:71]
	s_setprio 0
	s_barrier
	s_add_i32 s12, s75, s59
	s_mov_b32 m0, s12
	ds_read_b128 v[188:191], v169 offset:16384
	ds_read_b128 v[192:195], v169 offset:17408
	ds_read_b128 v[196:199], v169 offset:18432
	ds_read_b128 v[200:203], v169 offset:19456
	ds_read_b128 v[204:207], v169 offset:20480
	ds_read_b128 v[208:211], v169 offset:21504
	ds_read_b128 v[212:215], v169 offset:22528
	ds_read_b128 v[216:219], v169 offset:23552
	global_load_lds_dwordx4 v146, s[52:53]
	s_add_i32 m0, s12, 0x2000
	s_add_u32 s80, s52, 0x40000
	v_lshl_add_u64 v[220:221], s[52:53], 0, v[150:151]
	s_addc_u32 s81, s53, 0
	s_add_i32 s12, s76, s59
	global_load_lds_dwordx4 v150, s[52:53]
	s_mov_b32 m0, s12
	v_lshl_add_u64 v[224:225], s[54:55], 0, v[148:149]
	global_load_lds_dwordx4 v146, s[80:81]
	s_add_i32 m0, s12, 0x2000
	s_nop 0
	global_load_lds_dwordx4 v150, s[80:81]
	v_lshl_add_u64 v[222:223], s[54:55], 0, v[144:145]
	s_mov_b32 m0, s60
	s_nop 0
	global_load_lds_dwordx4 v144, s[54:55]
	s_mov_b32 m0, s61
	s_nop 0
	global_load_lds_dwordx4 v148, s[54:55]
	s_waitcnt vmcnt(8)
	s_waitcnt lgkmcnt(0)
	s_barrier
	s_setprio 1
	s_waitcnt lgkmcnt(0)
	v_mfma_f32_16x16x32_bf16 v[60:63], v[128:131], v[188:191], v[60:63]
	v_mfma_f32_16x16x32_bf16 v[56:59], v[136:139], v[188:191], v[56:59]
	v_mfma_f32_16x16x32_bf16 v[44:47], v[136:139], v[196:199], v[44:47]
	v_mfma_f32_16x16x32_bf16 v[48:51], v[128:131], v[196:199], v[48:51]
	v_mfma_f32_16x16x32_bf16 v[36:39], v[128:131], v[204:207], v[36:39]
	v_mfma_f32_16x16x32_bf16 v[28:31], v[136:139], v[204:207], v[28:31]
	v_mfma_f32_16x16x32_bf16 v[12:15], v[136:139], v[212:215], v[12:15]
	v_mfma_f32_16x16x32_bf16 v[20:23], v[128:131], v[212:215], v[20:23]
	v_mfma_f32_16x16x32_bf16 v[60:63], v[132:135], v[192:195], v[60:63]
	v_mfma_f32_16x16x32_bf16 v[56:59], v[140:143], v[192:195], v[56:59]
	v_mfma_f32_16x16x32_bf16 v[44:47], v[140:143], v[200:203], v[44:47]
	v_mfma_f32_16x16x32_bf16 v[48:51], v[132:135], v[200:203], v[48:51]
	v_mfma_f32_16x16x32_bf16 v[36:39], v[132:135], v[208:211], v[36:39]
	v_mfma_f32_16x16x32_bf16 v[28:31], v[140:143], v[208:211], v[28:31]
	v_mfma_f32_16x16x32_bf16 v[12:15], v[140:143], v[216:219], v[12:15]
	v_mfma_f32_16x16x32_bf16 v[20:23], v[132:135], v[216:219], v[20:23]
	s_setprio 0
	s_setprio 1
	v_mfma_f32_16x16x32_bf16 v[52:55], v[160:163], v[188:191], v[52:55]
	v_mfma_f32_16x16x32_bf16 v[40:43], v[174:177], v[188:191], v[40:43]
	v_mfma_f32_16x16x32_bf16 v[24:27], v[174:177], v[196:199], v[24:27]
	v_mfma_f32_16x16x32_bf16 v[32:35], v[160:163], v[196:199], v[32:35]
	v_mfma_f32_16x16x32_bf16 v[16:19], v[160:163], v[204:207], v[16:19]
	v_mfma_f32_16x16x32_bf16 v[8:11], v[174:177], v[204:207], v[8:11]
	v_mfma_f32_16x16x32_bf16 v[0:3], v[174:177], v[212:215], v[0:3]
	v_mfma_f32_16x16x32_bf16 v[4:7], v[160:163], v[212:215], v[4:7]
	v_mfma_f32_16x16x32_bf16 v[52:55], v[170:173], v[192:195], v[52:55]
	v_mfma_f32_16x16x32_bf16 v[40:43], v[178:181], v[192:195], v[40:43]
	v_mfma_f32_16x16x32_bf16 v[24:27], v[178:181], v[200:203], v[24:27]
	v_mfma_f32_16x16x32_bf16 v[32:35], v[170:173], v[200:203], v[32:35]
	v_mfma_f32_16x16x32_bf16 v[16:19], v[170:173], v[208:211], v[16:19]
	v_mfma_f32_16x16x32_bf16 v[8:11], v[178:181], v[208:211], v[8:11]
	v_mfma_f32_16x16x32_bf16 v[0:3], v[178:181], v[216:219], v[0:3]
	v_mfma_f32_16x16x32_bf16 v[4:7], v[170:173], v[216:219], v[4:7]
	s_setprio 0
	s_barrier
; #define PG8_STAGE(bufoff, gbase, voff) do { _Pragma("unroll") for (int _i = 0; _i < 2; ++_i) \
;         __builtin_amdgcn_global_load_lds((const unsigned*)((const char*)(gbase) + (voff)[_i]), (PG8_LAS unsigned*)(lds + (bufoff) + ldsw + _i * 8192), 16, 0, 0); } while (0)
; #define PG8_LDA(dst, b, h) do { _Pragma("unroll") for (int m = 0; m < 4; ++m) _Pragma("unroll") for (int k = 0; k < 2; ++k) dst[m][k] = *(const PG8_LAS bf16x8*)(lds + PG8_SA(b, h) + aoff + m * 2048 + k * 1024); } while (0)
; #define PG8_LDB(dst, b, h) do { _Pragma("unroll") for (int n = 0; n < 2; ++n) _Pragma("unroll") for (int k = 0; k < 2; ++k) dst[n][k] = *(const PG8_LAS bf16x8*)(lds + PG8_SB(b, h) + boff + n * 2048 + k * 1024); } while (0)
; #define PG8_MMA(ai, bj, At, Bt) do { __builtin_amdgcn_s_setprio(1); _Pragma("unroll") for (int m = 0; m < 4; ++m) _Pragma("unroll") for (int n = 0; n < 2; ++n) _Pragma("unroll") for (int k = 0; k < 2; ++k) \
;         acc[ai][bj][m][n] = __builtin_amdgcn_mfma_f32_16x16x32_bf16(Bt[n][k], At[m][k], acc[ai][bj][m][n], 0, 0, 0); __builtin_amdgcn_s_setprio(0); } while (0)
; #define PG8_WAIT_V(n) asm volatile("s_waitcnt vmcnt(" #n ")" ::: "memory")
; #define PG8_WAIT_L(n) asm volatile("s_waitcnt lgkmcnt(" #n ")" ::: "memory")
; #define PG8_BAR __builtin_amdgcn_s_barrier()
; #define PG8_SCHED __builtin_amdgcn_sched_barrier(0)
; template <class Epi, class Sched, bool ALIGN_EPI = false, bool SP2 = false>
; __device__ __forceinline__ void gemm_phase(PG8_LAS unsigned char* lds, const Gemm g, const Sched& S, const Epi& E) {
;     ...
;             PG8_LDB(B0, 1, 0); PG8_LDB(B1, 1, 1); PG8_SCHED; PG8_LDA(At, 1, 0); PG8_STAGE(PG8_SA(0, 1), a2 + hstep, voffA);
;             PG8_WAIT_V(8); PG8_WAIT_L(0); PG8_BAR; PG8_MMA(0, 0, At, B0); PG8_MMA(0, 1, At, B1); PG8_BAR; PG8_SCHED;
;             PG8_LDA(At, 1, 1); PG8_STAGE(PG8_SB(1, 0), b3, voffB); PG8_STAGE(PG8_SB(1, 1), b3 + hstep, voffB); PG8_STAGE(PG8_SA(1, 0), a3, voffA);
;             PG8_WAIT_V(8); PG8_WAIT_L(0); PG8_BAR; PG8_MMA(1, 0, At, B0); PG8_MMA(1, 1, At, B1); PG8_BAR; PG8_SCHED;
	s_add_i32 s12, 0, 0x18000
	s_add_i32 s13, 0, 0x1c000
	v_add_u32_e32 v140, s12, v165
	v_add_u32_e32 v178, s13, v165
	ds_read_b128 v[128:131], v140
	ds_read_b128 v[132:135], v140 offset:1024
	ds_read_b128 v[136:139], v140 offset:2048
	ds_read_b128 v[140:143], v140 offset:3072
	ds_read_b128 v[160:163], v178
	ds_read_b128 v[170:173], v178 offset:1024
	ds_read_b128 v[174:177], v178 offset:2048
	ds_read_b128 v[178:181], v178 offset:3072
	s_add_u32 s54, s54, 0x40000
	s_addc_u32 s55, s55, 0
	s_mov_b32 m0, s62
	ds_read_b128 v[188:191], v169 offset:32768
	ds_read_b128 v[192:195], v169 offset:33792
	ds_read_b128 v[196:199], v169 offset:34816
	ds_read_b128 v[200:203], v169 offset:35840
	ds_read_b128 v[204:207], v169 offset:36864
	ds_read_b128 v[208:211], v169 offset:37888
	ds_read_b128 v[212:215], v169 offset:38912
	ds_read_b128 v[216:219], v169 offset:39936
	global_load_lds_dwordx4 v144, s[54:55]
	s_mov_b32 m0, s63
	s_nop 0
	global_load_lds_dwordx4 v148, s[54:55]
	s_waitcnt vmcnt(8)
	s_waitcnt lgkmcnt(0)
	s_barrier
	s_setprio 1
	s_waitcnt lgkmcnt(0)
	v_mfma_f32_16x16x32_bf16 v[124:127], v[128:131], v[188:191], v[124:127]
	v_mfma_f32_16x16x32_bf16 v[120:123], v[136:139], v[188:191], v[120:123]
	v_mfma_f32_16x16x32_bf16 v[108:111], v[136:139], v[196:199], v[108:111]
	v_mfma_f32_16x16x32_bf16 v[116:119], v[128:131], v[196:199], v[116:119]
	v_mfma_f32_16x16x32_bf16 v[100:103], v[128:131], v[204:207], v[100:103]
	v_mfma_f32_16x16x32_bf16 v[92:95], v[136:139], v[204:207], v[92:95]
	v_mfma_f32_16x16x32_bf16 v[76:79], v[136:139], v[212:215], v[76:79]
	v_mfma_f32_16x16x32_bf16 v[84:87], v[128:131], v[212:215], v[84:87]
	v_mfma_f32_16x16x32_bf16 v[124:127], v[132:135], v[192:195], v[124:127]
	v_mfma_f32_16x16x32_bf16 v[120:123], v[140:143], v[192:195], v[120:123]
	v_mfma_f32_16x16x32_bf16 v[108:111], v[140:143], v[200:203], v[108:111]
	v_mfma_f32_16x16x32_bf16 v[116:119], v[132:135], v[200:203], v[116:119]
	v_mfma_f32_16x16x32_bf16 v[100:103], v[132:135], v[208:211], v[100:103]
	v_mfma_f32_16x16x32_bf16 v[92:95], v[140:143], v[208:211], v[92:95]
	v_mfma_f32_16x16x32_bf16 v[76:79], v[140:143], v[216:219], v[76:79]
	v_mfma_f32_16x16x32_bf16 v[84:87], v[132:135], v[216:219], v[84:87]
	s_setprio 0
	s_setprio 1
	v_mfma_f32_16x16x32_bf16 v[112:115], v[160:163], v[188:191], v[112:115]
	v_mfma_f32_16x16x32_bf16 v[104:107], v[174:177], v[188:191], v[104:107]
	v_mfma_f32_16x16x32_bf16 v[88:91], v[174:177], v[196:199], v[88:91]
	v_mfma_f32_16x16x32_bf16 v[96:99], v[160:163], v[196:199], v[96:99]
	v_mfma_f32_16x16x32_bf16 v[80:83], v[160:163], v[204:207], v[80:83]
	v_mfma_f32_16x16x32_bf16 v[72:75], v[174:177], v[204:207], v[72:75]
	v_mfma_f32_16x16x32_bf16 v[64:67], v[174:177], v[212:215], v[64:67]
	v_mfma_f32_16x16x32_bf16 v[68:71], v[160:163], v[212:215], v[68:71]
	v_mfma_f32_16x16x32_bf16 v[112:115], v[170:173], v[192:195], v[112:115]
	v_mfma_f32_16x16x32_bf16 v[104:107], v[178:181], v[192:195], v[104:107]
	v_mfma_f32_16x16x32_bf16 v[88:91], v[178:181], v[200:203], v[88:91]
	v_mfma_f32_16x16x32_bf16 v[96:99], v[170:173], v[200:203], v[96:99]
	v_mfma_f32_16x16x32_bf16 v[80:83], v[170:173], v[208:211], v[80:83]
	v_mfma_f32_16x16x32_bf16 v[72:75], v[178:181], v[208:211], v[72:75]
	v_mfma_f32_16x16x32_bf16 v[64:67], v[178:181], v[216:219], v[64:67]
	v_mfma_f32_16x16x32_bf16 v[68:71], v[170:173], v[216:219], v[68:71]
	s_setprio 0
	s_barrier
	s_add_i32 s12, s12, s59
	s_add_u32 s98, s52, s22
	s_addc_u32 s99, s53, s23
	s_mov_b32 m0, s12
	ds_read_b128 v[188:191], v169 offset:49152
	ds_read_b128 v[192:195], v169 offset:50176
	ds_read_b128 v[196:199], v169 offset:51200
	ds_read_b128 v[200:203], v169 offset:52224
	ds_read_b128 v[204:207], v169 offset:53248
	ds_read_b128 v[208:211], v169 offset:54272
	ds_read_b128 v[212:215], v169 offset:55296
	ds_read_b128 v[216:219], v169 offset:56320
	global_load_lds_dwordx4 v146, s[98:99]
	s_add_i32 m0, s12, 0x2000
	s_add_u32 s52, s52, 0x40080
	v_lshl_add_u64 v[184:185], v[220:221], 0, s[22:23]
	s_addc_u32 s53, s53, 0
	s_add_i32 s12, s13, s59
	global_load_lds_dwordx4 v[184:185], off
	s_mov_b32 m0, s12
	s_nop 0
	global_load_lds_dwordx4 v146, s[52:53]
	s_add_i32 m0, s12, 0x2000
	s_nop 0
	global_load_lds_dwordx4 v150, s[52:53]
	v_lshl_add_u64 v[184:185], v[222:223], 0, s[22:23]
	s_mov_b32 m0, s69
	s_nop 0
	global_load_lds_dwordx4 v[184:185], off
	v_lshl_add_u64 v[184:185], v[224:225], 0, s[22:23]
	s_mov_b32 m0, s70
	s_nop 0
	global_load_lds_dwordx4 v[184:185], off
	s_waitcnt vmcnt(8)
	s_waitcnt lgkmcnt(0)
	s_barrier
	s_setprio 1
	s_waitcnt lgkmcnt(0)
	v_mfma_f32_16x16x32_bf16 v[60:63], v[128:131], v[188:191], v[60:63]
	v_mfma_f32_16x16x32_bf16 v[56:59], v[136:139], v[188:191], v[56:59]
	v_mfma_f32_16x16x32_bf16 v[44:47], v[136:139], v[196:199], v[44:47]
	v_mfma_f32_16x16x32_bf16 v[48:51], v[128:131], v[196:199], v[48:51]
	v_mfma_f32_16x16x32_bf16 v[36:39], v[128:131], v[204:207], v[36:39]
	v_mfma_f32_16x16x32_bf16 v[28:31], v[136:139], v[204:207], v[28:31]
	v_mfma_f32_16x16x32_bf16 v[12:15], v[136:139], v[212:215], v[12:15]
	v_mfma_f32_16x16x32_bf16 v[20:23], v[128:131], v[212:215], v[20:23]
	v_mfma_f32_16x16x32_bf16 v[60:63], v[132:135], v[192:195], v[60:63]
	v_mfma_f32_16x16x32_bf16 v[56:59], v[140:143], v[192:195], v[56:59]
	v_mfma_f32_16x16x32_bf16 v[44:47], v[140:143], v[200:203], v[44:47]
	v_mfma_f32_16x16x32_bf16 v[48:51], v[132:135], v[200:203], v[48:51]
	v_mfma_f32_16x16x32_bf16 v[36:39], v[132:135], v[208:211], v[36:39]
	v_mfma_f32_16x16x32_bf16 v[28:31], v[140:143], v[208:211], v[28:31]
	v_mfma_f32_16x16x32_bf16 v[12:15], v[140:143], v[216:219], v[12:15]
	v_mfma_f32_16x16x32_bf16 v[20:23], v[132:135], v[216:219], v[20:23]
	s_setprio 0
	s_setprio 1
	v_mfma_f32_16x16x32_bf16 v[52:55], v[160:163], v[188:191], v[52:55]
	v_mfma_f32_16x16x32_bf16 v[40:43], v[174:177], v[188:191], v[40:43]
	v_mfma_f32_16x16x32_bf16 v[24:27], v[174:177], v[196:199], v[24:27]
	v_mfma_f32_16x16x32_bf16 v[32:35], v[160:163], v[196:199], v[32:35]
	v_mfma_f32_16x16x32_bf16 v[16:19], v[160:163], v[204:207], v[16:19]
	v_mfma_f32_16x16x32_bf16 v[8:11], v[174:177], v[204:207], v[8:11]
	v_mfma_f32_16x16x32_bf16 v[0:3], v[174:177], v[212:215], v[0:3]
	v_mfma_f32_16x16x32_bf16 v[4:7], v[160:163], v[212:215], v[4:7]
	v_mfma_f32_16x16x32_bf16 v[52:55], v[170:173], v[192:195], v[52:55]
	v_mfma_f32_16x16x32_bf16 v[40:43], v[178:181], v[192:195], v[40:43]
	v_mfma_f32_16x16x32_bf16 v[24:27], v[178:181], v[200:203], v[24:27]
	v_mfma_f32_16x16x32_bf16 v[32:35], v[170:173], v[200:203], v[32:35]
	v_mfma_f32_16x16x32_bf16 v[16:19], v[170:173], v[208:211], v[16:19]
	v_mfma_f32_16x16x32_bf16 v[8:11], v[178:181], v[208:211], v[8:11]
	v_mfma_f32_16x16x32_bf16 v[0:3], v[178:181], v[216:219], v[0:3]
	v_mfma_f32_16x16x32_bf16 v[4:7], v[170:173], v[216:219], v[4:7]
	s_setprio 0
	s_barrier
	s_add_i32 s79, s79, 2
	s_add_u32 s77, s77, 0x100
	s_addc_u32 s78, s78, 0
	s_add_u32 s50, s50, 0x100
	s_addc_u32 s51, s51, 0
	s_cmp_gt_u32 s79, 13
	s_cbranch_scc0 .LBB0_1272
	s_and_b64 vcc, exec, s[36:37]
	s_cbranch_vccz .LBB0_1275
	s_barrier

; #define PG8_STAGE(bufoff, gbase, voff) do { _Pragma("unroll") for (int _i = 0; _i < 2; ++_i) \
;         __builtin_amdgcn_global_load_lds((const unsigned*)((const char*)(gbase) + (voff)[_i]), (PG8_LAS unsigned*)(lds + (bufoff) + ldsw + _i * 8192), 16, 0, 0); } while (0)
; #define PG8_LDA(dst, b, h) do { _Pragma("unroll") for (int m = 0; m < 4; ++m) _Pragma("unroll") for (int k = 0; k < 2; ++k) dst[m][k] = *(const PG8_LAS bf16x8*)(lds + PG8_SA(b, h) + aoff + m * 2048 + k * 1024); } while (0)
; #define PG8_LDB(dst, b, h) do { _Pragma("unroll") for (int n = 0; n < 2; ++n) _Pragma("unroll") for (int k = 0; k < 2; ++k) dst[n][k] = *(const PG8_LAS bf16x8*)(lds + PG8_SB(b, h) + boff + n * 2048 + k * 1024); } while (0)
; #define PG8_MMA(ai, bj, At, Bt) do { __builtin_amdgcn_s_setprio(1); _Pragma("unroll") for (int m = 0; m < 4; ++m) _Pragma("unroll") for (int n = 0; n < 2; ++n) _Pragma("unroll") for (int k = 0; k < 2; ++k) \
;         acc[ai][bj][m][n] = __builtin_amdgcn_mfma_f32_16x16x32_bf16(Bt[n][k], At[m][k], acc[ai][bj][m][n], 0, 0, 0); __builtin_amdgcn_s_setprio(0); } while (0)
; #define PG8_WAIT_V(n) asm volatile("s_waitcnt vmcnt(" #n ")" ::: "memory")
; #define PG8_WAIT_L(n) asm volatile("s_waitcnt lgkmcnt(" #n ")" ::: "memory")
; #define PG8_BAR __builtin_amdgcn_s_barrier()
; template <class Epi, class Sched, bool ALIGN_EPI = false, bool SP2 = false>
; __device__ __forceinline__ void gemm_phase(PG8_LAS unsigned char* lds, const Gemm g, const Sched& S, const Epi& E) {
;     ...
;             const char* a2 = last ? nA : cA + (size_t)(t + 2) * kstep; const char* b2 = last ? nB : cB + (size_t)(t + 2) * kstep;
;             const char* a3 = a2 + kstep; const char* b3 = b2 + kstep;
;             if (last && has_next) S.a_ready(nxt);
;             if (last) E.prefetch(lds + 139264, cur, wid, lane);
;             if constexpr (SP2) {
;             PG8_LDB(B0, 0, 0); PG8_LDB(B1, 0, 1); PG8_SCHED; PG8_LDA(At, 0, 0); PG8_STAGE(PG8_SA(1, 1), a1 + hstep, voffA);
;             PG8_WAIT_V(8); PG8_WAIT_L(0); PG8_BAR; PG8_MMA(0, 0, At, B0); PG8_MMA(0, 1, At, B1); PG8_BAR; PG8_SCHED;
;             PG8_LDA(At, 0, 1); PG8_STAGE(PG8_SB(0, 0), b2, voffB); PG8_STAGE(PG8_SB(0, 1), b2 + hstep, voffB); PG8_STAGE(PG8_SA(0, 0), a2, voffA);
;             PG8_WAIT_V(8); PG8_WAIT_L(0); PG8_BAR; PG8_MMA(1, 0, At, B0); PG8_MMA(1, 1, At, B1); PG8_BAR; PG8_SCHED;
.LBB0_1358:
	v_add_u32_e32 v130, s71, v163
	ds_read_b128 v[118:121], v130
	ds_read_b128 v[122:125], v130 offset:1024
	ds_read_b128 v[126:129], v130 offset:2048
	ds_read_b128 v[170:173], v130 offset:3072
	v_add_u32_e32 v130, s72, v163
	ds_read_b128 v[174:177], v130
	ds_read_b128 v[178:181], v130 offset:1024
	ds_read_b128 v[184:187], v130 offset:2048
	ds_read_b128 v[188:191], v130 offset:3072
	s_add_u32 s14, s48, 0xfffc0080
	s_addc_u32 s15, s49, -1
	s_and_b64 s[50:51], s[50:51], exec
	s_cselect_b32 s53, s39, s15
	s_cselect_b32 s52, s73, s14
	s_cselect_b32 s51, s37, s47
	s_cselect_b32 s50, s74, s45
	s_add_i32 m0, s58, 0xc000
	ds_read_b128 v[192:195], v168
	ds_read_b128 v[196:199], v168 offset:1024
	ds_read_b128 v[200:203], v168 offset:2048
	ds_read_b128 v[204:207], v168 offset:3072
	ds_read_b128 v[208:211], v168 offset:4096
	ds_read_b128 v[212:215], v168 offset:5120
	ds_read_b128 v[216:219], v168 offset:6144
	ds_read_b128 v[220:223], v168 offset:7168
	global_load_lds_dwordx4 v154, s[48:49]
	s_add_i32 m0, s58, 0xe000
	s_nop 0
	global_load_lds_dwordx4 v152, s[48:49]
	s_waitcnt vmcnt(8)
	s_waitcnt lgkmcnt(0)
	s_barrier
	s_setprio 1
	s_waitcnt lgkmcnt(0)
	v_mfma_f32_16x16x32_bf16 v[140:143], v[118:121], v[192:195], v[140:143]
	v_mfma_f32_16x16x32_bf16 v[136:139], v[126:129], v[192:195], v[136:139]
	v_mfma_f32_16x16x32_bf16 v[104:107], v[126:129], v[200:203], v[104:107]
	v_mfma_f32_16x16x32_bf16 v[108:111], v[118:121], v[200:203], v[108:111]
	v_mfma_f32_16x16x32_bf16 v[92:95], v[118:121], v[208:211], v[92:95]
	v_mfma_f32_16x16x32_bf16 v[88:91], v[126:129], v[208:211], v[88:91]
	v_mfma_f32_16x16x32_bf16 v[72:75], v[126:129], v[216:219], v[72:75]
	v_mfma_f32_16x16x32_bf16 v[76:79], v[118:121], v[216:219], v[76:79]
	v_mfma_f32_16x16x32_bf16 v[140:143], v[122:125], v[196:199], v[140:143]
	v_mfma_f32_16x16x32_bf16 v[136:139], v[170:173], v[196:199], v[136:139]
	v_mfma_f32_16x16x32_bf16 v[104:107], v[170:173], v[204:207], v[104:107]
	v_mfma_f32_16x16x32_bf16 v[108:111], v[122:125], v[204:207], v[108:111]
	v_mfma_f32_16x16x32_bf16 v[92:95], v[122:125], v[212:215], v[92:95]
	v_mfma_f32_16x16x32_bf16 v[88:91], v[170:173], v[212:215], v[88:91]
	v_mfma_f32_16x16x32_bf16 v[72:75], v[170:173], v[220:223], v[72:75]
	v_mfma_f32_16x16x32_bf16 v[76:79], v[122:125], v[220:223], v[76:79]
	s_setprio 0
	s_setprio 1
	v_mfma_f32_16x16x32_bf16 v[130:133], v[174:177], v[192:195], v[132:135]
	v_mfma_f32_16x16x32_bf16 v[112:115], v[184:187], v[192:195], v[112:115]
	v_mfma_f32_16x16x32_bf16 v[96:99], v[184:187], v[200:203], v[96:99]
	v_mfma_f32_16x16x32_bf16 v[100:103], v[174:177], v[200:203], v[100:103]
	v_mfma_f32_16x16x32_bf16 v[84:87], v[174:177], v[208:211], v[84:87]
	v_mfma_f32_16x16x32_bf16 v[80:83], v[184:187], v[208:211], v[80:83]
	v_mfma_f32_16x16x32_bf16 v[64:67], v[184:187], v[216:219], v[64:67]
	v_mfma_f32_16x16x32_bf16 v[68:71], v[174:177], v[216:219], v[68:71]
	v_mfma_f32_16x16x32_bf16 v[130:133], v[178:181], v[196:199], v[130:133]
	v_mfma_f32_16x16x32_bf16 v[112:115], v[188:191], v[196:199], v[112:115]
	v_mfma_f32_16x16x32_bf16 v[96:99], v[188:191], v[204:207], v[96:99]
	v_mfma_f32_16x16x32_bf16 v[100:103], v[178:181], v[204:207], v[100:103]
	v_mfma_f32_16x16x32_bf16 v[84:87], v[178:181], v[212:215], v[84:87]
	v_mfma_f32_16x16x32_bf16 v[80:83], v[188:191], v[212:215], v[80:83]
	v_mfma_f32_16x16x32_bf16 v[64:67], v[188:191], v[220:223], v[64:67]
	v_mfma_f32_16x16x32_bf16 v[68:71], v[178:181], v[220:223], v[68:71]
	s_setprio 0
	s_barrier
	s_add_i32 s14, s71, s55
	s_mov_b32 m0, s14
	ds_read_b128 v[192:195], v168 offset:16384
	ds_read_b128 v[196:199], v168 offset:17408
	ds_read_b128 v[200:203], v168 offset:18432
	ds_read_b128 v[204:207], v168 offset:19456
	ds_read_b128 v[208:211], v168 offset:20480
	ds_read_b128 v[212:215], v168 offset:21504
	ds_read_b128 v[216:219], v168 offset:22528
	ds_read_b128 v[220:223], v168 offset:23552
	global_load_lds_dwordx4 v148, s[50:51]
	s_add_i32 m0, s14, 0x2000
	s_add_u32 s76, s50, 0x40000
	v_lshl_add_u64 v[226:227], s[50:51], 0, v[144:145]
	s_addc_u32 s77, s51, 0
	s_add_i32 s14, s72, s55
	global_load_lds_dwordx4 v144, s[50:51]
	s_mov_b32 m0, s14
	v_lshl_add_u64 v[228:229], s[52:53], 0, v[150:151]
	global_load_lds_dwordx4 v148, s[76:77]
	s_add_i32 m0, s14, 0x2000
	v_lshl_add_u64 v[230:231], s[52:53], 0, v[146:147]
	global_load_lds_dwordx4 v144, s[76:77]
	s_mov_b32 m0, s58
	s_nop 0
	global_load_lds_dwordx4 v150, s[52:53]
	s_mov_b32 m0, s59
	s_nop 0
	global_load_lds_dwordx4 v146, s[52:53]
	s_waitcnt vmcnt(8)
	s_waitcnt lgkmcnt(0)
	s_barrier
; #define PG8_STAGE(bufoff, gbase, voff) do { _Pragma("unroll") for (int _i = 0; _i < 2; ++_i) \
;         __builtin_amdgcn_global_load_lds((const unsigned*)((const char*)(gbase) + (voff)[_i]), (PG8_LAS unsigned*)(lds + (bufoff) + ldsw + _i * 8192), 16, 0, 0); } while (0)
; #define PG8_LDA(dst, b, h) do { _Pragma("unroll") for (int m = 0; m < 4; ++m) _Pragma("unroll") for (int k = 0; k < 2; ++k) dst[m][k] = *(const PG8_LAS bf16x8*)(lds + PG8_SA(b, h) + aoff + m * 2048 + k * 1024); } while (0)
; #define PG8_LDB(dst, b, h) do { _Pragma("unroll") for (int n = 0; n < 2; ++n) _Pragma("unroll") for (int k = 0; k < 2; ++k) dst[n][k] = *(const PG8_LAS bf16x8*)(lds + PG8_SB(b, h) + boff + n * 2048 + k * 1024); } while (0)
; #define PG8_MMA(ai, bj, At, Bt) do { __builtin_amdgcn_s_setprio(1); _Pragma("unroll") for (int m = 0; m < 4; ++m) _Pragma("unroll") for (int n = 0; n < 2; ++n) _Pragma("unroll") for (int k = 0; k < 2; ++k) \
;         acc[ai][bj][m][n] = __builtin_amdgcn_mfma_f32_16x16x32_bf16(Bt[n][k], At[m][k], acc[ai][bj][m][n], 0, 0, 0); __builtin_amdgcn_s_setprio(0); } while (0)
; #define PG8_WAIT_V(n) asm volatile("s_waitcnt vmcnt(" #n ")" ::: "memory")
; #define PG8_WAIT_L(n) asm volatile("s_waitcnt lgkmcnt(" #n ")" ::: "memory")
; #define PG8_BAR __builtin_amdgcn_s_barrier()
; #define PG8_SCHED __builtin_amdgcn_sched_barrier(0)
; template <class Epi, class Sched, bool ALIGN_EPI = false, bool SP2 = false>
; __device__ __forceinline__ void gemm_phase(PG8_LAS unsigned char* lds, const Gemm g, const Sched& S, const Epi& E) {
;     ...
;             PG8_WAIT_V(8); PG8_WAIT_L(0); PG8_BAR; PG8_MMA(1, 0, At, B0); PG8_MMA(1, 1, At, B1); PG8_BAR; PG8_SCHED;
;             PG8_LDB(B0, 1, 0); PG8_LDB(B1, 1, 1); PG8_SCHED; PG8_LDA(At, 1, 0); PG8_STAGE(PG8_SA(0, 1), a2 + hstep, voffA);
;             PG8_WAIT_V(8); PG8_WAIT_L(0); PG8_BAR; PG8_MMA(0, 0, At, B0); PG8_MMA(0, 1, At, B1); PG8_BAR; PG8_SCHED;
	s_setprio 1
	s_waitcnt lgkmcnt(0)
	v_mfma_f32_16x16x32_bf16 v[60:63], v[118:121], v[192:195], v[60:63]
	v_mfma_f32_16x16x32_bf16 v[56:59], v[126:129], v[192:195], v[56:59]
	v_mfma_f32_16x16x32_bf16 v[40:43], v[126:129], v[200:203], v[40:43]
	v_mfma_f32_16x16x32_bf16 v[44:47], v[118:121], v[200:203], v[44:47]
	v_mfma_f32_16x16x32_bf16 v[28:31], v[118:121], v[208:211], v[28:31]
	v_mfma_f32_16x16x32_bf16 v[24:27], v[126:129], v[208:211], v[24:27]
	v_mfma_f32_16x16x32_bf16 v[8:11], v[126:129], v[216:219], v[8:11]
	v_mfma_f32_16x16x32_bf16 v[12:15], v[118:121], v[216:219], v[12:15]
	v_mfma_f32_16x16x32_bf16 v[60:63], v[122:125], v[196:199], v[60:63]
	v_mfma_f32_16x16x32_bf16 v[56:59], v[170:173], v[196:199], v[56:59]
	v_mfma_f32_16x16x32_bf16 v[40:43], v[170:173], v[204:207], v[40:43]
	v_mfma_f32_16x16x32_bf16 v[44:47], v[122:125], v[204:207], v[44:47]
	v_mfma_f32_16x16x32_bf16 v[28:31], v[122:125], v[212:215], v[28:31]
	v_mfma_f32_16x16x32_bf16 v[24:27], v[170:173], v[212:215], v[24:27]
	v_mfma_f32_16x16x32_bf16 v[8:11], v[170:173], v[220:223], v[8:11]
	v_mfma_f32_16x16x32_bf16 v[12:15], v[122:125], v[220:223], v[12:15]
	s_setprio 0
	s_setprio 1
	v_mfma_f32_16x16x32_bf16 v[52:55], v[174:177], v[192:195], v[52:55]
	v_mfma_f32_16x16x32_bf16 v[48:51], v[184:187], v[192:195], v[48:51]
	v_mfma_f32_16x16x32_bf16 v[32:35], v[184:187], v[200:203], v[32:35]
	v_mfma_f32_16x16x32_bf16 v[36:39], v[174:177], v[200:203], v[36:39]
	v_mfma_f32_16x16x32_bf16 v[20:23], v[174:177], v[208:211], v[20:23]
	v_mfma_f32_16x16x32_bf16 v[16:19], v[184:187], v[208:211], v[16:19]
	v_mfma_f32_16x16x32_bf16 v[0:3], v[184:187], v[216:219], v[0:3]
	v_mfma_f32_16x16x32_bf16 v[4:7], v[174:177], v[216:219], v[4:7]
	v_mfma_f32_16x16x32_bf16 v[52:55], v[178:181], v[196:199], v[52:55]
	v_mfma_f32_16x16x32_bf16 v[48:51], v[188:191], v[196:199], v[48:51]
	v_mfma_f32_16x16x32_bf16 v[32:35], v[188:191], v[204:207], v[32:35]
	v_mfma_f32_16x16x32_bf16 v[36:39], v[178:181], v[204:207], v[36:39]
	v_mfma_f32_16x16x32_bf16 v[20:23], v[178:181], v[212:215], v[20:23]
	v_mfma_f32_16x16x32_bf16 v[16:19], v[188:191], v[212:215], v[16:19]
	v_mfma_f32_16x16x32_bf16 v[0:3], v[188:191], v[220:223], v[0:3]
	v_mfma_f32_16x16x32_bf16 v[4:7], v[178:181], v[220:223], v[4:7]
	s_setprio 0
	s_barrier
	s_add_i32 s14, 0, 0x18000
	v_add_u32_e32 v134, s14, v163
	s_add_i32 s15, 0, 0x1c000
	ds_read_b128 v[118:121], v134
	ds_read_b128 v[122:125], v134 offset:1024
	ds_read_b128 v[126:129], v134 offset:2048
	ds_read_b128 v[170:173], v134 offset:3072
	v_add_u32_e32 v134, s15, v163
	ds_read_b128 v[174:177], v134
	ds_read_b128 v[178:181], v134 offset:1024
	ds_read_b128 v[184:187], v134 offset:2048
	ds_read_b128 v[188:191], v134 offset:3072
	s_add_u32 s52, s52, 0x40000
	s_addc_u32 s53, s53, 0
	s_mov_b32 m0, s60
	ds_read_b128 v[192:195], v168 offset:32768
	ds_read_b128 v[196:199], v168 offset:33792
	ds_read_b128 v[200:203], v168 offset:34816
	ds_read_b128 v[204:207], v168 offset:35840
	ds_read_b128 v[208:211], v168 offset:36864
	ds_read_b128 v[212:215], v168 offset:37888
	ds_read_b128 v[216:219], v168 offset:38912
	ds_read_b128 v[220:223], v168 offset:39936
	global_load_lds_dwordx4 v150, s[52:53]
	s_mov_b32 m0, s61
	s_nop 0
	global_load_lds_dwordx4 v146, s[52:53]
	s_waitcnt vmcnt(8)
	s_waitcnt lgkmcnt(0)
	s_barrier
	s_setprio 1
	s_waitcnt lgkmcnt(0)
	v_mfma_f32_16x16x32_bf16 v[140:143], v[118:121], v[192:195], v[140:143]
	v_mfma_f32_16x16x32_bf16 v[134:137], v[126:129], v[192:195], v[136:139]
	v_mfma_f32_16x16x32_bf16 v[104:107], v[126:129], v[200:203], v[104:107]
	v_mfma_f32_16x16x32_bf16 v[108:111], v[118:121], v[200:203], v[108:111]
	v_mfma_f32_16x16x32_bf16 v[92:95], v[118:121], v[208:211], v[92:95]
	v_mfma_f32_16x16x32_bf16 v[88:91], v[126:129], v[208:211], v[88:91]
	v_mfma_f32_16x16x32_bf16 v[72:75], v[126:129], v[216:219], v[72:75]
	v_mfma_f32_16x16x32_bf16 v[76:79], v[118:121], v[216:219], v[76:79]
	v_mfma_f32_16x16x32_bf16 v[140:143], v[122:125], v[196:199], v[140:143]
	v_mfma_f32_16x16x32_bf16 v[136:139], v[170:173], v[196:199], v[134:137]
	v_mfma_f32_16x16x32_bf16 v[104:107], v[170:173], v[204:207], v[104:107]
	v_mfma_f32_16x16x32_bf16 v[108:111], v[122:125], v[204:207], v[108:111]
	v_mfma_f32_16x16x32_bf16 v[92:95], v[122:125], v[212:215], v[92:95]
	v_mfma_f32_16x16x32_bf16 v[88:91], v[170:173], v[212:215], v[88:91]
	v_mfma_f32_16x16x32_bf16 v[72:75], v[170:173], v[220:223], v[72:75]
	v_mfma_f32_16x16x32_bf16 v[76:79], v[122:125], v[220:223], v[76:79]
	s_setprio 0
	s_setprio 1
	v_mfma_f32_16x16x32_bf16 v[130:133], v[174:177], v[192:195], v[130:133]
	v_mfma_f32_16x16x32_bf16 v[112:115], v[184:187], v[192:195], v[112:115]
	v_mfma_f32_16x16x32_bf16 v[96:99], v[184:187], v[200:203], v[96:99]
	v_mfma_f32_16x16x32_bf16 v[100:103], v[174:177], v[200:203], v[100:103]
	v_mfma_f32_16x16x32_bf16 v[84:87], v[174:177], v[208:211], v[84:87]
	v_mfma_f32_16x16x32_bf16 v[80:83], v[184:187], v[208:211], v[80:83]
	v_mfma_f32_16x16x32_bf16 v[64:67], v[184:187], v[216:219], v[64:67]
	v_mfma_f32_16x16x32_bf16 v[68:71], v[174:177], v[216:219], v[68:71]
	v_mfma_f32_16x16x32_bf16 v[132:135], v[178:181], v[196:199], v[130:133]
	v_mfma_f32_16x16x32_bf16 v[112:115], v[188:191], v[196:199], v[112:115]
	v_mfma_f32_16x16x32_bf16 v[96:99], v[188:191], v[204:207], v[96:99]
	v_mfma_f32_16x16x32_bf16 v[100:103], v[178:181], v[204:207], v[100:103]
	v_mfma_f32_16x16x32_bf16 v[84:87], v[178:181], v[212:215], v[84:87]
	v_mfma_f32_16x16x32_bf16 v[80:83], v[188:191], v[212:215], v[80:83]
	v_mfma_f32_16x16x32_bf16 v[64:67], v[188:191], v[220:223], v[64:67]
	v_mfma_f32_16x16x32_bf16 v[68:71], v[178:181], v[220:223], v[68:71]
	s_setprio 0
	s_barrier
; #define PG8_STAGE(bufoff, gbase, voff) do { _Pragma("unroll") for (int _i = 0; _i < 2; ++_i) \
;         __builtin_amdgcn_global_load_lds((const unsigned*)((const char*)(gbase) + (voff)[_i]), (PG8_LAS unsigned*)(lds + (bufoff) + ldsw + _i * 8192), 16, 0, 0); } while (0)
; #define PG8_LDA(dst, b, h) do { _Pragma("unroll") for (int m = 0; m < 4; ++m) _Pragma("unroll") for (int k = 0; k < 2; ++k) dst[m][k] = *(const PG8_LAS bf16x8*)(lds + PG8_SA(b, h) + aoff + m * 2048 + k * 1024); } while (0)
; #define PG8_MMA(ai, bj, At, Bt) do { __builtin_amdgcn_s_setprio(1); _Pragma("unroll") for (int m = 0; m < 4; ++m) _Pragma("unroll") for (int n = 0; n < 2; ++n) _Pragma("unroll") for (int k = 0; k < 2; ++k) \
;         acc[ai][bj][m][n] = __builtin_amdgcn_mfma_f32_16x16x32_bf16(Bt[n][k], At[m][k], acc[ai][bj][m][n], 0, 0, 0); __builtin_amdgcn_s_setprio(0); } while (0)
; #define PG8_WAIT_V(n) asm volatile("s_waitcnt vmcnt(" #n ")" ::: "memory")
; #define PG8_WAIT_L(n) asm volatile("s_waitcnt lgkmcnt(" #n ")" ::: "memory")
; #define PG8_BAR __builtin_amdgcn_s_barrier()
; #define PG8_SCHED __builtin_amdgcn_sched_barrier(0)
; template <class Epi, class Sched, bool ALIGN_EPI = false, bool SP2 = false>
; __device__ __forceinline__ void gemm_phase(PG8_LAS unsigned char* lds, const Gemm g, const Sched& S, const Epi& E) {
;     ...
;             PG8_LDA(At, 1, 1); PG8_STAGE(PG8_SB(1, 0), b3, voffB); PG8_STAGE(PG8_SB(1, 1), b3 + hstep, voffB); PG8_STAGE(PG8_SA(1, 0), a3, voffA);
;             PG8_WAIT_V(8); PG8_WAIT_L(0); PG8_BAR; PG8_MMA(1, 0, At, B0); PG8_MMA(1, 1, At, B1); PG8_BAR; PG8_SCHED;
	s_add_i32 s14, s14, s55
	s_add_u32 s98, s50, s18
	s_addc_u32 s99, s51, s19
	s_mov_b32 m0, s14
	ds_read_b128 v[192:195], v168 offset:49152
	ds_read_b128 v[196:199], v168 offset:50176
	ds_read_b128 v[200:203], v168 offset:51200
	ds_read_b128 v[204:207], v168 offset:52224
	ds_read_b128 v[208:211], v168 offset:53248
	ds_read_b128 v[212:215], v168 offset:54272
	ds_read_b128 v[216:219], v168 offset:55296
	ds_read_b128 v[220:223], v168 offset:56320
	global_load_lds_dwordx4 v148, s[98:99]
	s_add_i32 m0, s14, 0x2000
	s_add_u32 s50, s50, 0x40080
	v_lshl_add_u64 v[130:131], v[226:227], 0, s[18:19]
	s_addc_u32 s51, s51, 0
	s_add_i32 s14, s15, s55
	global_load_lds_dwordx4 v[130:131], off
	s_mov_b32 m0, s14
	s_nop 0
	global_load_lds_dwordx4 v148, s[50:51]
	s_add_i32 m0, s14, 0x2000
	s_nop 0
	global_load_lds_dwordx4 v144, s[50:51]
	v_lshl_add_u64 v[130:131], v[228:229], 0, s[18:19]
	s_mov_b32 m0, s64
	s_nop 0
	global_load_lds_dwordx4 v[130:131], off
	v_lshl_add_u64 v[130:131], v[230:231], 0, s[18:19]
	s_mov_b32 m0, s65
	s_nop 0
	global_load_lds_dwordx4 v[130:131], off
	s_waitcnt vmcnt(8)
	s_waitcnt lgkmcnt(0)
	s_barrier
	s_setprio 1
	s_waitcnt lgkmcnt(0)
	v_mfma_f32_16x16x32_bf16 v[60:63], v[118:121], v[192:195], v[60:63]
	v_mfma_f32_16x16x32_bf16 v[56:59], v[126:129], v[192:195], v[56:59]
	v_mfma_f32_16x16x32_bf16 v[40:43], v[126:129], v[200:203], v[40:43]
	v_mfma_f32_16x16x32_bf16 v[44:47], v[118:121], v[200:203], v[44:47]
	v_mfma_f32_16x16x32_bf16 v[28:31], v[118:121], v[208:211], v[28:31]
	v_mfma_f32_16x16x32_bf16 v[24:27], v[126:129], v[208:211], v[24:27]
	v_mfma_f32_16x16x32_bf16 v[8:11], v[126:129], v[216:219], v[8:11]
	v_mfma_f32_16x16x32_bf16 v[12:15], v[118:121], v[216:219], v[12:15]
	v_mfma_f32_16x16x32_bf16 v[60:63], v[122:125], v[196:199], v[60:63]
	v_mfma_f32_16x16x32_bf16 v[56:59], v[170:173], v[196:199], v[56:59]
	v_mfma_f32_16x16x32_bf16 v[40:43], v[170:173], v[204:207], v[40:43]
	v_mfma_f32_16x16x32_bf16 v[44:47], v[122:125], v[204:207], v[44:47]
	v_mfma_f32_16x16x32_bf16 v[28:31], v[122:125], v[212:215], v[28:31]
	v_mfma_f32_16x16x32_bf16 v[24:27], v[170:173], v[212:215], v[24:27]
	v_mfma_f32_16x16x32_bf16 v[8:11], v[170:173], v[220:223], v[8:11]
	v_mfma_f32_16x16x32_bf16 v[12:15], v[122:125], v[220:223], v[12:15]
	s_setprio 0
	s_setprio 1
	v_mfma_f32_16x16x32_bf16 v[52:55], v[174:177], v[192:195], v[52:55]
	v_mfma_f32_16x16x32_bf16 v[48:51], v[184:187], v[192:195], v[48:51]
	v_mfma_f32_16x16x32_bf16 v[32:35], v[184:187], v[200:203], v[32:35]
	v_mfma_f32_16x16x32_bf16 v[36:39], v[174:177], v[200:203], v[36:39]
	v_mfma_f32_16x16x32_bf16 v[20:23], v[174:177], v[208:211], v[20:23]
	v_mfma_f32_16x16x32_bf16 v[16:19], v[184:187], v[208:211], v[16:19]
	v_mfma_f32_16x16x32_bf16 v[0:3], v[184:187], v[216:219], v[0:3]
	v_mfma_f32_16x16x32_bf16 v[4:7], v[174:177], v[216:219], v[4:7]
	v_mfma_f32_16x16x32_bf16 v[52:55], v[178:181], v[196:199], v[52:55]
	v_mfma_f32_16x16x32_bf16 v[48:51], v[188:191], v[196:199], v[48:51]
	v_mfma_f32_16x16x32_bf16 v[32:35], v[188:191], v[204:207], v[32:35]
	v_mfma_f32_16x16x32_bf16 v[36:39], v[178:181], v[204:207], v[36:39]
	v_mfma_f32_16x16x32_bf16 v[20:23], v[178:181], v[212:215], v[20:23]
	v_mfma_f32_16x16x32_bf16 v[16:19], v[188:191], v[212:215], v[16:19]
	v_mfma_f32_16x16x32_bf16 v[0:3], v[188:191], v[220:223], v[0:3]
	v_mfma_f32_16x16x32_bf16 v[4:7], v[178:181], v[220:223], v[4:7]
	s_setprio 0
	s_barrier
	s_add_i32 s75, s75, 2
	s_add_u32 s45, s45, 0x100
	s_addc_u32 s47, s47, 0
	s_add_u32 s48, s48, 0x100
	s_addc_u32 s49, s49, 0
	s_cmp_gt_u32 s75, 13
	s_cbranch_scc1 .LBB0_1361

; #define PG8_STAGE(bufoff, gbase, voff) do { _Pragma("unroll") for (int _i = 0; _i < 2; ++_i) \
;         __builtin_amdgcn_global_load_lds((const unsigned*)((const char*)(gbase) + (voff)[_i]), (PG8_LAS unsigned*)(lds + (bufoff) + ldsw + _i * 8192), 16, 0, 0); } while (0)
; #define PG8_LDA(dst, b, h) do { _Pragma("unroll") for (int m = 0; m < 4; ++m) _Pragma("unroll") for (int k = 0; k < 2; ++k) dst[m][k] = *(const PG8_LAS bf16x8*)(lds + PG8_SA(b, h) + aoff + m * 2048 + k * 1024); } while (0)
; #define PG8_LDB(dst, b, h) do { _Pragma("unroll") for (int n = 0; n < 2; ++n) _Pragma("unroll") for (int k = 0; k < 2; ++k) dst[n][k] = *(const PG8_LAS bf16x8*)(lds + PG8_SB(b, h) + boff + n * 2048 + k * 1024); } while (0)
; #define PG8_MMA(ai, bj, At, Bt) do { __builtin_amdgcn_s_setprio(1); _Pragma("unroll") for (int m = 0; m < 4; ++m) _Pragma("unroll") for (int n = 0; n < 2; ++n) _Pragma("unroll") for (int k = 0; k < 2; ++k) \
;         acc[ai][bj][m][n] = __builtin_amdgcn_mfma_f32_16x16x32_bf16(Bt[n][k], At[m][k], acc[ai][bj][m][n], 0, 0, 0); __builtin_amdgcn_s_setprio(0); } while (0)
; #define PG8_WAIT_V(n) asm volatile("s_waitcnt vmcnt(" #n ")" ::: "memory")
; #define PG8_WAIT_L(n) asm volatile("s_waitcnt lgkmcnt(" #n ")" ::: "memory")
; #define PG8_BAR __builtin_amdgcn_s_barrier()
; template <class Epi, class Sched, bool ALIGN_EPI = false, bool SP2 = false>
; __device__ __forceinline__ void gemm_phase(PG8_LAS unsigned char* lds, const Gemm g, const Sched& S, const Epi& E) {
;     ...
;             const char* a2 = last ? nA : cA + (size_t)(t + 2) * kstep; const char* b2 = last ? nB : cB + (size_t)(t + 2) * kstep;
;             const char* a3 = a2 + kstep; const char* b3 = b2 + kstep;
;             if (last && has_next) S.a_ready(nxt);
;             if (last) E.prefetch(lds + 139264, cur, wid, lane);
;             if constexpr (SP2) {
;             PG8_LDB(B0, 0, 0); PG8_LDB(B1, 0, 1); PG8_SCHED; PG8_LDA(At, 0, 0); PG8_STAGE(PG8_SA(1, 1), a1 + hstep, voffA);
;             PG8_WAIT_V(8); PG8_WAIT_L(0); PG8_BAR; PG8_MMA(0, 0, At, B0); PG8_MMA(0, 1, At, B1); PG8_BAR; PG8_SCHED;
;             PG8_LDA(At, 0, 1); PG8_STAGE(PG8_SB(0, 0), b2, voffB); PG8_STAGE(PG8_SB(0, 1), b2 + hstep, voffB); PG8_STAGE(PG8_SA(0, 0), a2, voffA);
;             PG8_WAIT_V(8); PG8_WAIT_L(0); PG8_BAR; PG8_MMA(1, 0, At, B0); PG8_MMA(1, 1, At, B1); PG8_BAR; PG8_SCHED;
.LBB0_1432:
	ds_read_b128 v[128:131], v167
	ds_read_b128 v[132:135], v167 offset:1024
	ds_read_b128 v[136:139], v167 offset:2048
	ds_read_b128 v[140:143], v167 offset:3072
	ds_read_b128 v[160:163], v168
	ds_read_b128 v[170:173], v168 offset:1024
	ds_read_b128 v[174:177], v168 offset:2048
	ds_read_b128 v[178:181], v168 offset:3072
	s_add_u32 s20, s18, 0x100
	s_addc_u32 s21, s19, 0
	s_cmp_eq_u32 s52, 40
	s_cselect_b32 s27, s5, s21
	s_cselect_b32 s26, s4, s20
	s_cselect_b32 s23, s17, s51
	s_cselect_b32 s22, s16, s50
	v_lshl_add_u64 v[214:215], s[18:19], 0, v[154:155]
	s_add_i32 m0, s36, 0xc000
	ds_read_b128 v[182:185], v169
	ds_read_b128 v[186:189], v169 offset:1024
	ds_read_b128 v[190:193], v169 offset:2048
	ds_read_b128 v[194:197], v169 offset:3072
	ds_read_b128 v[198:201], v169 offset:4096
	ds_read_b128 v[202:205], v169 offset:5120
	ds_read_b128 v[206:209], v169 offset:6144
	ds_read_b128 v[210:213], v169 offset:7168
	global_load_lds_dwordx4 v[214:215], off
	v_lshl_add_u64 v[214:215], s[18:19], 0, v[152:153]
	s_add_i32 m0, s36, 0xe000
	s_nop 0
	global_load_lds_dwordx4 v[214:215], off
	s_waitcnt vmcnt(8)
	s_waitcnt lgkmcnt(0)
	s_barrier
	s_setprio 1
	s_waitcnt lgkmcnt(0)
	v_mfma_f32_16x16x32_bf16 v[124:127], v[128:131], v[182:185], v[124:127]
	v_mfma_f32_16x16x32_bf16 v[120:123], v[136:139], v[182:185], v[120:123]
	v_mfma_f32_16x16x32_bf16 v[108:111], v[136:139], v[190:193], v[108:111]
	v_mfma_f32_16x16x32_bf16 v[116:119], v[128:131], v[190:193], v[116:119]
	v_mfma_f32_16x16x32_bf16 v[100:103], v[128:131], v[198:201], v[100:103]
	v_mfma_f32_16x16x32_bf16 v[92:95], v[136:139], v[198:201], v[92:95]
	v_mfma_f32_16x16x32_bf16 v[76:79], v[136:139], v[206:209], v[76:79]
	v_mfma_f32_16x16x32_bf16 v[84:87], v[128:131], v[206:209], v[84:87]
	v_mfma_f32_16x16x32_bf16 v[124:127], v[132:135], v[186:189], v[124:127]
	v_mfma_f32_16x16x32_bf16 v[120:123], v[140:143], v[186:189], v[120:123]
	v_mfma_f32_16x16x32_bf16 v[108:111], v[140:143], v[194:197], v[108:111]
	v_mfma_f32_16x16x32_bf16 v[116:119], v[132:135], v[194:197], v[116:119]
	v_mfma_f32_16x16x32_bf16 v[100:103], v[132:135], v[202:205], v[100:103]
	v_mfma_f32_16x16x32_bf16 v[92:95], v[140:143], v[202:205], v[92:95]
	v_mfma_f32_16x16x32_bf16 v[76:79], v[140:143], v[210:213], v[76:79]
	v_mfma_f32_16x16x32_bf16 v[84:87], v[132:135], v[210:213], v[84:87]
	s_setprio 0
	s_setprio 1
	v_mfma_f32_16x16x32_bf16 v[112:115], v[160:163], v[182:185], v[112:115]
	v_mfma_f32_16x16x32_bf16 v[104:107], v[174:177], v[182:185], v[104:107]
	v_mfma_f32_16x16x32_bf16 v[88:91], v[174:177], v[190:193], v[88:91]
	v_mfma_f32_16x16x32_bf16 v[96:99], v[160:163], v[190:193], v[96:99]
	v_mfma_f32_16x16x32_bf16 v[80:83], v[160:163], v[198:201], v[80:83]
	v_mfma_f32_16x16x32_bf16 v[72:75], v[174:177], v[198:201], v[72:75]
	v_mfma_f32_16x16x32_bf16 v[64:67], v[174:177], v[206:209], v[64:67]
	v_mfma_f32_16x16x32_bf16 v[68:71], v[160:163], v[206:209], v[68:71]
	v_mfma_f32_16x16x32_bf16 v[112:115], v[170:173], v[186:189], v[112:115]
	v_mfma_f32_16x16x32_bf16 v[104:107], v[178:181], v[186:189], v[104:107]
	v_mfma_f32_16x16x32_bf16 v[88:91], v[178:181], v[194:197], v[88:91]
	v_mfma_f32_16x16x32_bf16 v[96:99], v[170:173], v[194:197], v[96:99]
	v_mfma_f32_16x16x32_bf16 v[80:83], v[170:173], v[202:205], v[80:83]
	v_mfma_f32_16x16x32_bf16 v[72:75], v[178:181], v[202:205], v[72:75]
	v_mfma_f32_16x16x32_bf16 v[64:67], v[178:181], v[210:213], v[64:67]
	v_mfma_f32_16x16x32_bf16 v[68:71], v[170:173], v[210:213], v[68:71]
	s_setprio 0
	s_barrier
	s_add_i32 s18, s44, s33
	s_mov_b32 m0, s18
	ds_read_b128 v[182:185], v169 offset:16384
	ds_read_b128 v[186:189], v169 offset:17408
	ds_read_b128 v[190:193], v169 offset:18432
	ds_read_b128 v[194:197], v169 offset:19456
	ds_read_b128 v[198:201], v169 offset:20480
	ds_read_b128 v[202:205], v169 offset:21504
	ds_read_b128 v[206:209], v169 offset:22528
	ds_read_b128 v[210:213], v169 offset:23552
	global_load_lds_dwordx4 v148, s[22:23]
	s_add_i32 m0, s18, 0x2000
	s_add_u32 s18, s22, 0xb0000
	v_lshl_add_u64 v[216:217], s[22:23], 0, v[144:145]
	s_addc_u32 s19, s23, 0
	s_add_i32 s53, s45, s33
	global_load_lds_dwordx4 v144, s[22:23]
	s_mov_b32 m0, s53
	s_nop 0
	global_load_lds_dwordx4 v148, s[18:19]
	s_add_i32 m0, s53, 0x2000
	s_nop 0
	global_load_lds_dwordx4 v144, s[18:19]
	s_mov_b32 m0, s36
	s_nop 0
	global_load_lds_dwordx4 v150, s[26:27]
	s_mov_b32 m0, s37
	s_nop 0
	global_load_lds_dwordx4 v146, s[26:27]
	s_waitcnt vmcnt(8)
	s_waitcnt lgkmcnt(0)
	s_barrier
	s_setprio 1
	s_waitcnt lgkmcnt(0)
	v_mfma_f32_16x16x32_bf16 v[60:63], v[128:131], v[182:185], v[60:63]
	v_mfma_f32_16x16x32_bf16 v[56:59], v[136:139], v[182:185], v[56:59]
	v_mfma_f32_16x16x32_bf16 v[44:47], v[136:139], v[190:193], v[44:47]
	v_mfma_f32_16x16x32_bf16 v[48:51], v[128:131], v[190:193], v[48:51]
	v_mfma_f32_16x16x32_bf16 v[36:39], v[128:131], v[198:201], v[36:39]
	v_mfma_f32_16x16x32_bf16 v[28:31], v[136:139], v[198:201], v[28:31]
	v_mfma_f32_16x16x32_bf16 v[12:15], v[136:139], v[206:209], v[12:15]
	v_mfma_f32_16x16x32_bf16 v[20:23], v[128:131], v[206:209], v[20:23]
	v_mfma_f32_16x16x32_bf16 v[60:63], v[132:135], v[186:189], v[60:63]
	v_mfma_f32_16x16x32_bf16 v[56:59], v[140:143], v[186:189], v[56:59]
	v_mfma_f32_16x16x32_bf16 v[44:47], v[140:143], v[194:197], v[44:47]
	v_mfma_f32_16x16x32_bf16 v[48:51], v[132:135], v[194:197], v[48:51]
	v_mfma_f32_16x16x32_bf16 v[36:39], v[132:135], v[202:205], v[36:39]
	v_mfma_f32_16x16x32_bf16 v[28:31], v[140:143], v[202:205], v[28:31]
	v_mfma_f32_16x16x32_bf16 v[12:15], v[140:143], v[210:213], v[12:15]
	v_mfma_f32_16x16x32_bf16 v[20:23], v[132:135], v[210:213], v[20:23]
	s_setprio 0
	s_setprio 1
	v_mfma_f32_16x16x32_bf16 v[52:55], v[160:163], v[182:185], v[52:55]
	v_mfma_f32_16x16x32_bf16 v[40:43], v[174:177], v[182:185], v[40:43]
	v_mfma_f32_16x16x32_bf16 v[24:27], v[174:177], v[190:193], v[24:27]
	v_mfma_f32_16x16x32_bf16 v[32:35], v[160:163], v[190:193], v[32:35]
	v_mfma_f32_16x16x32_bf16 v[16:19], v[160:163], v[198:201], v[16:19]
	v_mfma_f32_16x16x32_bf16 v[8:11], v[174:177], v[198:201], v[8:11]
	v_mfma_f32_16x16x32_bf16 v[0:3], v[174:177], v[206:209], v[0:3]
	v_mfma_f32_16x16x32_bf16 v[4:7], v[160:163], v[206:209], v[4:7]
	v_mfma_f32_16x16x32_bf16 v[52:55], v[170:173], v[186:189], v[52:55]
	v_mfma_f32_16x16x32_bf16 v[40:43], v[178:181], v[186:189], v[40:43]
	v_mfma_f32_16x16x32_bf16 v[24:27], v[178:181], v[194:197], v[24:27]
	v_mfma_f32_16x16x32_bf16 v[32:35], v[170:173], v[194:197], v[32:35]
	v_mfma_f32_16x16x32_bf16 v[16:19], v[170:173], v[202:205], v[16:19]
	v_mfma_f32_16x16x32_bf16 v[8:11], v[178:181], v[202:205], v[8:11]
	v_mfma_f32_16x16x32_bf16 v[0:3], v[178:181], v[210:213], v[0:3]
	v_mfma_f32_16x16x32_bf16 v[4:7], v[170:173], v[210:213], v[4:7]
	s_setprio 0
	s_barrier
; #define PG8_STAGE(bufoff, gbase, voff) do { _Pragma("unroll") for (int _i = 0; _i < 2; ++_i) \
;         __builtin_amdgcn_global_load_lds((const unsigned*)((const char*)(gbase) + (voff)[_i]), (PG8_LAS unsigned*)(lds + (bufoff) + ldsw + _i * 8192), 16, 0, 0); } while (0)
; #define PG8_LDA(dst, b, h) do { _Pragma("unroll") for (int m = 0; m < 4; ++m) _Pragma("unroll") for (int k = 0; k < 2; ++k) dst[m][k] = *(const PG8_LAS bf16x8*)(lds + PG8_SA(b, h) + aoff + m * 2048 + k * 1024); } while (0)
; #define PG8_LDB(dst, b, h) do { _Pragma("unroll") for (int n = 0; n < 2; ++n) _Pragma("unroll") for (int k = 0; k < 2; ++k) dst[n][k] = *(const PG8_LAS bf16x8*)(lds + PG8_SB(b, h) + boff + n * 2048 + k * 1024); } while (0)
; #define PG8_MMA(ai, bj, At, Bt) do { __builtin_amdgcn_s_setprio(1); _Pragma("unroll") for (int m = 0; m < 4; ++m) _Pragma("unroll") for (int n = 0; n < 2; ++n) _Pragma("unroll") for (int k = 0; k < 2; ++k) \
;         acc[ai][bj][m][n] = __builtin_amdgcn_mfma_f32_16x16x32_bf16(Bt[n][k], At[m][k], acc[ai][bj][m][n], 0, 0, 0); __builtin_amdgcn_s_setprio(0); } while (0)
; #define PG8_WAIT_V(n) asm volatile("s_waitcnt vmcnt(" #n ")" ::: "memory")
; #define PG8_WAIT_L(n) asm volatile("s_waitcnt lgkmcnt(" #n ")" ::: "memory")
; #define PG8_BAR __builtin_amdgcn_s_barrier()
; #define PG8_SCHED __builtin_amdgcn_sched_barrier(0)
; template <class Epi, class Sched, bool ALIGN_EPI = false, bool SP2 = false>
; __device__ __forceinline__ void gemm_phase(PG8_LAS unsigned char* lds, const Gemm g, const Sched& S, const Epi& E) {
;     ...
;             PG8_LDB(B0, 1, 0); PG8_LDB(B1, 1, 1); PG8_SCHED; PG8_LDA(At, 1, 0); PG8_STAGE(PG8_SA(0, 1), a2 + hstep, voffA);
;             PG8_WAIT_V(8); PG8_WAIT_L(0); PG8_BAR; PG8_MMA(0, 0, At, B0); PG8_MMA(0, 1, At, B1); PG8_BAR; PG8_SCHED;
;             PG8_LDA(At, 1, 1); PG8_STAGE(PG8_SB(1, 0), b3, voffB); PG8_STAGE(PG8_SB(1, 1), b3 + hstep, voffB); PG8_STAGE(PG8_SA(1, 0), a3, voffA);
;             PG8_WAIT_V(8); PG8_WAIT_L(0); PG8_BAR; PG8_MMA(1, 0, At, B0); PG8_MMA(1, 1, At, B1); PG8_BAR; PG8_SCHED;
	s_add_i32 s53, 0, 0x18000
	s_add_i32 s54, 0, 0x1c000
	v_add_u32_e32 v140, s53, v165
	v_add_u32_e32 v178, s54, v165
	ds_read_b128 v[128:131], v140
	ds_read_b128 v[132:135], v140 offset:1024
	ds_read_b128 v[136:139], v140 offset:2048
	ds_read_b128 v[140:143], v140 offset:3072
	ds_read_b128 v[160:163], v178
	ds_read_b128 v[170:173], v178 offset:1024
	ds_read_b128 v[174:177], v178 offset:2048
	ds_read_b128 v[178:181], v178 offset:3072
	s_add_u32 s18, s26, 0xb0000
	s_addc_u32 s19, s27, 0
	s_mov_b32 m0, s38
	ds_read_b128 v[182:185], v169 offset:32768
	ds_read_b128 v[186:189], v169 offset:33792
	ds_read_b128 v[190:193], v169 offset:34816
	ds_read_b128 v[194:197], v169 offset:35840
	ds_read_b128 v[198:201], v169 offset:36864
	ds_read_b128 v[202:205], v169 offset:37888
	ds_read_b128 v[206:209], v169 offset:38912
	ds_read_b128 v[210:213], v169 offset:39936
	global_load_lds_dwordx4 v150, s[18:19]
	s_mov_b32 m0, s39
	s_nop 0
	global_load_lds_dwordx4 v146, s[18:19]
	s_waitcnt vmcnt(8)
	s_waitcnt lgkmcnt(0)
	s_barrier
	s_setprio 1
	s_waitcnt lgkmcnt(0)
	v_mfma_f32_16x16x32_bf16 v[124:127], v[128:131], v[182:185], v[124:127]
	v_mfma_f32_16x16x32_bf16 v[120:123], v[136:139], v[182:185], v[120:123]
	v_mfma_f32_16x16x32_bf16 v[108:111], v[136:139], v[190:193], v[108:111]
	v_mfma_f32_16x16x32_bf16 v[116:119], v[128:131], v[190:193], v[116:119]
	v_mfma_f32_16x16x32_bf16 v[100:103], v[128:131], v[198:201], v[100:103]
	v_mfma_f32_16x16x32_bf16 v[92:95], v[136:139], v[198:201], v[92:95]
	v_mfma_f32_16x16x32_bf16 v[76:79], v[136:139], v[206:209], v[76:79]
	v_mfma_f32_16x16x32_bf16 v[84:87], v[128:131], v[206:209], v[84:87]
	v_mfma_f32_16x16x32_bf16 v[124:127], v[132:135], v[186:189], v[124:127]
	v_mfma_f32_16x16x32_bf16 v[120:123], v[140:143], v[186:189], v[120:123]
	v_mfma_f32_16x16x32_bf16 v[108:111], v[140:143], v[194:197], v[108:111]
	v_mfma_f32_16x16x32_bf16 v[116:119], v[132:135], v[194:197], v[116:119]
	v_mfma_f32_16x16x32_bf16 v[100:103], v[132:135], v[202:205], v[100:103]
	v_mfma_f32_16x16x32_bf16 v[92:95], v[140:143], v[202:205], v[92:95]
	v_mfma_f32_16x16x32_bf16 v[76:79], v[140:143], v[210:213], v[76:79]
	v_mfma_f32_16x16x32_bf16 v[84:87], v[132:135], v[210:213], v[84:87]
	s_setprio 0
	s_setprio 1
	v_mfma_f32_16x16x32_bf16 v[112:115], v[160:163], v[182:185], v[112:115]
	v_mfma_f32_16x16x32_bf16 v[104:107], v[174:177], v[182:185], v[104:107]
	v_mfma_f32_16x16x32_bf16 v[88:91], v[174:177], v[190:193], v[88:91]
	v_mfma_f32_16x16x32_bf16 v[96:99], v[160:163], v[190:193], v[96:99]
	v_mfma_f32_16x16x32_bf16 v[80:83], v[160:163], v[198:201], v[80:83]
	v_mfma_f32_16x16x32_bf16 v[72:75], v[174:177], v[198:201], v[72:75]
	v_mfma_f32_16x16x32_bf16 v[64:67], v[174:177], v[206:209], v[64:67]
	v_mfma_f32_16x16x32_bf16 v[68:71], v[160:163], v[206:209], v[68:71]
	v_mfma_f32_16x16x32_bf16 v[112:115], v[170:173], v[186:189], v[112:115]
	v_mfma_f32_16x16x32_bf16 v[104:107], v[178:181], v[186:189], v[104:107]
	v_mfma_f32_16x16x32_bf16 v[88:91], v[178:181], v[194:197], v[88:91]
	v_mfma_f32_16x16x32_bf16 v[96:99], v[170:173], v[194:197], v[96:99]
	v_mfma_f32_16x16x32_bf16 v[80:83], v[170:173], v[202:205], v[80:83]
	v_mfma_f32_16x16x32_bf16 v[72:75], v[178:181], v[202:205], v[72:75]
	v_mfma_f32_16x16x32_bf16 v[64:67], v[178:181], v[210:213], v[64:67]
	v_mfma_f32_16x16x32_bf16 v[68:71], v[170:173], v[210:213], v[68:71]
	s_setprio 0
	s_barrier
	s_add_i32 s18, s53, s33
	s_add_u32 s98, s22, s12
	s_addc_u32 s99, s23, s13
	s_add_u32 s100, s26, s12
	s_addc_u32 s101, s27, s13
	s_mov_b32 m0, s18
	ds_read_b128 v[182:185], v169 offset:49152
	ds_read_b128 v[186:189], v169 offset:50176
	ds_read_b128 v[190:193], v169 offset:51200
	ds_read_b128 v[194:197], v169 offset:52224
	ds_read_b128 v[198:201], v169 offset:53248
	ds_read_b128 v[202:205], v169 offset:54272
	ds_read_b128 v[206:209], v169 offset:55296
	ds_read_b128 v[210:213], v169 offset:56320
	global_load_lds_dwordx4 v148, s[98:99]
	s_add_i32 m0, s18, 0x2000
	s_add_u32 s18, s22, 0xb0080
	v_lshl_add_u64 v[214:215], v[216:217], 0, s[12:13]
	s_addc_u32 s19, s23, 0
	s_add_i32 s22, s54, s33
	global_load_lds_dwordx4 v[214:215], off
	s_mov_b32 m0, s22
	s_nop 0
	global_load_lds_dwordx4 v148, s[18:19]
	s_add_i32 m0, s22, 0x2000
	s_nop 0
	global_load_lds_dwordx4 v144, s[18:19]
	s_mov_b32 m0, s41
	s_nop 0
	global_load_lds_dwordx4 v150, s[100:101]
	s_mov_b32 m0, s42
	s_nop 0
	global_load_lds_dwordx4 v146, s[100:101]
	s_waitcnt vmcnt(8)
	s_waitcnt lgkmcnt(0)
	s_barrier
	s_setprio 1
	s_waitcnt lgkmcnt(0)
	v_mfma_f32_16x16x32_bf16 v[60:63], v[128:131], v[182:185], v[60:63]
	v_mfma_f32_16x16x32_bf16 v[56:59], v[136:139], v[182:185], v[56:59]
	v_mfma_f32_16x16x32_bf16 v[44:47], v[136:139], v[190:193], v[44:47]
	v_mfma_f32_16x16x32_bf16 v[48:51], v[128:131], v[190:193], v[48:51]
	v_mfma_f32_16x16x32_bf16 v[36:39], v[128:131], v[198:201], v[36:39]
	v_mfma_f32_16x16x32_bf16 v[28:31], v[136:139], v[198:201], v[28:31]
	v_mfma_f32_16x16x32_bf16 v[12:15], v[136:139], v[206:209], v[12:15]
	v_mfma_f32_16x16x32_bf16 v[20:23], v[128:131], v[206:209], v[20:23]
	v_mfma_f32_16x16x32_bf16 v[60:63], v[132:135], v[186:189], v[60:63]
	v_mfma_f32_16x16x32_bf16 v[56:59], v[140:143], v[186:189], v[56:59]
	v_mfma_f32_16x16x32_bf16 v[44:47], v[140:143], v[194:197], v[44:47]
	v_mfma_f32_16x16x32_bf16 v[48:51], v[132:135], v[194:197], v[48:51]
	v_mfma_f32_16x16x32_bf16 v[36:39], v[132:135], v[202:205], v[36:39]
	v_mfma_f32_16x16x32_bf16 v[28:31], v[140:143], v[202:205], v[28:31]
	v_mfma_f32_16x16x32_bf16 v[12:15], v[140:143], v[210:213], v[12:15]
	v_mfma_f32_16x16x32_bf16 v[20:23], v[132:135], v[210:213], v[20:23]
	s_setprio 0
	s_setprio 1
	v_mfma_f32_16x16x32_bf16 v[52:55], v[160:163], v[182:185], v[52:55]
	v_mfma_f32_16x16x32_bf16 v[40:43], v[174:177], v[182:185], v[40:43]
	v_mfma_f32_16x16x32_bf16 v[24:27], v[174:177], v[190:193], v[24:27]
	v_mfma_f32_16x16x32_bf16 v[32:35], v[160:163], v[190:193], v[32:35]
	v_mfma_f32_16x16x32_bf16 v[16:19], v[160:163], v[198:201], v[16:19]
	v_mfma_f32_16x16x32_bf16 v[8:11], v[174:177], v[198:201], v[8:11]
	v_mfma_f32_16x16x32_bf16 v[0:3], v[174:177], v[206:209], v[0:3]
	v_mfma_f32_16x16x32_bf16 v[4:7], v[160:163], v[206:209], v[4:7]
	v_mfma_f32_16x16x32_bf16 v[52:55], v[170:173], v[186:189], v[52:55]
	v_mfma_f32_16x16x32_bf16 v[40:43], v[178:181], v[186:189], v[40:43]
	v_mfma_f32_16x16x32_bf16 v[24:27], v[178:181], v[194:197], v[24:27]
	v_mfma_f32_16x16x32_bf16 v[32:35], v[170:173], v[194:197], v[32:35]
	v_mfma_f32_16x16x32_bf16 v[16:19], v[170:173], v[202:205], v[16:19]
	v_mfma_f32_16x16x32_bf16 v[8:11], v[178:181], v[202:205], v[8:11]
	v_mfma_f32_16x16x32_bf16 v[0:3], v[178:181], v[210:213], v[0:3]
	v_mfma_f32_16x16x32_bf16 v[4:7], v[170:173], v[210:213], v[4:7]
	s_setprio 0
	s_barrier
	s_add_i32 s52, s52, 2
	s_add_u32 s50, s50, 0x100
	s_addc_u32 s51, s51, 0
	s_cmp_gt_u32 s52, 41
	s_mov_b64 s[18:19], s[20:21]
	s_cbranch_scc0 .LBB0_1432
	s_and_b64 vcc, exec, s[14:15]
	s_cbranch_vccz .LBB0_1435
	s_barrier
